# hot loop heads (10 GEMM K-loops + attention tile loop) aligned to 64 bytes with s_nop padding
# baseline (speedup 1.0000x reference)
.LBB0_275:
	s_ashr_i32 s17, s16, 31
	s_lshl_b64 s[18:19], s[16:17], 19
	s_add_u32 s18, s25, s18
	s_addc_u32 s19, s29, s19
	s_and_b64 s[20:21], s[4:5], exec
	s_cselect_b32 s17, s19, s23
	s_cselect_b32 s50, s18, s22
	s_ashr_i32 s15, s14, 31
	s_lshl_b64 s[20:21], s[14:15], 19
	s_add_u32 s20, s36, s20
	s_addc_u32 s21, s37, s21
	s_and_b64 s[34:35], s[4:5], exec
	s_cselect_b32 s15, s21, s31
	s_cselect_b32 s51, s20, s30
	s_add_u32 s22, s22, 0x40080
	s_addc_u32 s23, s23, 0
	s_add_u32 s55, s30, 0x100
	s_addc_u32 s58, s31, 0
	s_mov_b32 s59, -2
	s_add_u32 s30, s22, 0xfffc0080
	s_addc_u32 s31, s23, -1
	s_add_i32 s56, 0, 0x10000
	s_cmp_eq_u32 s59, 12
	s_cselect_b32 s35, s17, s31
	s_cselect_b32 s34, s50, s30
	s_cselect_b32 s31, s15, s58
	s_cselect_b32 s30, s51, s55
	s_add_i32 s62, 0, 0x14000
	v_add_u32_e32 v122, s56, v204
	v_add_u32_e32 v170, s62, v204
	ds_read_b128 v[76:79], v122
	ds_read_b128 v[80:83], v122 offset:1024
	ds_read_b128 v[118:121], v122 offset:2048
	ds_read_b128 v[122:125], v122 offset:3072
	ds_read_b128 v[146:149], v170
	ds_read_b128 v[150:153], v170 offset:1024
	ds_read_b128 v[166:169], v170 offset:2048
	ds_read_b128 v[170:173], v170 offset:3072
	v_lshl_add_u64 v[194:195], s[22:23], 0, v[162:163]
	s_add_i32 m0, s40, 0xc000
	ds_read_b128 v[174:177], v206
	ds_read_b128 v[178:181], v206 offset:1024
	ds_read_b128 v[182:185], v206 offset:2048
	ds_read_b128 v[198:201], v206 offset:3072
	ds_read_b128 v[208:211], v206 offset:4096
	ds_read_b128 v[212:215], v206 offset:5120
	ds_read_b128 v[216:219], v206 offset:6144
	ds_read_b128 v[220:223], v206 offset:7168
	global_load_lds_dwordx4 v[194:195], off
	v_lshl_add_u64 v[194:195], s[22:23], 0, v[164:165]
	s_add_i32 m0, s40, 0xe000
	s_nop 0
	global_load_lds_dwordx4 v[194:195], off
	s_waitcnt vmcnt(8)
	s_waitcnt lgkmcnt(0)
	s_barrier
	s_setprio 1
	s_waitcnt lgkmcnt(0)
	v_mfma_f32_16x16x32_bf16 v[142:145], v[76:79], v[174:177], 0
	v_mfma_f32_16x16x32_bf16 v[134:137], v[118:121], v[174:177], 0
	v_mfma_f32_16x16x32_bf16 v[126:129], v[76:79], v[182:185], 0
	v_mfma_f32_16x16x32_bf16 v[108:111], v[118:121], v[182:185], 0
	v_mfma_f32_16x16x32_bf16 v[100:103], v[76:79], v[208:211], 0
	v_mfma_f32_16x16x32_bf16 v[92:95], v[118:121], v[208:211], 0
	v_mfma_f32_16x16x32_bf16 v[84:87], v[76:79], v[216:219], 0
	v_mfma_f32_16x16x32_bf16 v[68:71], v[118:121], v[216:219], 0
	v_mfma_f32_16x16x32_bf16 v[142:145], v[80:83], v[178:181], v[142:145]
	v_mfma_f32_16x16x32_bf16 v[134:137], v[122:125], v[178:181], v[134:137]
	v_mfma_f32_16x16x32_bf16 v[126:129], v[80:83], v[198:201], v[126:129]
	v_mfma_f32_16x16x32_bf16 v[108:111], v[122:125], v[198:201], v[108:111]
	v_mfma_f32_16x16x32_bf16 v[100:103], v[80:83], v[212:215], v[100:103]
	v_mfma_f32_16x16x32_bf16 v[92:95], v[122:125], v[212:215], v[92:95]
	v_mfma_f32_16x16x32_bf16 v[84:87], v[80:83], v[220:223], v[84:87]
	v_mfma_f32_16x16x32_bf16 v[68:71], v[122:125], v[220:223], v[68:71]
	s_setprio 0
	s_setprio 1
	v_mfma_f32_16x16x32_bf16 v[138:141], v[146:149], v[174:177], 0
	v_mfma_f32_16x16x32_bf16 v[130:133], v[166:169], v[174:177], 0
	v_mfma_f32_16x16x32_bf16 v[114:117], v[146:149], v[182:185], 0
	v_mfma_f32_16x16x32_bf16 v[104:107], v[166:169], v[182:185], 0
	v_mfma_f32_16x16x32_bf16 v[96:99], v[146:149], v[208:211], 0
	v_mfma_f32_16x16x32_bf16 v[88:91], v[166:169], v[208:211], 0
	v_mfma_f32_16x16x32_bf16 v[72:75], v[146:149], v[216:219], 0
	v_mfma_f32_16x16x32_bf16 v[64:67], v[166:169], v[216:219], 0
	v_mfma_f32_16x16x32_bf16 v[138:141], v[150:153], v[178:181], v[138:141]
	v_mfma_f32_16x16x32_bf16 v[130:133], v[170:173], v[178:181], v[130:133]
	v_mfma_f32_16x16x32_bf16 v[114:117], v[150:153], v[198:201], v[114:117]
	v_mfma_f32_16x16x32_bf16 v[104:107], v[170:173], v[198:201], v[104:107]
	v_mfma_f32_16x16x32_bf16 v[96:99], v[150:153], v[212:215], v[96:99]
	v_mfma_f32_16x16x32_bf16 v[88:91], v[170:173], v[212:215], v[88:91]
	v_mfma_f32_16x16x32_bf16 v[72:75], v[150:153], v[220:223], v[72:75]
	v_mfma_f32_16x16x32_bf16 v[64:67], v[170:173], v[220:223], v[64:67]
	s_setprio 0
	s_barrier
	s_add_i32 s56, s56, s39
	v_lshl_add_u64 v[194:195], s[30:31], 0, v[112:113]
	s_mov_b32 m0, s56
	ds_read_b128 v[174:177], v206 offset:16384
	ds_read_b128 v[178:181], v206 offset:17408
	ds_read_b128 v[182:185], v206 offset:18432
	ds_read_b128 v[198:201], v206 offset:19456
	ds_read_b128 v[208:211], v206 offset:20480
	ds_read_b128 v[212:215], v206 offset:21504
	ds_read_b128 v[216:219], v206 offset:22528
	ds_read_b128 v[220:223], v206 offset:23552
	global_load_lds_dwordx4 v[194:195], off
	s_add_i32 m0, s56, 0x2000
	s_add_u32 s56, s30, 0x40000
	v_lshl_add_u64 v[196:197], s[30:31], 0, v[154:155]
	s_addc_u32 s57, s31, 0
	s_add_i32 s62, s62, s39
	global_load_lds_dwordx4 v[196:197], off
	v_lshl_add_u64 v[234:235], s[56:57], 0, v[112:113]
	s_mov_b32 m0, s62
	v_lshl_add_u64 v[236:237], s[34:35], 0, v[156:157]
	global_load_lds_dwordx4 v[234:235], off
	v_lshl_add_u64 v[234:235], s[56:57], 0, v[154:155]
	s_add_i32 m0, s62, 0x2000
	s_nop 0
	global_load_lds_dwordx4 v[234:235], off
	v_lshl_add_u64 v[234:235], s[34:35], 0, v[158:159]
	s_mov_b32 m0, s40
	s_nop 0
	global_load_lds_dwordx4 v[234:235], off
	s_mov_b32 m0, s41
	s_nop 0
	global_load_lds_dwordx4 v[236:237], off
	s_waitcnt vmcnt(8)
	s_waitcnt lgkmcnt(0)
	s_barrier
	s_setprio 1
	s_waitcnt lgkmcnt(0)
	v_mfma_f32_16x16x32_bf16 v[60:63], v[76:79], v[174:177], 0
	v_mfma_f32_16x16x32_bf16 v[52:55], v[118:121], v[174:177], 0
	v_mfma_f32_16x16x32_bf16 v[44:47], v[76:79], v[182:185], 0
	v_mfma_f32_16x16x32_bf16 v[36:39], v[118:121], v[182:185], 0
	v_mfma_f32_16x16x32_bf16 v[28:31], v[76:79], v[208:211], 0
	v_mfma_f32_16x16x32_bf16 v[20:23], v[118:121], v[208:211], 0
	v_mfma_f32_16x16x32_bf16 v[12:15], v[76:79], v[216:219], 0
	v_mfma_f32_16x16x32_bf16 v[4:7], v[118:121], v[216:219], 0
	v_mfma_f32_16x16x32_bf16 v[60:63], v[80:83], v[178:181], v[60:63]
	v_mfma_f32_16x16x32_bf16 v[52:55], v[122:125], v[178:181], v[52:55]
	v_mfma_f32_16x16x32_bf16 v[44:47], v[80:83], v[198:201], v[44:47]
	v_mfma_f32_16x16x32_bf16 v[36:39], v[122:125], v[198:201], v[36:39]
	v_mfma_f32_16x16x32_bf16 v[28:31], v[80:83], v[212:215], v[28:31]
	v_mfma_f32_16x16x32_bf16 v[20:23], v[122:125], v[212:215], v[20:23]
	v_mfma_f32_16x16x32_bf16 v[12:15], v[80:83], v[220:223], v[12:15]
	v_mfma_f32_16x16x32_bf16 v[4:7], v[122:125], v[220:223], v[4:7]
	s_setprio 0
	s_setprio 1
	v_mfma_f32_16x16x32_bf16 v[56:59], v[146:149], v[174:177], 0
	v_mfma_f32_16x16x32_bf16 v[48:51], v[166:169], v[174:177], 0
	v_mfma_f32_16x16x32_bf16 v[40:43], v[146:149], v[182:185], 0
	v_mfma_f32_16x16x32_bf16 v[32:35], v[166:169], v[182:185], 0
	v_mfma_f32_16x16x32_bf16 v[24:27], v[146:149], v[208:211], 0
	v_mfma_f32_16x16x32_bf16 v[16:19], v[166:169], v[208:211], 0
	v_mfma_f32_16x16x32_bf16 v[8:11], v[146:149], v[216:219], 0
	v_mfma_f32_16x16x32_bf16 v[0:3], v[166:169], v[216:219], 0
	v_mfma_f32_16x16x32_bf16 v[56:59], v[150:153], v[178:181], v[56:59]
	v_mfma_f32_16x16x32_bf16 v[48:51], v[170:173], v[178:181], v[48:51]
	v_mfma_f32_16x16x32_bf16 v[40:43], v[150:153], v[198:201], v[40:43]
	v_mfma_f32_16x16x32_bf16 v[32:35], v[170:173], v[198:201], v[32:35]
	v_mfma_f32_16x16x32_bf16 v[24:27], v[150:153], v[212:215], v[24:27]
	v_mfma_f32_16x16x32_bf16 v[16:19], v[170:173], v[212:215], v[16:19]
	v_mfma_f32_16x16x32_bf16 v[8:11], v[150:153], v[220:223], v[8:11]
	v_mfma_f32_16x16x32_bf16 v[0:3], v[170:173], v[220:223], v[0:3]
	s_setprio 0
	s_barrier
	s_add_i32 s56, 0, 0x18000
	s_add_i32 s57, 0, 0x1c000
	v_add_u32_e32 v122, s56, v204
	v_add_u32_e32 v170, s57, v204
	ds_read_b128 v[76:79], v122
	ds_read_b128 v[80:83], v122 offset:1024
	ds_read_b128 v[118:121], v122 offset:2048
	ds_read_b128 v[122:125], v122 offset:3072
	ds_read_b128 v[146:149], v170
	ds_read_b128 v[150:153], v170 offset:1024
	ds_read_b128 v[166:169], v170 offset:2048
	ds_read_b128 v[170:173], v170 offset:3072
	s_add_u32 s34, s34, 0x40000
	s_addc_u32 s35, s35, 0
	s_mov_b32 m0, s42
	v_lshl_add_u64 v[238:239], s[34:35], 0, v[158:159]
	ds_read_b128 v[174:177], v206 offset:32768
	ds_read_b128 v[178:181], v206 offset:33792
	ds_read_b128 v[182:185], v206 offset:34816
	ds_read_b128 v[198:201], v206 offset:35840
	ds_read_b128 v[208:211], v206 offset:36864
	ds_read_b128 v[212:215], v206 offset:37888
	ds_read_b128 v[216:219], v206 offset:38912
	ds_read_b128 v[220:223], v206 offset:39936
	global_load_lds_dwordx4 v[238:239], off
	v_lshl_add_u64 v[238:239], s[34:35], 0, v[156:157]
	s_mov_b32 m0, s43
	s_nop 0
	global_load_lds_dwordx4 v[238:239], off
	s_waitcnt vmcnt(8)
	s_waitcnt lgkmcnt(0)
	s_barrier
	s_setprio 1
	s_waitcnt lgkmcnt(0)
	v_mfma_f32_16x16x32_bf16 v[142:145], v[76:79], v[174:177], v[142:145]
	v_mfma_f32_16x16x32_bf16 v[134:137], v[118:121], v[174:177], v[134:137]
	v_mfma_f32_16x16x32_bf16 v[126:129], v[76:79], v[182:185], v[126:129]
	v_mfma_f32_16x16x32_bf16 v[108:111], v[118:121], v[182:185], v[108:111]
	v_mfma_f32_16x16x32_bf16 v[100:103], v[76:79], v[208:211], v[100:103]
	v_mfma_f32_16x16x32_bf16 v[92:95], v[118:121], v[208:211], v[92:95]
	v_mfma_f32_16x16x32_bf16 v[84:87], v[76:79], v[216:219], v[84:87]
	v_mfma_f32_16x16x32_bf16 v[68:71], v[118:121], v[216:219], v[68:71]
	v_mfma_f32_16x16x32_bf16 v[142:145], v[80:83], v[178:181], v[142:145]
	v_mfma_f32_16x16x32_bf16 v[134:137], v[122:125], v[178:181], v[134:137]
	v_mfma_f32_16x16x32_bf16 v[126:129], v[80:83], v[198:201], v[126:129]
	v_mfma_f32_16x16x32_bf16 v[108:111], v[122:125], v[198:201], v[108:111]
	v_mfma_f32_16x16x32_bf16 v[100:103], v[80:83], v[212:215], v[100:103]
	v_mfma_f32_16x16x32_bf16 v[92:95], v[122:125], v[212:215], v[92:95]
	v_mfma_f32_16x16x32_bf16 v[84:87], v[80:83], v[220:223], v[84:87]
	v_mfma_f32_16x16x32_bf16 v[68:71], v[122:125], v[220:223], v[68:71]
	s_setprio 0
	s_setprio 1
	v_mfma_f32_16x16x32_bf16 v[138:141], v[146:149], v[174:177], v[138:141]
	v_mfma_f32_16x16x32_bf16 v[130:133], v[166:169], v[174:177], v[130:133]
	v_mfma_f32_16x16x32_bf16 v[114:117], v[146:149], v[182:185], v[114:117]
	v_mfma_f32_16x16x32_bf16 v[104:107], v[166:169], v[182:185], v[104:107]
	v_mfma_f32_16x16x32_bf16 v[96:99], v[146:149], v[208:211], v[96:99]
	v_mfma_f32_16x16x32_bf16 v[88:91], v[166:169], v[208:211], v[88:91]
	v_mfma_f32_16x16x32_bf16 v[72:75], v[146:149], v[216:219], v[72:75]
	v_mfma_f32_16x16x32_bf16 v[64:67], v[166:169], v[216:219], v[64:67]
	v_mfma_f32_16x16x32_bf16 v[138:141], v[150:153], v[178:181], v[138:141]
	v_mfma_f32_16x16x32_bf16 v[130:133], v[170:173], v[178:181], v[130:133]
	v_mfma_f32_16x16x32_bf16 v[114:117], v[150:153], v[198:201], v[114:117]
	v_mfma_f32_16x16x32_bf16 v[104:107], v[170:173], v[198:201], v[104:107]
	v_mfma_f32_16x16x32_bf16 v[96:99], v[150:153], v[212:215], v[96:99]
	v_mfma_f32_16x16x32_bf16 v[88:91], v[170:173], v[212:215], v[88:91]
	v_mfma_f32_16x16x32_bf16 v[72:75], v[150:153], v[220:223], v[72:75]
	v_mfma_f32_16x16x32_bf16 v[64:67], v[170:173], v[220:223], v[64:67]
	s_setprio 0
	s_barrier
	s_add_i32 s34, s56, s39
	v_lshl_add_u64 v[194:195], v[194:195], 0, s[60:61]
	s_mov_b32 m0, s34
	ds_read_b128 v[174:177], v206 offset:49152
	ds_read_b128 v[178:181], v206 offset:50176
	ds_read_b128 v[182:185], v206 offset:51200
	ds_read_b128 v[198:201], v206 offset:52224
	ds_read_b128 v[208:211], v206 offset:53248
	ds_read_b128 v[212:215], v206 offset:54272
	ds_read_b128 v[216:219], v206 offset:55296
	ds_read_b128 v[220:223], v206 offset:56320
	global_load_lds_dwordx4 v[194:195], off
	s_add_i32 m0, s34, 0x2000
	s_add_u32 s30, s30, 0x40080
	v_lshl_add_u64 v[194:195], v[196:197], 0, s[60:61]
	s_addc_u32 s31, s31, 0
	s_add_i32 s34, s57, s39
	global_load_lds_dwordx4 v[194:195], off
	v_lshl_add_u64 v[194:195], s[30:31], 0, v[112:113]
	s_mov_b32 m0, s34
	s_nop 0
	global_load_lds_dwordx4 v[194:195], off
	v_lshl_add_u64 v[194:195], s[30:31], 0, v[154:155]
	s_add_i32 m0, s34, 0x2000
	s_nop 0
	global_load_lds_dwordx4 v[194:195], off
	v_lshl_add_u64 v[194:195], v[234:235], 0, s[60:61]
	s_mov_b32 m0, s44
	s_nop 0
	global_load_lds_dwordx4 v[194:195], off
	v_lshl_add_u64 v[194:195], v[236:237], 0, s[60:61]
	s_mov_b32 m0, s45
	s_nop 0
	global_load_lds_dwordx4 v[194:195], off
	s_waitcnt vmcnt(8)
	s_waitcnt lgkmcnt(0)
	s_barrier
	s_setprio 1
	s_waitcnt lgkmcnt(0)
	v_mfma_f32_16x16x32_bf16 v[60:63], v[76:79], v[174:177], v[60:63]
	v_mfma_f32_16x16x32_bf16 v[52:55], v[118:121], v[174:177], v[52:55]
	v_mfma_f32_16x16x32_bf16 v[44:47], v[76:79], v[182:185], v[44:47]
	v_mfma_f32_16x16x32_bf16 v[36:39], v[118:121], v[182:185], v[36:39]
	v_mfma_f32_16x16x32_bf16 v[28:31], v[76:79], v[208:211], v[28:31]
	v_mfma_f32_16x16x32_bf16 v[20:23], v[118:121], v[208:211], v[20:23]
	v_mfma_f32_16x16x32_bf16 v[12:15], v[76:79], v[216:219], v[12:15]
	v_mfma_f32_16x16x32_bf16 v[4:7], v[118:121], v[216:219], v[4:7]
	v_mfma_f32_16x16x32_bf16 v[60:63], v[80:83], v[178:181], v[60:63]
	v_mfma_f32_16x16x32_bf16 v[52:55], v[122:125], v[178:181], v[52:55]
	v_mfma_f32_16x16x32_bf16 v[44:47], v[80:83], v[198:201], v[44:47]
	v_mfma_f32_16x16x32_bf16 v[36:39], v[122:125], v[198:201], v[36:39]
	v_mfma_f32_16x16x32_bf16 v[28:31], v[80:83], v[212:215], v[28:31]
	v_mfma_f32_16x16x32_bf16 v[20:23], v[122:125], v[212:215], v[20:23]
	v_mfma_f32_16x16x32_bf16 v[12:15], v[80:83], v[220:223], v[12:15]
	v_mfma_f32_16x16x32_bf16 v[4:7], v[122:125], v[220:223], v[4:7]
	s_setprio 0
	s_setprio 1
	v_mfma_f32_16x16x32_bf16 v[56:59], v[146:149], v[174:177], v[56:59]
	v_mfma_f32_16x16x32_bf16 v[48:51], v[166:169], v[174:177], v[48:51]
	v_mfma_f32_16x16x32_bf16 v[40:43], v[146:149], v[182:185], v[40:43]
	v_mfma_f32_16x16x32_bf16 v[32:35], v[166:169], v[182:185], v[32:35]
	v_mfma_f32_16x16x32_bf16 v[24:27], v[146:149], v[208:211], v[24:27]
	v_mfma_f32_16x16x32_bf16 v[16:19], v[166:169], v[208:211], v[16:19]
	v_mfma_f32_16x16x32_bf16 v[8:11], v[146:149], v[216:219], v[8:11]
	v_mfma_f32_16x16x32_bf16 v[0:3], v[166:169], v[216:219], v[0:3]
	v_mfma_f32_16x16x32_bf16 v[56:59], v[150:153], v[178:181], v[56:59]
	v_mfma_f32_16x16x32_bf16 v[48:51], v[170:173], v[178:181], v[48:51]
	v_mfma_f32_16x16x32_bf16 v[40:43], v[150:153], v[198:201], v[40:43]
	v_mfma_f32_16x16x32_bf16 v[32:35], v[170:173], v[198:201], v[32:35]
	v_mfma_f32_16x16x32_bf16 v[24:27], v[150:153], v[212:215], v[24:27]
	v_mfma_f32_16x16x32_bf16 v[16:19], v[170:173], v[212:215], v[16:19]
	v_mfma_f32_16x16x32_bf16 v[8:11], v[150:153], v[220:223], v[8:11]
	v_mfma_f32_16x16x32_bf16 v[0:3], v[170:173], v[220:223], v[0:3]
	s_setprio 0
	s_barrier
	s_add_i32 s59, s59, 2
	s_add_u32 s22, s22, 0x100
	s_addc_u32 s23, s23, 0
	s_add_u32 s55, s55, 0x100
	s_addc_u32 s58, s58, 0
	s_cmp_gt_u32 s59, 13
	s_cbranch_scc0 .LBB0_276
	s_branch .Lpeel_after_0
	.p2alignl 6, 3212836864

.LBB0_363:
	s_add_u32 s73, s40, 0x100
	s_addc_u32 s82, s41, 0
	s_mov_b32 s83, -2
	s_waitcnt lgkmcnt(0)
	s_add_u32 s40, s36, 0x100
	s_addc_u32 s41, s37, 0
	s_add_i32 s56, 0, 0x10000
	s_cmp_eq_u32 s83, 40
	s_cselect_b32 s45, s9, s41
	s_cselect_b32 s44, s8, s40
	s_cselect_b32 s43, s35, s82
	s_cselect_b32 s42, s34, s73
	s_add_i32 s57, 0, 0x14000
	v_add_u32_e32 v142, s56, v213
	v_add_u32_e32 v158, s57, v213
	ds_read_b128 v[130:133], v142
	ds_read_b128 v[134:137], v142 offset:1024
	ds_read_b128 v[138:141], v142 offset:2048
	ds_read_b128 v[142:145], v142 offset:3072
	ds_read_b128 v[146:149], v158
	ds_read_b128 v[150:153], v158 offset:1024
	ds_read_b128 v[154:157], v158 offset:2048
	ds_read_b128 v[158:161], v158 offset:3072
	v_lshl_add_u64 v[194:195], s[36:37], 0, v[184:185]
	s_add_i32 m0, s50, 0xc000
	ds_read_b128 v[162:165], v215
	ds_read_b128 v[166:169], v215 offset:1024
	ds_read_b128 v[170:173], v215 offset:2048
	ds_read_b128 v[174:177], v215 offset:3072
	ds_read_b128 v[200:203], v215 offset:4096
	ds_read_b128 v[204:207], v215 offset:5120
	ds_read_b128 v[208:211], v215 offset:6144
	ds_read_b128 v[216:219], v215 offset:7168
	global_load_lds_dwordx4 v[194:195], off
	v_lshl_add_u64 v[194:195], s[36:37], 0, v[198:199]
	s_add_i32 m0, s50, 0xe000
	s_nop 0
	global_load_lds_dwordx4 v[194:195], off
	s_waitcnt vmcnt(8)
	s_waitcnt lgkmcnt(0)
	s_barrier
	s_setprio 1
	s_waitcnt lgkmcnt(0)
	v_mfma_f32_16x16x32_bf16 v[126:129], v[130:133], v[162:165], 0
	v_mfma_f32_16x16x32_bf16 v[122:125], v[138:141], v[162:165], 0
	v_mfma_f32_16x16x32_bf16 v[108:111], v[130:133], v[170:173], 0
	v_mfma_f32_16x16x32_bf16 v[104:107], v[138:141], v[170:173], 0
	v_mfma_f32_16x16x32_bf16 v[92:95], v[130:133], v[200:203], 0
	v_mfma_f32_16x16x32_bf16 v[88:91], v[138:141], v[200:203], 0
	v_mfma_f32_16x16x32_bf16 v[76:79], v[130:133], v[208:211], 0
	v_mfma_f32_16x16x32_bf16 v[72:75], v[138:141], v[208:211], 0
	v_mfma_f32_16x16x32_bf16 v[126:129], v[134:137], v[166:169], v[126:129]
	v_mfma_f32_16x16x32_bf16 v[122:125], v[142:145], v[166:169], v[122:125]
	v_mfma_f32_16x16x32_bf16 v[108:111], v[134:137], v[174:177], v[108:111]
	v_mfma_f32_16x16x32_bf16 v[104:107], v[142:145], v[174:177], v[104:107]
	v_mfma_f32_16x16x32_bf16 v[92:95], v[134:137], v[204:207], v[92:95]
	v_mfma_f32_16x16x32_bf16 v[88:91], v[142:145], v[204:207], v[88:91]
	v_mfma_f32_16x16x32_bf16 v[76:79], v[134:137], v[216:219], v[76:79]
	v_mfma_f32_16x16x32_bf16 v[72:75], v[142:145], v[216:219], v[72:75]
	s_setprio 0
	s_setprio 1
	v_mfma_f32_16x16x32_bf16 v[118:121], v[146:149], v[162:165], 0
	v_mfma_f32_16x16x32_bf16 v[114:117], v[154:157], v[162:165], 0
	v_mfma_f32_16x16x32_bf16 v[100:103], v[146:149], v[170:173], 0
	v_mfma_f32_16x16x32_bf16 v[96:99], v[154:157], v[170:173], 0
	v_mfma_f32_16x16x32_bf16 v[84:87], v[146:149], v[200:203], 0
	v_mfma_f32_16x16x32_bf16 v[80:83], v[154:157], v[200:203], 0
	v_mfma_f32_16x16x32_bf16 v[68:71], v[146:149], v[208:211], 0
	v_mfma_f32_16x16x32_bf16 v[64:67], v[154:157], v[208:211], 0
	v_mfma_f32_16x16x32_bf16 v[118:121], v[150:153], v[166:169], v[118:121]
	v_mfma_f32_16x16x32_bf16 v[114:117], v[158:161], v[166:169], v[114:117]
	v_mfma_f32_16x16x32_bf16 v[100:103], v[150:153], v[174:177], v[100:103]
	v_mfma_f32_16x16x32_bf16 v[96:99], v[158:161], v[174:177], v[96:99]
	v_mfma_f32_16x16x32_bf16 v[84:87], v[150:153], v[204:207], v[84:87]
	v_mfma_f32_16x16x32_bf16 v[80:83], v[158:161], v[204:207], v[80:83]
	v_mfma_f32_16x16x32_bf16 v[68:71], v[150:153], v[216:219], v[68:71]
	v_mfma_f32_16x16x32_bf16 v[64:67], v[158:161], v[216:219], v[64:67]
	s_setprio 0
	s_barrier
	s_add_i32 s36, s56, s19
	v_lshl_add_u64 v[194:195], s[42:43], 0, v[112:113]
	s_mov_b32 m0, s36
	ds_read_b128 v[162:165], v215 offset:16384
	ds_read_b128 v[166:169], v215 offset:17408
	ds_read_b128 v[170:173], v215 offset:18432
	ds_read_b128 v[174:177], v215 offset:19456
	ds_read_b128 v[200:203], v215 offset:20480
	ds_read_b128 v[204:207], v215 offset:21504
	ds_read_b128 v[208:211], v215 offset:22528
	ds_read_b128 v[216:219], v215 offset:23552
	global_load_lds_dwordx4 v[194:195], off
	s_add_i32 m0, s36, 0x2000
	s_add_u32 s36, s42, 0xb0000
	v_lshl_add_u64 v[196:197], s[42:43], 0, v[182:183]
	s_addc_u32 s37, s43, 0
	s_add_i32 s56, s57, s19
	global_load_lds_dwordx4 v[196:197], off
	v_lshl_add_u64 v[220:221], s[36:37], 0, v[112:113]
	s_mov_b32 m0, s56
	v_lshl_add_u64 v[222:223], s[44:45], 0, v[180:181]
	global_load_lds_dwordx4 v[220:221], off
	v_lshl_add_u64 v[220:221], s[36:37], 0, v[182:183]
	s_add_i32 m0, s56, 0x2000
	s_nop 0
	global_load_lds_dwordx4 v[220:221], off
	v_lshl_add_u64 v[220:221], s[44:45], 0, v[178:179]
	s_mov_b32 m0, s50
	s_nop 0
	global_load_lds_dwordx4 v[220:221], off
	s_mov_b32 m0, s51
	s_nop 0
	global_load_lds_dwordx4 v[222:223], off
	s_waitcnt vmcnt(8)
	s_waitcnt lgkmcnt(0)
	s_barrier
	s_setprio 1
	s_waitcnt lgkmcnt(0)
	v_mfma_f32_16x16x32_bf16 v[60:63], v[130:133], v[162:165], 0
	v_mfma_f32_16x16x32_bf16 v[56:59], v[138:141], v[162:165], 0
	v_mfma_f32_16x16x32_bf16 v[44:47], v[130:133], v[170:173], 0
	v_mfma_f32_16x16x32_bf16 v[40:43], v[138:141], v[170:173], 0
	v_mfma_f32_16x16x32_bf16 v[28:31], v[130:133], v[200:203], 0
	v_mfma_f32_16x16x32_bf16 v[24:27], v[138:141], v[200:203], 0
	v_mfma_f32_16x16x32_bf16 v[12:15], v[130:133], v[208:211], 0
	v_mfma_f32_16x16x32_bf16 v[8:11], v[138:141], v[208:211], 0
	v_mfma_f32_16x16x32_bf16 v[60:63], v[134:137], v[166:169], v[60:63]
	v_mfma_f32_16x16x32_bf16 v[56:59], v[142:145], v[166:169], v[56:59]
	v_mfma_f32_16x16x32_bf16 v[44:47], v[134:137], v[174:177], v[44:47]
	v_mfma_f32_16x16x32_bf16 v[40:43], v[142:145], v[174:177], v[40:43]
	v_mfma_f32_16x16x32_bf16 v[28:31], v[134:137], v[204:207], v[28:31]
	v_mfma_f32_16x16x32_bf16 v[24:27], v[142:145], v[204:207], v[24:27]
	v_mfma_f32_16x16x32_bf16 v[12:15], v[134:137], v[216:219], v[12:15]
	v_mfma_f32_16x16x32_bf16 v[8:11], v[142:145], v[216:219], v[8:11]
	s_setprio 0
	s_setprio 1
	v_mfma_f32_16x16x32_bf16 v[52:55], v[146:149], v[162:165], 0
	v_mfma_f32_16x16x32_bf16 v[48:51], v[154:157], v[162:165], 0
	v_mfma_f32_16x16x32_bf16 v[36:39], v[146:149], v[170:173], 0
	v_mfma_f32_16x16x32_bf16 v[32:35], v[154:157], v[170:173], 0
	v_mfma_f32_16x16x32_bf16 v[20:23], v[146:149], v[200:203], 0
	v_mfma_f32_16x16x32_bf16 v[16:19], v[154:157], v[200:203], 0
	v_mfma_f32_16x16x32_bf16 v[4:7], v[146:149], v[208:211], 0
	v_mfma_f32_16x16x32_bf16 v[0:3], v[154:157], v[208:211], 0
	v_mfma_f32_16x16x32_bf16 v[52:55], v[150:153], v[166:169], v[52:55]
	v_mfma_f32_16x16x32_bf16 v[48:51], v[158:161], v[166:169], v[48:51]
	v_mfma_f32_16x16x32_bf16 v[36:39], v[150:153], v[174:177], v[36:39]
	v_mfma_f32_16x16x32_bf16 v[32:35], v[158:161], v[174:177], v[32:35]
	v_mfma_f32_16x16x32_bf16 v[20:23], v[150:153], v[204:207], v[20:23]
	v_mfma_f32_16x16x32_bf16 v[16:19], v[158:161], v[204:207], v[16:19]
	v_mfma_f32_16x16x32_bf16 v[4:7], v[150:153], v[216:219], v[4:7]
	v_mfma_f32_16x16x32_bf16 v[0:3], v[158:161], v[216:219], v[0:3]
	s_setprio 0
	s_barrier
	s_add_i32 s56, 0, 0x18000
	s_add_i32 s57, 0, 0x1c000
	v_add_u32_e32 v142, s56, v213
	v_add_u32_e32 v158, s57, v213
	ds_read_b128 v[130:133], v142
	ds_read_b128 v[134:137], v142 offset:1024
	ds_read_b128 v[138:141], v142 offset:2048
	ds_read_b128 v[142:145], v142 offset:3072
	ds_read_b128 v[146:149], v158
	ds_read_b128 v[150:153], v158 offset:1024
	ds_read_b128 v[154:157], v158 offset:2048
	ds_read_b128 v[158:161], v158 offset:3072
	s_add_u32 s36, s44, 0xb0000
	s_addc_u32 s37, s45, 0
	s_mov_b32 m0, s55
	v_lshl_add_u64 v[234:235], s[36:37], 0, v[178:179]
	ds_read_b128 v[162:165], v215 offset:32768
	ds_read_b128 v[166:169], v215 offset:33792
	ds_read_b128 v[170:173], v215 offset:34816
	ds_read_b128 v[174:177], v215 offset:35840
	ds_read_b128 v[200:203], v215 offset:36864
	ds_read_b128 v[204:207], v215 offset:37888
	ds_read_b128 v[208:211], v215 offset:38912
	ds_read_b128 v[216:219], v215 offset:39936
	global_load_lds_dwordx4 v[234:235], off
	v_lshl_add_u64 v[234:235], s[36:37], 0, v[180:181]
	s_mov_b32 m0, s58
	s_nop 0
	global_load_lds_dwordx4 v[234:235], off
	s_waitcnt vmcnt(8)
	s_waitcnt lgkmcnt(0)
	s_barrier
	s_setprio 1
	s_waitcnt lgkmcnt(0)
	v_mfma_f32_16x16x32_bf16 v[126:129], v[130:133], v[162:165], v[126:129]
	v_mfma_f32_16x16x32_bf16 v[122:125], v[138:141], v[162:165], v[122:125]
	v_mfma_f32_16x16x32_bf16 v[108:111], v[130:133], v[170:173], v[108:111]
	v_mfma_f32_16x16x32_bf16 v[104:107], v[138:141], v[170:173], v[104:107]
	v_mfma_f32_16x16x32_bf16 v[92:95], v[130:133], v[200:203], v[92:95]
	v_mfma_f32_16x16x32_bf16 v[88:91], v[138:141], v[200:203], v[88:91]
	v_mfma_f32_16x16x32_bf16 v[76:79], v[130:133], v[208:211], v[76:79]
	v_mfma_f32_16x16x32_bf16 v[72:75], v[138:141], v[208:211], v[72:75]
	v_mfma_f32_16x16x32_bf16 v[126:129], v[134:137], v[166:169], v[126:129]
	v_mfma_f32_16x16x32_bf16 v[122:125], v[142:145], v[166:169], v[122:125]
	v_mfma_f32_16x16x32_bf16 v[108:111], v[134:137], v[174:177], v[108:111]
	v_mfma_f32_16x16x32_bf16 v[104:107], v[142:145], v[174:177], v[104:107]
	v_mfma_f32_16x16x32_bf16 v[92:95], v[134:137], v[204:207], v[92:95]
	v_mfma_f32_16x16x32_bf16 v[88:91], v[142:145], v[204:207], v[88:91]
	v_mfma_f32_16x16x32_bf16 v[76:79], v[134:137], v[216:219], v[76:79]
	v_mfma_f32_16x16x32_bf16 v[72:75], v[142:145], v[216:219], v[72:75]
	s_setprio 0
	s_setprio 1
	v_mfma_f32_16x16x32_bf16 v[118:121], v[146:149], v[162:165], v[118:121]
	v_mfma_f32_16x16x32_bf16 v[114:117], v[154:157], v[162:165], v[114:117]
	v_mfma_f32_16x16x32_bf16 v[100:103], v[146:149], v[170:173], v[100:103]
	v_mfma_f32_16x16x32_bf16 v[96:99], v[154:157], v[170:173], v[96:99]
	v_mfma_f32_16x16x32_bf16 v[84:87], v[146:149], v[200:203], v[84:87]
	v_mfma_f32_16x16x32_bf16 v[80:83], v[154:157], v[200:203], v[80:83]
	v_mfma_f32_16x16x32_bf16 v[68:71], v[146:149], v[208:211], v[68:71]
	v_mfma_f32_16x16x32_bf16 v[64:67], v[154:157], v[208:211], v[64:67]
	v_mfma_f32_16x16x32_bf16 v[118:121], v[150:153], v[166:169], v[118:121]
	v_mfma_f32_16x16x32_bf16 v[114:117], v[158:161], v[166:169], v[114:117]
	v_mfma_f32_16x16x32_bf16 v[100:103], v[150:153], v[174:177], v[100:103]
	v_mfma_f32_16x16x32_bf16 v[96:99], v[158:161], v[174:177], v[96:99]
	v_mfma_f32_16x16x32_bf16 v[84:87], v[150:153], v[204:207], v[84:87]
	v_mfma_f32_16x16x32_bf16 v[80:83], v[158:161], v[204:207], v[80:83]
	v_mfma_f32_16x16x32_bf16 v[68:71], v[150:153], v[216:219], v[68:71]
	v_mfma_f32_16x16x32_bf16 v[64:67], v[158:161], v[216:219], v[64:67]
	s_setprio 0
	s_barrier
	s_add_i32 s36, s56, s19
	v_lshl_add_u64 v[194:195], v[194:195], 0, s[60:61]
	s_mov_b32 m0, s36
	ds_read_b128 v[162:165], v215 offset:49152
	ds_read_b128 v[166:169], v215 offset:50176
	ds_read_b128 v[170:173], v215 offset:51200
	ds_read_b128 v[174:177], v215 offset:52224
	ds_read_b128 v[200:203], v215 offset:53248
	ds_read_b128 v[204:207], v215 offset:54272
	ds_read_b128 v[208:211], v215 offset:55296
	ds_read_b128 v[216:219], v215 offset:56320
	global_load_lds_dwordx4 v[194:195], off
	s_add_i32 m0, s36, 0x2000
	s_add_u32 s36, s42, 0xb0080
	v_lshl_add_u64 v[194:195], v[196:197], 0, s[60:61]
	s_addc_u32 s37, s43, 0
	s_add_i32 s42, s57, s19
	global_load_lds_dwordx4 v[194:195], off
	v_lshl_add_u64 v[194:195], s[36:37], 0, v[112:113]
	s_mov_b32 m0, s42
	s_nop 0
	global_load_lds_dwordx4 v[194:195], off
	v_lshl_add_u64 v[194:195], s[36:37], 0, v[182:183]
	s_add_i32 m0, s42, 0x2000
	s_nop 0
	global_load_lds_dwordx4 v[194:195], off
	v_lshl_add_u64 v[194:195], v[220:221], 0, s[60:61]
	s_mov_b32 m0, s62
	s_nop 0
	global_load_lds_dwordx4 v[194:195], off
	v_lshl_add_u64 v[194:195], v[222:223], 0, s[60:61]
	s_mov_b32 m0, s63
	s_nop 0
	global_load_lds_dwordx4 v[194:195], off
	s_waitcnt vmcnt(8)
	s_waitcnt lgkmcnt(0)
	s_barrier
	s_setprio 1
	s_waitcnt lgkmcnt(0)
	v_mfma_f32_16x16x32_bf16 v[60:63], v[130:133], v[162:165], v[60:63]
	v_mfma_f32_16x16x32_bf16 v[56:59], v[138:141], v[162:165], v[56:59]
	v_mfma_f32_16x16x32_bf16 v[44:47], v[130:133], v[170:173], v[44:47]
	v_mfma_f32_16x16x32_bf16 v[40:43], v[138:141], v[170:173], v[40:43]
	v_mfma_f32_16x16x32_bf16 v[28:31], v[130:133], v[200:203], v[28:31]
	v_mfma_f32_16x16x32_bf16 v[24:27], v[138:141], v[200:203], v[24:27]
	v_mfma_f32_16x16x32_bf16 v[12:15], v[130:133], v[208:211], v[12:15]
	v_mfma_f32_16x16x32_bf16 v[8:11], v[138:141], v[208:211], v[8:11]
	v_mfma_f32_16x16x32_bf16 v[60:63], v[134:137], v[166:169], v[60:63]
	v_mfma_f32_16x16x32_bf16 v[56:59], v[142:145], v[166:169], v[56:59]
	v_mfma_f32_16x16x32_bf16 v[44:47], v[134:137], v[174:177], v[44:47]
	v_mfma_f32_16x16x32_bf16 v[40:43], v[142:145], v[174:177], v[40:43]
	v_mfma_f32_16x16x32_bf16 v[28:31], v[134:137], v[204:207], v[28:31]
	v_mfma_f32_16x16x32_bf16 v[24:27], v[142:145], v[204:207], v[24:27]
	v_mfma_f32_16x16x32_bf16 v[12:15], v[134:137], v[216:219], v[12:15]
	v_mfma_f32_16x16x32_bf16 v[8:11], v[142:145], v[216:219], v[8:11]
	s_setprio 0
	s_setprio 1
	v_mfma_f32_16x16x32_bf16 v[52:55], v[146:149], v[162:165], v[52:55]
	v_mfma_f32_16x16x32_bf16 v[48:51], v[154:157], v[162:165], v[48:51]
	v_mfma_f32_16x16x32_bf16 v[36:39], v[146:149], v[170:173], v[36:39]
	v_mfma_f32_16x16x32_bf16 v[32:35], v[154:157], v[170:173], v[32:35]
	v_mfma_f32_16x16x32_bf16 v[20:23], v[146:149], v[200:203], v[20:23]
	v_mfma_f32_16x16x32_bf16 v[16:19], v[154:157], v[200:203], v[16:19]
	v_mfma_f32_16x16x32_bf16 v[4:7], v[146:149], v[208:211], v[4:7]
	v_mfma_f32_16x16x32_bf16 v[0:3], v[154:157], v[208:211], v[0:3]
	v_mfma_f32_16x16x32_bf16 v[52:55], v[150:153], v[166:169], v[52:55]
	v_mfma_f32_16x16x32_bf16 v[48:51], v[158:161], v[166:169], v[48:51]
	v_mfma_f32_16x16x32_bf16 v[36:39], v[150:153], v[174:177], v[36:39]
	v_mfma_f32_16x16x32_bf16 v[32:35], v[158:161], v[174:177], v[32:35]
	v_mfma_f32_16x16x32_bf16 v[20:23], v[150:153], v[204:207], v[20:23]
	v_mfma_f32_16x16x32_bf16 v[16:19], v[158:161], v[204:207], v[16:19]
	v_mfma_f32_16x16x32_bf16 v[4:7], v[150:153], v[216:219], v[4:7]
	v_mfma_f32_16x16x32_bf16 v[0:3], v[158:161], v[216:219], v[0:3]
	s_setprio 0
	s_barrier
	s_add_i32 s83, s83, 2
	s_add_u32 s73, s73, 0x100
	s_addc_u32 s82, s82, 0
	s_cmp_gt_u32 s83, 41
	s_mov_b64 s[36:37], s[40:41]
	s_cbranch_scc0 .LBB0_364
	s_branch .Lpeel_after_1
	.p2alignl 6, 3212836864

.LBB0_453:
	s_ashr_i32 s97, s96, 31
	s_lshl_b64 s[10:11], s[96:97], 19
	s_add_u32 s30, s70, s10
	s_addc_u32 s31, s71, s11
	s_and_b64 s[10:11], s[6:7], exec
	s_cselect_b32 s9, s31, s51
	s_cselect_b32 s13, s30, s50
	s_ashr_i32 s95, s94, 31
	s_lshl_b64 s[10:11], s[94:95], 19
	s_add_u32 s40, s38, s10
	s_addc_u32 s41, s39, s11
	s_and_b64 s[10:11], s[6:7], exec
	s_cselect_b32 s24, s41, s45
	s_cselect_b32 s25, s40, s44
	s_add_u32 s10, s50, 0x40080
	s_addc_u32 s11, s51, 0
	s_add_u32 s90, s44, 0x100
	s_addc_u32 s95, s45, 0
	s_mov_b32 s97, -2
	s_waitcnt lgkmcnt(0)
	s_add_u32 s44, s10, 0xfffc0080
	s_addc_u32 s45, s11, -1
	s_add_i32 s56, 0, 0x10000
	s_cmp_eq_u32 s97, 12
	s_cselect_b32 s51, s9, s45
	s_cselect_b32 s50, s13, s44
	s_cselect_b32 s45, s24, s95
	s_cselect_b32 s44, s25, s90
	s_add_i32 s64, 0, 0x14000
	v_add_u32_e32 v118, s56, v205
	v_add_u32_e32 v158, s64, v205
	ds_read_b128 v[64:67], v118
	ds_read_b128 v[76:79], v118 offset:1024
	ds_read_b128 v[96:99], v118 offset:2048
	ds_read_b128 v[118:121], v118 offset:3072
	ds_read_b128 v[138:141], v158
	ds_read_b128 v[142:145], v158 offset:1024
	ds_read_b128 v[154:157], v158 offset:2048
	ds_read_b128 v[158:161], v158 offset:3072
	v_lshl_add_u64 v[194:195], s[10:11], 0, v[170:171]
	s_add_i32 m0, s83, 0xc000
	ds_read_b128 v[174:177], v207
	ds_read_b128 v[178:181], v207 offset:1024
	ds_read_b128 v[182:185], v207 offset:2048
	ds_read_b128 v[198:201], v207 offset:3072
	ds_read_b128 v[208:211], v207 offset:4096
	ds_read_b128 v[212:215], v207 offset:5120
	ds_read_b128 v[216:219], v207 offset:6144
	ds_read_b128 v[220:223], v207 offset:7168
	global_load_lds_dwordx4 v[194:195], off
	v_lshl_add_u64 v[194:195], s[10:11], 0, v[172:173]
	s_add_i32 m0, s83, 0xe000
	s_nop 0
	global_load_lds_dwordx4 v[194:195], off
	s_waitcnt vmcnt(8)
	s_waitcnt lgkmcnt(0)
	s_barrier
	s_setprio 1
	s_waitcnt lgkmcnt(0)
	v_mfma_f32_16x16x32_bf16 v[150:153], v[64:67], v[174:177], 0
	v_mfma_f32_16x16x32_bf16 v[146:149], v[96:99], v[174:177], 0
	v_mfma_f32_16x16x32_bf16 v[126:129], v[64:67], v[182:185], 0
	v_mfma_f32_16x16x32_bf16 v[122:125], v[96:99], v[182:185], 0
	v_mfma_f32_16x16x32_bf16 v[104:107], v[64:67], v[208:211], 0
	v_mfma_f32_16x16x32_bf16 v[100:103], v[96:99], v[208:211], 0
	v_mfma_f32_16x16x32_bf16 v[84:87], v[64:67], v[216:219], 0
	v_mfma_f32_16x16x32_bf16 v[80:83], v[96:99], v[216:219], 0
	v_mfma_f32_16x16x32_bf16 v[150:153], v[76:79], v[178:181], v[150:153]
	v_mfma_f32_16x16x32_bf16 v[146:149], v[118:121], v[178:181], v[146:149]
	v_mfma_f32_16x16x32_bf16 v[126:129], v[76:79], v[198:201], v[126:129]
	v_mfma_f32_16x16x32_bf16 v[122:125], v[118:121], v[198:201], v[122:125]
	v_mfma_f32_16x16x32_bf16 v[104:107], v[76:79], v[212:215], v[104:107]
	v_mfma_f32_16x16x32_bf16 v[100:103], v[118:121], v[212:215], v[100:103]
	v_mfma_f32_16x16x32_bf16 v[84:87], v[76:79], v[220:223], v[84:87]
	v_mfma_f32_16x16x32_bf16 v[80:83], v[118:121], v[220:223], v[80:83]
	s_setprio 0
	s_setprio 1
	v_mfma_f32_16x16x32_bf16 v[134:137], v[138:141], v[174:177], 0
	v_mfma_f32_16x16x32_bf16 v[130:133], v[154:157], v[174:177], 0
	v_mfma_f32_16x16x32_bf16 v[114:117], v[138:141], v[182:185], 0
	v_mfma_f32_16x16x32_bf16 v[108:111], v[154:157], v[182:185], 0
	v_mfma_f32_16x16x32_bf16 v[92:95], v[138:141], v[208:211], 0
	v_mfma_f32_16x16x32_bf16 v[88:91], v[154:157], v[208:211], 0
	v_mfma_f32_16x16x32_bf16 v[72:75], v[138:141], v[216:219], 0
	v_mfma_f32_16x16x32_bf16 v[68:71], v[154:157], v[216:219], 0
	v_mfma_f32_16x16x32_bf16 v[134:137], v[142:145], v[178:181], v[134:137]
	v_mfma_f32_16x16x32_bf16 v[130:133], v[158:161], v[178:181], v[130:133]
	v_mfma_f32_16x16x32_bf16 v[114:117], v[142:145], v[198:201], v[114:117]
	v_mfma_f32_16x16x32_bf16 v[108:111], v[158:161], v[198:201], v[108:111]
	v_mfma_f32_16x16x32_bf16 v[92:95], v[142:145], v[212:215], v[92:95]
	v_mfma_f32_16x16x32_bf16 v[88:91], v[158:161], v[212:215], v[88:91]
	v_mfma_f32_16x16x32_bf16 v[72:75], v[142:145], v[220:223], v[72:75]
	v_mfma_f32_16x16x32_bf16 v[68:71], v[158:161], v[220:223], v[68:71]
	s_setprio 0
	s_barrier
	s_add_i32 s56, s56, s82
	v_lshl_add_u64 v[194:195], s[44:45], 0, v[112:113]
	s_mov_b32 m0, s56
	ds_read_b128 v[174:177], v207 offset:16384
	ds_read_b128 v[178:181], v207 offset:17408
	ds_read_b128 v[182:185], v207 offset:18432
	ds_read_b128 v[198:201], v207 offset:19456
	ds_read_b128 v[208:211], v207 offset:20480
	ds_read_b128 v[212:215], v207 offset:21504
	ds_read_b128 v[216:219], v207 offset:22528
	ds_read_b128 v[220:223], v207 offset:23552
	global_load_lds_dwordx4 v[194:195], off
	s_add_i32 m0, s56, 0x2000
	s_add_u32 s56, s44, 0x40000
	v_lshl_add_u64 v[196:197], s[44:45], 0, v[166:167]
	s_addc_u32 s57, s45, 0
	s_add_i32 s64, s64, s82
	global_load_lds_dwordx4 v[196:197], off
	v_lshl_add_u64 v[202:203], s[56:57], 0, v[112:113]
	s_mov_b32 m0, s64
	v_lshl_add_u64 v[234:235], s[50:51], 0, v[164:165]
	global_load_lds_dwordx4 v[202:203], off
	v_lshl_add_u64 v[202:203], s[56:57], 0, v[166:167]
	s_add_i32 m0, s64, 0x2000
	s_nop 0
	global_load_lds_dwordx4 v[202:203], off
	v_lshl_add_u64 v[202:203], s[50:51], 0, v[162:163]
	s_mov_b32 m0, s83
	s_nop 0
	global_load_lds_dwordx4 v[202:203], off
	s_mov_b32 m0, s85
	s_nop 0
	global_load_lds_dwordx4 v[234:235], off
	s_waitcnt vmcnt(8)
	s_waitcnt lgkmcnt(0)
	s_barrier
	s_setprio 1
	s_waitcnt lgkmcnt(0)
	v_mfma_f32_16x16x32_bf16 v[60:63], v[64:67], v[174:177], 0
	v_mfma_f32_16x16x32_bf16 v[56:59], v[96:99], v[174:177], 0
	v_mfma_f32_16x16x32_bf16 v[44:47], v[64:67], v[182:185], 0
	v_mfma_f32_16x16x32_bf16 v[40:43], v[96:99], v[182:185], 0
	v_mfma_f32_16x16x32_bf16 v[28:31], v[64:67], v[208:211], 0
	v_mfma_f32_16x16x32_bf16 v[24:27], v[96:99], v[208:211], 0
	v_mfma_f32_16x16x32_bf16 v[12:15], v[64:67], v[216:219], 0
	v_mfma_f32_16x16x32_bf16 v[8:11], v[96:99], v[216:219], 0
	v_mfma_f32_16x16x32_bf16 v[60:63], v[76:79], v[178:181], v[60:63]
	v_mfma_f32_16x16x32_bf16 v[56:59], v[118:121], v[178:181], v[56:59]
	v_mfma_f32_16x16x32_bf16 v[44:47], v[76:79], v[198:201], v[44:47]
	v_mfma_f32_16x16x32_bf16 v[40:43], v[118:121], v[198:201], v[40:43]
	v_mfma_f32_16x16x32_bf16 v[28:31], v[76:79], v[212:215], v[28:31]
	v_mfma_f32_16x16x32_bf16 v[24:27], v[118:121], v[212:215], v[24:27]
	v_mfma_f32_16x16x32_bf16 v[12:15], v[76:79], v[220:223], v[12:15]
	v_mfma_f32_16x16x32_bf16 v[8:11], v[118:121], v[220:223], v[8:11]
	s_setprio 0
	s_setprio 1
	v_mfma_f32_16x16x32_bf16 v[52:55], v[138:141], v[174:177], 0
	v_mfma_f32_16x16x32_bf16 v[48:51], v[154:157], v[174:177], 0
	v_mfma_f32_16x16x32_bf16 v[36:39], v[138:141], v[182:185], 0
	v_mfma_f32_16x16x32_bf16 v[32:35], v[154:157], v[182:185], 0
	v_mfma_f32_16x16x32_bf16 v[20:23], v[138:141], v[208:211], 0
	v_mfma_f32_16x16x32_bf16 v[16:19], v[154:157], v[208:211], 0
	v_mfma_f32_16x16x32_bf16 v[4:7], v[138:141], v[216:219], 0
	v_mfma_f32_16x16x32_bf16 v[0:3], v[154:157], v[216:219], 0
	v_mfma_f32_16x16x32_bf16 v[52:55], v[142:145], v[178:181], v[52:55]
	v_mfma_f32_16x16x32_bf16 v[48:51], v[158:161], v[178:181], v[48:51]
	v_mfma_f32_16x16x32_bf16 v[36:39], v[142:145], v[198:201], v[36:39]
	v_mfma_f32_16x16x32_bf16 v[32:35], v[158:161], v[198:201], v[32:35]
	v_mfma_f32_16x16x32_bf16 v[20:23], v[142:145], v[212:215], v[20:23]
	v_mfma_f32_16x16x32_bf16 v[16:19], v[158:161], v[212:215], v[16:19]
	v_mfma_f32_16x16x32_bf16 v[4:7], v[142:145], v[220:223], v[4:7]
	v_mfma_f32_16x16x32_bf16 v[0:3], v[158:161], v[220:223], v[0:3]
	s_setprio 0
	s_barrier
	s_add_i32 s56, 0, 0x18000
	s_add_i32 s57, 0, 0x1c000
	v_add_u32_e32 v118, s56, v205
	v_add_u32_e32 v158, s57, v205
	ds_read_b128 v[64:67], v118
	ds_read_b128 v[76:79], v118 offset:1024
	ds_read_b128 v[96:99], v118 offset:2048
	ds_read_b128 v[118:121], v118 offset:3072
	ds_read_b128 v[138:141], v158
	ds_read_b128 v[142:145], v158 offset:1024
	ds_read_b128 v[154:157], v158 offset:2048
	ds_read_b128 v[158:161], v158 offset:3072
	s_add_u32 s50, s50, 0x40000
	s_addc_u32 s51, s51, 0
	s_mov_b32 m0, s84
	v_lshl_add_u64 v[236:237], s[50:51], 0, v[162:163]
	ds_read_b128 v[174:177], v207 offset:32768
	ds_read_b128 v[178:181], v207 offset:33792
	ds_read_b128 v[182:185], v207 offset:34816
	ds_read_b128 v[198:201], v207 offset:35840
	ds_read_b128 v[208:211], v207 offset:36864
	ds_read_b128 v[212:215], v207 offset:37888
	ds_read_b128 v[216:219], v207 offset:38912
	ds_read_b128 v[220:223], v207 offset:39936
	global_load_lds_dwordx4 v[236:237], off
	v_lshl_add_u64 v[236:237], s[50:51], 0, v[164:165]
	s_mov_b32 m0, s18
	s_nop 0
	global_load_lds_dwordx4 v[236:237], off
	s_waitcnt vmcnt(8)
	s_waitcnt lgkmcnt(0)
	s_barrier
	s_setprio 1
	s_waitcnt lgkmcnt(0)
	v_mfma_f32_16x16x32_bf16 v[150:153], v[64:67], v[174:177], v[150:153]
	v_mfma_f32_16x16x32_bf16 v[146:149], v[96:99], v[174:177], v[146:149]
	v_mfma_f32_16x16x32_bf16 v[126:129], v[64:67], v[182:185], v[126:129]
	v_mfma_f32_16x16x32_bf16 v[122:125], v[96:99], v[182:185], v[122:125]
	v_mfma_f32_16x16x32_bf16 v[104:107], v[64:67], v[208:211], v[104:107]
	v_mfma_f32_16x16x32_bf16 v[100:103], v[96:99], v[208:211], v[100:103]
	v_mfma_f32_16x16x32_bf16 v[84:87], v[64:67], v[216:219], v[84:87]
	v_mfma_f32_16x16x32_bf16 v[80:83], v[96:99], v[216:219], v[80:83]
	v_mfma_f32_16x16x32_bf16 v[150:153], v[76:79], v[178:181], v[150:153]
	v_mfma_f32_16x16x32_bf16 v[146:149], v[118:121], v[178:181], v[146:149]
	v_mfma_f32_16x16x32_bf16 v[126:129], v[76:79], v[198:201], v[126:129]
	v_mfma_f32_16x16x32_bf16 v[122:125], v[118:121], v[198:201], v[122:125]
	v_mfma_f32_16x16x32_bf16 v[104:107], v[76:79], v[212:215], v[104:107]
	v_mfma_f32_16x16x32_bf16 v[100:103], v[118:121], v[212:215], v[100:103]
	v_mfma_f32_16x16x32_bf16 v[84:87], v[76:79], v[220:223], v[84:87]
	v_mfma_f32_16x16x32_bf16 v[80:83], v[118:121], v[220:223], v[80:83]
	s_setprio 0
	s_setprio 1
	v_mfma_f32_16x16x32_bf16 v[134:137], v[138:141], v[174:177], v[134:137]
	v_mfma_f32_16x16x32_bf16 v[130:133], v[154:157], v[174:177], v[130:133]
	v_mfma_f32_16x16x32_bf16 v[114:117], v[138:141], v[182:185], v[114:117]
	v_mfma_f32_16x16x32_bf16 v[108:111], v[154:157], v[182:185], v[108:111]
	v_mfma_f32_16x16x32_bf16 v[92:95], v[138:141], v[208:211], v[92:95]
	v_mfma_f32_16x16x32_bf16 v[88:91], v[154:157], v[208:211], v[88:91]
	v_mfma_f32_16x16x32_bf16 v[72:75], v[138:141], v[216:219], v[72:75]
	v_mfma_f32_16x16x32_bf16 v[68:71], v[154:157], v[216:219], v[68:71]
	v_mfma_f32_16x16x32_bf16 v[134:137], v[142:145], v[178:181], v[134:137]
	v_mfma_f32_16x16x32_bf16 v[130:133], v[158:161], v[178:181], v[130:133]
	v_mfma_f32_16x16x32_bf16 v[114:117], v[142:145], v[198:201], v[114:117]
	v_mfma_f32_16x16x32_bf16 v[108:111], v[158:161], v[198:201], v[108:111]
	v_mfma_f32_16x16x32_bf16 v[92:95], v[142:145], v[212:215], v[92:95]
	v_mfma_f32_16x16x32_bf16 v[88:91], v[158:161], v[212:215], v[88:91]
	v_mfma_f32_16x16x32_bf16 v[72:75], v[142:145], v[220:223], v[72:75]
	v_mfma_f32_16x16x32_bf16 v[68:71], v[158:161], v[220:223], v[68:71]
	s_setprio 0
	s_barrier
	s_add_i32 s50, s56, s82
	v_lshl_add_u64 v[194:195], v[194:195], 0, s[60:61]
	s_mov_b32 m0, s50
	ds_read_b128 v[174:177], v207 offset:49152
	ds_read_b128 v[178:181], v207 offset:50176
	ds_read_b128 v[182:185], v207 offset:51200
	ds_read_b128 v[198:201], v207 offset:52224
	ds_read_b128 v[208:211], v207 offset:53248
	ds_read_b128 v[212:215], v207 offset:54272
	ds_read_b128 v[216:219], v207 offset:55296
	ds_read_b128 v[220:223], v207 offset:56320
	global_load_lds_dwordx4 v[194:195], off
	s_add_i32 m0, s50, 0x2000
	s_add_u32 s44, s44, 0x40080
	v_lshl_add_u64 v[194:195], v[196:197], 0, s[60:61]
	s_addc_u32 s45, s45, 0
	s_add_i32 s50, s57, s82
	global_load_lds_dwordx4 v[194:195], off
	v_lshl_add_u64 v[194:195], s[44:45], 0, v[112:113]
	s_mov_b32 m0, s50
	s_nop 0
	global_load_lds_dwordx4 v[194:195], off
	v_lshl_add_u64 v[194:195], s[44:45], 0, v[166:167]
	s_add_i32 m0, s50, 0x2000
	s_nop 0
	global_load_lds_dwordx4 v[194:195], off
	v_lshl_add_u64 v[194:195], v[202:203], 0, s[60:61]
	s_mov_b32 m0, s14
	s_nop 0
	global_load_lds_dwordx4 v[194:195], off
	v_lshl_add_u64 v[194:195], v[234:235], 0, s[60:61]
	s_mov_b32 m0, s15
	s_nop 0
	global_load_lds_dwordx4 v[194:195], off
	s_waitcnt vmcnt(8)
	s_waitcnt lgkmcnt(0)
	s_barrier
	s_setprio 1
	s_waitcnt lgkmcnt(0)
	v_mfma_f32_16x16x32_bf16 v[60:63], v[64:67], v[174:177], v[60:63]
	v_mfma_f32_16x16x32_bf16 v[56:59], v[96:99], v[174:177], v[56:59]
	v_mfma_f32_16x16x32_bf16 v[44:47], v[64:67], v[182:185], v[44:47]
	v_mfma_f32_16x16x32_bf16 v[40:43], v[96:99], v[182:185], v[40:43]
	v_mfma_f32_16x16x32_bf16 v[28:31], v[64:67], v[208:211], v[28:31]
	v_mfma_f32_16x16x32_bf16 v[24:27], v[96:99], v[208:211], v[24:27]
	v_mfma_f32_16x16x32_bf16 v[12:15], v[64:67], v[216:219], v[12:15]
	v_mfma_f32_16x16x32_bf16 v[8:11], v[96:99], v[216:219], v[8:11]
	v_mfma_f32_16x16x32_bf16 v[60:63], v[76:79], v[178:181], v[60:63]
	v_mfma_f32_16x16x32_bf16 v[56:59], v[118:121], v[178:181], v[56:59]
	v_mfma_f32_16x16x32_bf16 v[44:47], v[76:79], v[198:201], v[44:47]
	v_mfma_f32_16x16x32_bf16 v[40:43], v[118:121], v[198:201], v[40:43]
	v_mfma_f32_16x16x32_bf16 v[28:31], v[76:79], v[212:215], v[28:31]
	v_mfma_f32_16x16x32_bf16 v[24:27], v[118:121], v[212:215], v[24:27]
	v_mfma_f32_16x16x32_bf16 v[12:15], v[76:79], v[220:223], v[12:15]
	v_mfma_f32_16x16x32_bf16 v[8:11], v[118:121], v[220:223], v[8:11]
	s_setprio 0
	s_setprio 1
	v_mfma_f32_16x16x32_bf16 v[52:55], v[138:141], v[174:177], v[52:55]
	v_mfma_f32_16x16x32_bf16 v[48:51], v[154:157], v[174:177], v[48:51]
	v_mfma_f32_16x16x32_bf16 v[36:39], v[138:141], v[182:185], v[36:39]
	v_mfma_f32_16x16x32_bf16 v[32:35], v[154:157], v[182:185], v[32:35]
	v_mfma_f32_16x16x32_bf16 v[20:23], v[138:141], v[208:211], v[20:23]
	v_mfma_f32_16x16x32_bf16 v[16:19], v[154:157], v[208:211], v[16:19]
	v_mfma_f32_16x16x32_bf16 v[4:7], v[138:141], v[216:219], v[4:7]
	v_mfma_f32_16x16x32_bf16 v[0:3], v[154:157], v[216:219], v[0:3]
	v_mfma_f32_16x16x32_bf16 v[52:55], v[142:145], v[178:181], v[52:55]
	v_mfma_f32_16x16x32_bf16 v[48:51], v[158:161], v[178:181], v[48:51]
	v_mfma_f32_16x16x32_bf16 v[36:39], v[142:145], v[198:201], v[36:39]
	v_mfma_f32_16x16x32_bf16 v[32:35], v[158:161], v[198:201], v[32:35]
	v_mfma_f32_16x16x32_bf16 v[20:23], v[142:145], v[212:215], v[20:23]
	v_mfma_f32_16x16x32_bf16 v[16:19], v[158:161], v[212:215], v[16:19]
	v_mfma_f32_16x16x32_bf16 v[4:7], v[142:145], v[220:223], v[4:7]
	v_mfma_f32_16x16x32_bf16 v[0:3], v[158:161], v[220:223], v[0:3]
	s_setprio 0
	s_barrier
	s_add_i32 s97, s97, 2
	s_add_u32 s10, s10, 0x100
	s_addc_u32 s11, s11, 0
	s_add_u32 s90, s90, 0x100
	s_addc_u32 s95, s95, 0
	s_cmp_gt_u32 s97, 13
	s_cbranch_scc0 .LBB0_454
	s_branch .Lpeel_after_2
	.p2alignl 6, 3212836864

.LBB0_598:
	s_ashr_i32 s19, s18, 31
	s_lshl_b64 s[20:21], s[18:19], 19
	s_add_u32 s20, s24, s20
	s_addc_u32 s21, s25, s21
	s_and_b64 s[22:23], s[30:31], exec
	s_cselect_b32 s19, s21, s37
	s_cselect_b32 s62, s20, s36
	s_ashr_i32 s13, s12, 31
	s_lshl_b64 s[22:23], s[12:13], 19
	s_add_u32 s22, s38, s22
	s_addc_u32 s23, s39, s23
	s_and_b64 s[42:43], s[30:31], exec
	s_cselect_b32 s13, s23, s41
	s_cselect_b32 s63, s22, s40
	s_add_u32 s36, s36, 0x40080
	s_addc_u32 s37, s37, 0
	s_add_u32 s69, s40, 0x100
	s_addc_u32 s70, s41, 0
	s_mov_b32 s71, -2
	s_add_u32 s40, s36, 0xfffc0080
	s_addc_u32 s41, s37, -1
	s_add_i32 s56, 0, 0x10000
	s_cmp_eq_u32 s71, 12
	s_cselect_b32 s43, s19, s41
	s_cselect_b32 s42, s62, s40
	s_cselect_b32 s41, s13, s70
	s_cselect_b32 s40, s63, s69
	s_add_i32 s64, 0, 0x14000
	v_add_u32_e32 v156, s56, v149
	v_add_u32_e32 v172, s64, v149
	ds_read_b128 v[140:143], v156
	ds_read_b128 v[144:147], v156 offset:1024
	ds_read_b128 v[152:155], v156 offset:2048
	ds_read_b128 v[156:159], v156 offset:3072
	ds_read_b128 v[160:163], v172
	ds_read_b128 v[164:167], v172 offset:1024
	ds_read_b128 v[168:171], v172 offset:2048
	ds_read_b128 v[172:175], v172 offset:3072
	v_lshl_add_u64 v[184:185], s[36:37], 0, v[136:137]
	s_add_i32 m0, s45, 0xc000
	ds_read_b128 v[176:179], v151
	ds_read_b128 v[180:183], v151 offset:1024
	ds_read_b128 v[198:201], v151 offset:2048
	ds_read_b128 v[202:205], v151 offset:3072
	ds_read_b128 v[206:209], v151 offset:4096
	ds_read_b128 v[210:213], v151 offset:5120
	ds_read_b128 v[214:217], v151 offset:6144
	ds_read_b128 v[218:221], v151 offset:7168
	global_load_lds_dwordx4 v[184:185], off
	v_lshl_add_u64 v[184:185], s[36:37], 0, v[138:139]
	s_add_i32 m0, s45, 0xe000
	s_nop 0
	global_load_lds_dwordx4 v[184:185], off
	s_waitcnt vmcnt(8)
	s_waitcnt lgkmcnt(0)
	s_barrier
	s_setprio 1
	s_waitcnt lgkmcnt(0)
	v_mfma_f32_16x16x32_bf16 v[126:129], v[140:143], v[176:179], 0
	v_mfma_f32_16x16x32_bf16 v[122:125], v[152:155], v[176:179], 0
	v_mfma_f32_16x16x32_bf16 v[108:111], v[140:143], v[198:201], 0
	v_mfma_f32_16x16x32_bf16 v[104:107], v[152:155], v[198:201], 0
	v_mfma_f32_16x16x32_bf16 v[92:95], v[140:143], v[206:209], 0
	v_mfma_f32_16x16x32_bf16 v[88:91], v[152:155], v[206:209], 0
	v_mfma_f32_16x16x32_bf16 v[76:79], v[140:143], v[214:217], 0
	v_mfma_f32_16x16x32_bf16 v[72:75], v[152:155], v[214:217], 0
	v_mfma_f32_16x16x32_bf16 v[126:129], v[144:147], v[180:183], v[126:129]
	v_mfma_f32_16x16x32_bf16 v[122:125], v[156:159], v[180:183], v[122:125]
	v_mfma_f32_16x16x32_bf16 v[108:111], v[144:147], v[202:205], v[108:111]
	v_mfma_f32_16x16x32_bf16 v[104:107], v[156:159], v[202:205], v[104:107]
	v_mfma_f32_16x16x32_bf16 v[92:95], v[144:147], v[210:213], v[92:95]
	v_mfma_f32_16x16x32_bf16 v[88:91], v[156:159], v[210:213], v[88:91]
	v_mfma_f32_16x16x32_bf16 v[76:79], v[144:147], v[218:221], v[76:79]
	v_mfma_f32_16x16x32_bf16 v[72:75], v[156:159], v[218:221], v[72:75]
	s_setprio 0
	s_setprio 1
	v_mfma_f32_16x16x32_bf16 v[118:121], v[160:163], v[176:179], 0
	v_mfma_f32_16x16x32_bf16 v[114:117], v[168:171], v[176:179], 0
	v_mfma_f32_16x16x32_bf16 v[100:103], v[160:163], v[198:201], 0
	v_mfma_f32_16x16x32_bf16 v[96:99], v[168:171], v[198:201], 0
	v_mfma_f32_16x16x32_bf16 v[84:87], v[160:163], v[206:209], 0
	v_mfma_f32_16x16x32_bf16 v[80:83], v[168:171], v[206:209], 0
	v_mfma_f32_16x16x32_bf16 v[68:71], v[160:163], v[214:217], 0
	v_mfma_f32_16x16x32_bf16 v[64:67], v[168:171], v[214:217], 0
	v_mfma_f32_16x16x32_bf16 v[118:121], v[164:167], v[180:183], v[118:121]
	v_mfma_f32_16x16x32_bf16 v[114:117], v[172:175], v[180:183], v[114:117]
	v_mfma_f32_16x16x32_bf16 v[100:103], v[164:167], v[202:205], v[100:103]
	v_mfma_f32_16x16x32_bf16 v[96:99], v[172:175], v[202:205], v[96:99]
	v_mfma_f32_16x16x32_bf16 v[84:87], v[164:167], v[210:213], v[84:87]
	v_mfma_f32_16x16x32_bf16 v[80:83], v[172:175], v[210:213], v[80:83]
	v_mfma_f32_16x16x32_bf16 v[68:71], v[164:167], v[218:221], v[68:71]
	v_mfma_f32_16x16x32_bf16 v[64:67], v[172:175], v[218:221], v[64:67]
	s_setprio 0
	s_barrier
	s_add_i32 s56, s56, s44
	v_lshl_add_u64 v[184:185], s[40:41], 0, v[112:113]
	s_mov_b32 m0, s56
	ds_read_b128 v[176:179], v151 offset:16384
	ds_read_b128 v[180:183], v151 offset:17408
	ds_read_b128 v[198:201], v151 offset:18432
	ds_read_b128 v[202:205], v151 offset:19456
	ds_read_b128 v[206:209], v151 offset:20480
	ds_read_b128 v[210:213], v151 offset:21504
	ds_read_b128 v[214:217], v151 offset:22528
	ds_read_b128 v[218:221], v151 offset:23552
	global_load_lds_dwordx4 v[184:185], off
	s_add_i32 m0, s56, 0x2000
	s_add_u32 s56, s40, 0x40000
	v_lshl_add_u64 v[194:195], s[40:41], 0, v[134:135]
	s_addc_u32 s57, s41, 0
	s_add_i32 s64, s64, s44
	global_load_lds_dwordx4 v[194:195], off
	v_lshl_add_u64 v[196:197], s[56:57], 0, v[112:113]
	s_mov_b32 m0, s64
	v_lshl_add_u64 v[222:223], s[42:43], 0, v[132:133]
	global_load_lds_dwordx4 v[196:197], off
	v_lshl_add_u64 v[196:197], s[56:57], 0, v[134:135]
	s_add_i32 m0, s64, 0x2000
	s_nop 0
	global_load_lds_dwordx4 v[196:197], off
	v_lshl_add_u64 v[196:197], s[42:43], 0, v[130:131]
	s_mov_b32 m0, s45
	s_nop 0
	global_load_lds_dwordx4 v[196:197], off
	s_mov_b32 m0, s47
	s_nop 0
	global_load_lds_dwordx4 v[222:223], off
	s_waitcnt vmcnt(8)
	s_waitcnt lgkmcnt(0)
	s_barrier
	s_setprio 1
	s_waitcnt lgkmcnt(0)
	v_mfma_f32_16x16x32_bf16 v[60:63], v[140:143], v[176:179], 0
	v_mfma_f32_16x16x32_bf16 v[56:59], v[152:155], v[176:179], 0
	v_mfma_f32_16x16x32_bf16 v[44:47], v[140:143], v[198:201], 0
	v_mfma_f32_16x16x32_bf16 v[40:43], v[152:155], v[198:201], 0
	v_mfma_f32_16x16x32_bf16 v[28:31], v[140:143], v[206:209], 0
	v_mfma_f32_16x16x32_bf16 v[24:27], v[152:155], v[206:209], 0
	v_mfma_f32_16x16x32_bf16 v[12:15], v[140:143], v[214:217], 0
	v_mfma_f32_16x16x32_bf16 v[8:11], v[152:155], v[214:217], 0
	v_mfma_f32_16x16x32_bf16 v[60:63], v[144:147], v[180:183], v[60:63]
	v_mfma_f32_16x16x32_bf16 v[56:59], v[156:159], v[180:183], v[56:59]
	v_mfma_f32_16x16x32_bf16 v[44:47], v[144:147], v[202:205], v[44:47]
	v_mfma_f32_16x16x32_bf16 v[40:43], v[156:159], v[202:205], v[40:43]
	v_mfma_f32_16x16x32_bf16 v[28:31], v[144:147], v[210:213], v[28:31]
	v_mfma_f32_16x16x32_bf16 v[24:27], v[156:159], v[210:213], v[24:27]
	v_mfma_f32_16x16x32_bf16 v[12:15], v[144:147], v[218:221], v[12:15]
	v_mfma_f32_16x16x32_bf16 v[8:11], v[156:159], v[218:221], v[8:11]
	s_setprio 0
	s_setprio 1
	v_mfma_f32_16x16x32_bf16 v[52:55], v[160:163], v[176:179], 0
	v_mfma_f32_16x16x32_bf16 v[48:51], v[168:171], v[176:179], 0
	v_mfma_f32_16x16x32_bf16 v[36:39], v[160:163], v[198:201], 0
	v_mfma_f32_16x16x32_bf16 v[32:35], v[168:171], v[198:201], 0
	v_mfma_f32_16x16x32_bf16 v[20:23], v[160:163], v[206:209], 0
	v_mfma_f32_16x16x32_bf16 v[16:19], v[168:171], v[206:209], 0
	v_mfma_f32_16x16x32_bf16 v[4:7], v[160:163], v[214:217], 0
	v_mfma_f32_16x16x32_bf16 v[0:3], v[168:171], v[214:217], 0
	v_mfma_f32_16x16x32_bf16 v[52:55], v[164:167], v[180:183], v[52:55]
	v_mfma_f32_16x16x32_bf16 v[48:51], v[172:175], v[180:183], v[48:51]
	v_mfma_f32_16x16x32_bf16 v[36:39], v[164:167], v[202:205], v[36:39]
	v_mfma_f32_16x16x32_bf16 v[32:35], v[172:175], v[202:205], v[32:35]
	v_mfma_f32_16x16x32_bf16 v[20:23], v[164:167], v[210:213], v[20:23]
	v_mfma_f32_16x16x32_bf16 v[16:19], v[172:175], v[210:213], v[16:19]
	v_mfma_f32_16x16x32_bf16 v[4:7], v[164:167], v[218:221], v[4:7]
	v_mfma_f32_16x16x32_bf16 v[0:3], v[172:175], v[218:221], v[0:3]
	s_setprio 0
	s_barrier
	s_add_i32 s56, 0, 0x18000
	s_add_i32 s57, 0, 0x1c000
	v_add_u32_e32 v156, s56, v149
	v_add_u32_e32 v172, s57, v149
	ds_read_b128 v[140:143], v156
	ds_read_b128 v[144:147], v156 offset:1024
	ds_read_b128 v[152:155], v156 offset:2048
	ds_read_b128 v[156:159], v156 offset:3072
	ds_read_b128 v[160:163], v172
	ds_read_b128 v[164:167], v172 offset:1024
	ds_read_b128 v[168:171], v172 offset:2048
	ds_read_b128 v[172:175], v172 offset:3072
	s_add_u32 s42, s42, 0x40000
	s_addc_u32 s43, s43, 0
	s_mov_b32 m0, s50
	v_lshl_add_u64 v[234:235], s[42:43], 0, v[130:131]
	ds_read_b128 v[176:179], v151 offset:32768
	ds_read_b128 v[180:183], v151 offset:33792
	ds_read_b128 v[198:201], v151 offset:34816
	ds_read_b128 v[202:205], v151 offset:35840
	ds_read_b128 v[206:209], v151 offset:36864
	ds_read_b128 v[210:213], v151 offset:37888
	ds_read_b128 v[214:217], v151 offset:38912
	ds_read_b128 v[218:221], v151 offset:39936
	global_load_lds_dwordx4 v[234:235], off
	v_lshl_add_u64 v[234:235], s[42:43], 0, v[132:133]
	s_mov_b32 m0, s51
	s_nop 0
	global_load_lds_dwordx4 v[234:235], off
	s_waitcnt vmcnt(8)
	s_waitcnt lgkmcnt(0)
	s_barrier
	s_setprio 1
	s_waitcnt lgkmcnt(0)
	v_mfma_f32_16x16x32_bf16 v[126:129], v[140:143], v[176:179], v[126:129]
	v_mfma_f32_16x16x32_bf16 v[122:125], v[152:155], v[176:179], v[122:125]
	v_mfma_f32_16x16x32_bf16 v[108:111], v[140:143], v[198:201], v[108:111]
	v_mfma_f32_16x16x32_bf16 v[104:107], v[152:155], v[198:201], v[104:107]
	v_mfma_f32_16x16x32_bf16 v[92:95], v[140:143], v[206:209], v[92:95]
	v_mfma_f32_16x16x32_bf16 v[88:91], v[152:155], v[206:209], v[88:91]
	v_mfma_f32_16x16x32_bf16 v[76:79], v[140:143], v[214:217], v[76:79]
	v_mfma_f32_16x16x32_bf16 v[72:75], v[152:155], v[214:217], v[72:75]
	v_mfma_f32_16x16x32_bf16 v[126:129], v[144:147], v[180:183], v[126:129]
	v_mfma_f32_16x16x32_bf16 v[122:125], v[156:159], v[180:183], v[122:125]
	v_mfma_f32_16x16x32_bf16 v[108:111], v[144:147], v[202:205], v[108:111]
	v_mfma_f32_16x16x32_bf16 v[104:107], v[156:159], v[202:205], v[104:107]
	v_mfma_f32_16x16x32_bf16 v[92:95], v[144:147], v[210:213], v[92:95]
	v_mfma_f32_16x16x32_bf16 v[88:91], v[156:159], v[210:213], v[88:91]
	v_mfma_f32_16x16x32_bf16 v[76:79], v[144:147], v[218:221], v[76:79]
	v_mfma_f32_16x16x32_bf16 v[72:75], v[156:159], v[218:221], v[72:75]
	s_setprio 0
	s_setprio 1
	v_mfma_f32_16x16x32_bf16 v[118:121], v[160:163], v[176:179], v[118:121]
	v_mfma_f32_16x16x32_bf16 v[114:117], v[168:171], v[176:179], v[114:117]
	v_mfma_f32_16x16x32_bf16 v[100:103], v[160:163], v[198:201], v[100:103]
	v_mfma_f32_16x16x32_bf16 v[96:99], v[168:171], v[198:201], v[96:99]
	v_mfma_f32_16x16x32_bf16 v[84:87], v[160:163], v[206:209], v[84:87]
	v_mfma_f32_16x16x32_bf16 v[80:83], v[168:171], v[206:209], v[80:83]
	v_mfma_f32_16x16x32_bf16 v[68:71], v[160:163], v[214:217], v[68:71]
	v_mfma_f32_16x16x32_bf16 v[64:67], v[168:171], v[214:217], v[64:67]
	v_mfma_f32_16x16x32_bf16 v[118:121], v[164:167], v[180:183], v[118:121]
	v_mfma_f32_16x16x32_bf16 v[114:117], v[172:175], v[180:183], v[114:117]
	v_mfma_f32_16x16x32_bf16 v[100:103], v[164:167], v[202:205], v[100:103]
	v_mfma_f32_16x16x32_bf16 v[96:99], v[172:175], v[202:205], v[96:99]
	v_mfma_f32_16x16x32_bf16 v[84:87], v[164:167], v[210:213], v[84:87]
	v_mfma_f32_16x16x32_bf16 v[80:83], v[172:175], v[210:213], v[80:83]
	v_mfma_f32_16x16x32_bf16 v[68:71], v[164:167], v[218:221], v[68:71]
	v_mfma_f32_16x16x32_bf16 v[64:67], v[172:175], v[218:221], v[64:67]
	s_setprio 0
	s_barrier
	s_add_i32 s42, s56, s44
	v_lshl_add_u64 v[184:185], v[184:185], 0, s[60:61]
	s_mov_b32 m0, s42
	ds_read_b128 v[176:179], v151 offset:49152
	ds_read_b128 v[180:183], v151 offset:50176
	ds_read_b128 v[198:201], v151 offset:51200
	ds_read_b128 v[202:205], v151 offset:52224
	ds_read_b128 v[206:209], v151 offset:53248
	ds_read_b128 v[210:213], v151 offset:54272
	ds_read_b128 v[214:217], v151 offset:55296
	ds_read_b128 v[218:221], v151 offset:56320
	global_load_lds_dwordx4 v[184:185], off
	s_add_i32 m0, s42, 0x2000
	s_add_u32 s40, s40, 0x40080
	v_lshl_add_u64 v[184:185], v[194:195], 0, s[60:61]
	s_addc_u32 s41, s41, 0
	s_add_i32 s42, s57, s44
	global_load_lds_dwordx4 v[184:185], off
	v_lshl_add_u64 v[184:185], s[40:41], 0, v[112:113]
	s_mov_b32 m0, s42
	s_nop 0
	global_load_lds_dwordx4 v[184:185], off
	v_lshl_add_u64 v[184:185], s[40:41], 0, v[134:135]
	s_add_i32 m0, s42, 0x2000
	s_nop 0
	global_load_lds_dwordx4 v[184:185], off
	v_lshl_add_u64 v[184:185], v[196:197], 0, s[60:61]
	s_mov_b32 m0, s55
	s_nop 0
	global_load_lds_dwordx4 v[184:185], off
	v_lshl_add_u64 v[184:185], v[222:223], 0, s[60:61]
	s_mov_b32 m0, s58
	s_nop 0
	global_load_lds_dwordx4 v[184:185], off
	s_waitcnt vmcnt(8)
	s_waitcnt lgkmcnt(0)
	s_barrier
	s_setprio 1
	s_waitcnt lgkmcnt(0)
	v_mfma_f32_16x16x32_bf16 v[60:63], v[140:143], v[176:179], v[60:63]
	v_mfma_f32_16x16x32_bf16 v[56:59], v[152:155], v[176:179], v[56:59]
	v_mfma_f32_16x16x32_bf16 v[44:47], v[140:143], v[198:201], v[44:47]
	v_mfma_f32_16x16x32_bf16 v[40:43], v[152:155], v[198:201], v[40:43]
	v_mfma_f32_16x16x32_bf16 v[28:31], v[140:143], v[206:209], v[28:31]
	v_mfma_f32_16x16x32_bf16 v[24:27], v[152:155], v[206:209], v[24:27]
	v_mfma_f32_16x16x32_bf16 v[12:15], v[140:143], v[214:217], v[12:15]
	v_mfma_f32_16x16x32_bf16 v[8:11], v[152:155], v[214:217], v[8:11]
	v_mfma_f32_16x16x32_bf16 v[60:63], v[144:147], v[180:183], v[60:63]
	v_mfma_f32_16x16x32_bf16 v[56:59], v[156:159], v[180:183], v[56:59]
	v_mfma_f32_16x16x32_bf16 v[44:47], v[144:147], v[202:205], v[44:47]
	v_mfma_f32_16x16x32_bf16 v[40:43], v[156:159], v[202:205], v[40:43]
	v_mfma_f32_16x16x32_bf16 v[28:31], v[144:147], v[210:213], v[28:31]
	v_mfma_f32_16x16x32_bf16 v[24:27], v[156:159], v[210:213], v[24:27]
	v_mfma_f32_16x16x32_bf16 v[12:15], v[144:147], v[218:221], v[12:15]
	v_mfma_f32_16x16x32_bf16 v[8:11], v[156:159], v[218:221], v[8:11]
	s_setprio 0
	s_setprio 1
	v_mfma_f32_16x16x32_bf16 v[52:55], v[160:163], v[176:179], v[52:55]
	v_mfma_f32_16x16x32_bf16 v[48:51], v[168:171], v[176:179], v[48:51]
	v_mfma_f32_16x16x32_bf16 v[36:39], v[160:163], v[198:201], v[36:39]
	v_mfma_f32_16x16x32_bf16 v[32:35], v[168:171], v[198:201], v[32:35]
	v_mfma_f32_16x16x32_bf16 v[20:23], v[160:163], v[206:209], v[20:23]
	v_mfma_f32_16x16x32_bf16 v[16:19], v[168:171], v[206:209], v[16:19]
	v_mfma_f32_16x16x32_bf16 v[4:7], v[160:163], v[214:217], v[4:7]
	v_mfma_f32_16x16x32_bf16 v[0:3], v[168:171], v[214:217], v[0:3]
	v_mfma_f32_16x16x32_bf16 v[52:55], v[164:167], v[180:183], v[52:55]
	v_mfma_f32_16x16x32_bf16 v[48:51], v[172:175], v[180:183], v[48:51]
	v_mfma_f32_16x16x32_bf16 v[36:39], v[164:167], v[202:205], v[36:39]
	v_mfma_f32_16x16x32_bf16 v[32:35], v[172:175], v[202:205], v[32:35]
	v_mfma_f32_16x16x32_bf16 v[20:23], v[164:167], v[210:213], v[20:23]
	v_mfma_f32_16x16x32_bf16 v[16:19], v[172:175], v[210:213], v[16:19]
	v_mfma_f32_16x16x32_bf16 v[4:7], v[164:167], v[218:221], v[4:7]
	v_mfma_f32_16x16x32_bf16 v[0:3], v[172:175], v[218:221], v[0:3]
	s_setprio 0
	s_barrier
	s_add_i32 s71, s71, 2
	s_add_u32 s36, s36, 0x100
	s_addc_u32 s37, s37, 0
	s_add_u32 s69, s69, 0x100
	s_addc_u32 s70, s70, 0
	s_cmp_gt_u32 s71, 13
	s_cbranch_scc0 .LBB0_599
	s_branch .Lpeel_after_3
	.p2alignl 6, 3212836864

.LBB0_730:
	s_ashr_i32 s23, s22, 31
	s_lshl_b64 s[34:35], s[22:23], 19
	s_add_u32 s34, s15, s34
	s_addc_u32 s35, s24, s35
	s_and_b64 s[6:7], s[6:7], exec
	s_cselect_b32 s9, s35, s41
	s_cselect_b32 s23, s34, s40
	s_add_u32 s6, s40, 0x40080
	s_addc_u32 s7, s41, 0
	s_add_u32 s62, s36, 0x100
	s_addc_u32 s63, s37, 0
	s_mov_b32 s69, -2
	s_add_u32 s36, s6, 0xfffc0080
	s_addc_u32 s37, s7, -1
	s_add_i32 s56, 0, 0x10000
	s_cmp_eq_u32 s69, 2
	s_cselect_b32 s41, s9, s37
	s_cselect_b32 s40, s23, s36
	v_add_u32_e32 v144, s56, v147
	s_cselect_b32 s37, s31, s63
	s_cselect_b32 s36, s30, s62
	s_add_i32 s64, 0, 0x14000
	ds_read_b128 v[140:143], v144
	ds_read_b128 v[150:153], v144 offset:1024
	ds_read_b128 v[154:157], v144 offset:2048
	ds_read_b128 v[158:161], v144 offset:3072
	v_add_u32_e32 v144, s64, v147
	ds_read_b128 v[162:165], v144
	ds_read_b128 v[166:169], v144 offset:1024
	ds_read_b128 v[170:173], v144 offset:2048
	ds_read_b128 v[174:177], v144 offset:3072
	v_lshl_add_u64 v[144:145], s[6:7], 0, v[136:137]
	s_add_i32 m0, s42, 0xc000
	ds_read_b128 v[178:181], v149
	ds_read_b128 v[182:185], v149 offset:1024
	ds_read_b128 v[198:201], v149 offset:2048
	ds_read_b128 v[202:205], v149 offset:3072
	ds_read_b128 v[206:209], v149 offset:4096
	ds_read_b128 v[210:213], v149 offset:5120
	ds_read_b128 v[214:217], v149 offset:6144
	ds_read_b128 v[218:221], v149 offset:7168
	global_load_lds_dwordx4 v[144:145], off
	v_lshl_add_u64 v[144:145], s[6:7], 0, v[138:139]
	s_add_i32 m0, s42, 0xe000
	s_nop 0
	global_load_lds_dwordx4 v[144:145], off
	s_waitcnt vmcnt(8)
	s_waitcnt lgkmcnt(0)
	s_barrier
	s_setprio 1
	s_waitcnt lgkmcnt(0)
	v_mfma_f32_16x16x32_bf16 v[126:129], v[140:143], v[178:181], 0
	v_mfma_f32_16x16x32_bf16 v[122:125], v[154:157], v[178:181], 0
	v_mfma_f32_16x16x32_bf16 v[108:111], v[140:143], v[198:201], 0
	v_mfma_f32_16x16x32_bf16 v[104:107], v[154:157], v[198:201], 0
	v_mfma_f32_16x16x32_bf16 v[92:95], v[140:143], v[206:209], 0
	v_mfma_f32_16x16x32_bf16 v[88:91], v[154:157], v[206:209], 0
	v_mfma_f32_16x16x32_bf16 v[76:79], v[140:143], v[214:217], 0
	v_mfma_f32_16x16x32_bf16 v[72:75], v[154:157], v[214:217], 0
	v_mfma_f32_16x16x32_bf16 v[126:129], v[150:153], v[182:185], v[126:129]
	v_mfma_f32_16x16x32_bf16 v[122:125], v[158:161], v[182:185], v[122:125]
	v_mfma_f32_16x16x32_bf16 v[108:111], v[150:153], v[202:205], v[108:111]
	v_mfma_f32_16x16x32_bf16 v[104:107], v[158:161], v[202:205], v[104:107]
	v_mfma_f32_16x16x32_bf16 v[92:95], v[150:153], v[210:213], v[92:95]
	v_mfma_f32_16x16x32_bf16 v[88:91], v[158:161], v[210:213], v[88:91]
	v_mfma_f32_16x16x32_bf16 v[76:79], v[150:153], v[218:221], v[76:79]
	v_mfma_f32_16x16x32_bf16 v[72:75], v[158:161], v[218:221], v[72:75]
	s_setprio 0
	s_setprio 1
	v_mfma_f32_16x16x32_bf16 v[118:121], v[162:165], v[178:181], 0
	v_mfma_f32_16x16x32_bf16 v[114:117], v[170:173], v[178:181], 0
	v_mfma_f32_16x16x32_bf16 v[100:103], v[162:165], v[198:201], 0
	v_mfma_f32_16x16x32_bf16 v[96:99], v[170:173], v[198:201], 0
	v_mfma_f32_16x16x32_bf16 v[84:87], v[162:165], v[206:209], 0
	v_mfma_f32_16x16x32_bf16 v[80:83], v[170:173], v[206:209], 0
	v_mfma_f32_16x16x32_bf16 v[68:71], v[162:165], v[214:217], 0
	v_mfma_f32_16x16x32_bf16 v[64:67], v[170:173], v[214:217], 0
	v_mfma_f32_16x16x32_bf16 v[118:121], v[166:169], v[182:185], v[118:121]
	v_mfma_f32_16x16x32_bf16 v[114:117], v[174:177], v[182:185], v[114:117]
	v_mfma_f32_16x16x32_bf16 v[100:103], v[166:169], v[202:205], v[100:103]
	v_mfma_f32_16x16x32_bf16 v[96:99], v[174:177], v[202:205], v[96:99]
	v_mfma_f32_16x16x32_bf16 v[84:87], v[166:169], v[210:213], v[84:87]
	v_mfma_f32_16x16x32_bf16 v[80:83], v[174:177], v[210:213], v[80:83]
	v_mfma_f32_16x16x32_bf16 v[68:71], v[166:169], v[218:221], v[68:71]
	v_mfma_f32_16x16x32_bf16 v[64:67], v[174:177], v[218:221], v[64:67]
	s_setprio 0
	s_barrier
	s_add_i32 s56, s56, s39
	v_lshl_add_u64 v[144:145], s[36:37], 0, v[112:113]
	s_mov_b32 m0, s56
	ds_read_b128 v[178:181], v149 offset:16384
	ds_read_b128 v[182:185], v149 offset:17408
	ds_read_b128 v[198:201], v149 offset:18432
	ds_read_b128 v[202:205], v149 offset:19456
	ds_read_b128 v[206:209], v149 offset:20480
	ds_read_b128 v[210:213], v149 offset:21504
	ds_read_b128 v[214:217], v149 offset:22528
	ds_read_b128 v[218:221], v149 offset:23552
	global_load_lds_dwordx4 v[144:145], off
	s_add_i32 m0, s56, 0x2000
	s_add_u32 s56, s36, 0x18000
	v_lshl_add_u64 v[194:195], s[36:37], 0, v[134:135]
	s_addc_u32 s57, s37, 0
	s_add_i32 s64, s64, s39
	global_load_lds_dwordx4 v[194:195], off
	v_lshl_add_u64 v[196:197], s[56:57], 0, v[112:113]
	s_mov_b32 m0, s64
	v_lshl_add_u64 v[222:223], s[40:41], 0, v[132:133]
	global_load_lds_dwordx4 v[196:197], off
	v_lshl_add_u64 v[196:197], s[56:57], 0, v[134:135]
	s_add_i32 m0, s64, 0x2000
	s_nop 0
	global_load_lds_dwordx4 v[196:197], off
	v_lshl_add_u64 v[196:197], s[40:41], 0, v[130:131]
	s_mov_b32 m0, s42
	s_nop 0
	global_load_lds_dwordx4 v[196:197], off
	s_mov_b32 m0, s43
	s_nop 0
	global_load_lds_dwordx4 v[222:223], off
	s_waitcnt vmcnt(8)
	s_waitcnt lgkmcnt(0)
	s_barrier
	s_setprio 1
	s_waitcnt lgkmcnt(0)
	v_mfma_f32_16x16x32_bf16 v[60:63], v[140:143], v[178:181], 0
	v_mfma_f32_16x16x32_bf16 v[56:59], v[154:157], v[178:181], 0
	v_mfma_f32_16x16x32_bf16 v[44:47], v[140:143], v[198:201], 0
	v_mfma_f32_16x16x32_bf16 v[40:43], v[154:157], v[198:201], 0
	v_mfma_f32_16x16x32_bf16 v[28:31], v[140:143], v[206:209], 0
	v_mfma_f32_16x16x32_bf16 v[24:27], v[154:157], v[206:209], 0
	v_mfma_f32_16x16x32_bf16 v[12:15], v[140:143], v[214:217], 0
	v_mfma_f32_16x16x32_bf16 v[8:11], v[154:157], v[214:217], 0
	v_mfma_f32_16x16x32_bf16 v[60:63], v[150:153], v[182:185], v[60:63]
	v_mfma_f32_16x16x32_bf16 v[56:59], v[158:161], v[182:185], v[56:59]
	v_mfma_f32_16x16x32_bf16 v[44:47], v[150:153], v[202:205], v[44:47]
	v_mfma_f32_16x16x32_bf16 v[40:43], v[158:161], v[202:205], v[40:43]
	v_mfma_f32_16x16x32_bf16 v[28:31], v[150:153], v[210:213], v[28:31]
	v_mfma_f32_16x16x32_bf16 v[24:27], v[158:161], v[210:213], v[24:27]
	v_mfma_f32_16x16x32_bf16 v[12:15], v[150:153], v[218:221], v[12:15]
	v_mfma_f32_16x16x32_bf16 v[8:11], v[158:161], v[218:221], v[8:11]
	s_setprio 0
	s_setprio 1
	v_mfma_f32_16x16x32_bf16 v[52:55], v[162:165], v[178:181], 0
	v_mfma_f32_16x16x32_bf16 v[48:51], v[170:173], v[178:181], 0
	v_mfma_f32_16x16x32_bf16 v[36:39], v[162:165], v[198:201], 0
	v_mfma_f32_16x16x32_bf16 v[32:35], v[170:173], v[198:201], 0
	v_mfma_f32_16x16x32_bf16 v[20:23], v[162:165], v[206:209], 0
	v_mfma_f32_16x16x32_bf16 v[16:19], v[170:173], v[206:209], 0
	v_mfma_f32_16x16x32_bf16 v[4:7], v[162:165], v[214:217], 0
	v_mfma_f32_16x16x32_bf16 v[0:3], v[170:173], v[214:217], 0
	v_mfma_f32_16x16x32_bf16 v[52:55], v[166:169], v[182:185], v[52:55]
	v_mfma_f32_16x16x32_bf16 v[48:51], v[174:177], v[182:185], v[48:51]
	v_mfma_f32_16x16x32_bf16 v[36:39], v[166:169], v[202:205], v[36:39]
	v_mfma_f32_16x16x32_bf16 v[32:35], v[174:177], v[202:205], v[32:35]
	v_mfma_f32_16x16x32_bf16 v[20:23], v[166:169], v[210:213], v[20:23]
	v_mfma_f32_16x16x32_bf16 v[16:19], v[174:177], v[210:213], v[16:19]
	v_mfma_f32_16x16x32_bf16 v[4:7], v[166:169], v[218:221], v[4:7]
	v_mfma_f32_16x16x32_bf16 v[0:3], v[174:177], v[218:221], v[0:3]
	s_setprio 0
	s_barrier
	s_add_i32 s56, 0, 0x18000
	s_add_i32 s57, 0, 0x1c000
	v_add_u32_e32 v158, s56, v147
	v_add_u32_e32 v174, s57, v147
	ds_read_b128 v[140:143], v158
	ds_read_b128 v[150:153], v158 offset:1024
	ds_read_b128 v[154:157], v158 offset:2048
	ds_read_b128 v[158:161], v158 offset:3072
	ds_read_b128 v[162:165], v174
	ds_read_b128 v[166:169], v174 offset:1024
	ds_read_b128 v[170:173], v174 offset:2048
	ds_read_b128 v[174:177], v174 offset:3072
	s_add_u32 s40, s40, 0x40000
	s_addc_u32 s41, s41, 0
	s_mov_b32 m0, s44
	v_lshl_add_u64 v[234:235], s[40:41], 0, v[130:131]
	ds_read_b128 v[178:181], v149 offset:32768
	ds_read_b128 v[182:185], v149 offset:33792
	ds_read_b128 v[198:201], v149 offset:34816
	ds_read_b128 v[202:205], v149 offset:35840
	ds_read_b128 v[206:209], v149 offset:36864
	ds_read_b128 v[210:213], v149 offset:37888
	ds_read_b128 v[214:217], v149 offset:38912
	ds_read_b128 v[218:221], v149 offset:39936
	global_load_lds_dwordx4 v[234:235], off
	v_lshl_add_u64 v[234:235], s[40:41], 0, v[132:133]
	s_mov_b32 m0, s45
	s_nop 0
	global_load_lds_dwordx4 v[234:235], off
	s_waitcnt vmcnt(8)
	s_waitcnt lgkmcnt(0)
	s_barrier
	s_setprio 1
	s_waitcnt lgkmcnt(0)
	v_mfma_f32_16x16x32_bf16 v[126:129], v[140:143], v[178:181], v[126:129]
	v_mfma_f32_16x16x32_bf16 v[122:125], v[154:157], v[178:181], v[122:125]
	v_mfma_f32_16x16x32_bf16 v[108:111], v[140:143], v[198:201], v[108:111]
	v_mfma_f32_16x16x32_bf16 v[104:107], v[154:157], v[198:201], v[104:107]
	v_mfma_f32_16x16x32_bf16 v[92:95], v[140:143], v[206:209], v[92:95]
	v_mfma_f32_16x16x32_bf16 v[88:91], v[154:157], v[206:209], v[88:91]
	v_mfma_f32_16x16x32_bf16 v[76:79], v[140:143], v[214:217], v[76:79]
	v_mfma_f32_16x16x32_bf16 v[72:75], v[154:157], v[214:217], v[72:75]
	v_mfma_f32_16x16x32_bf16 v[126:129], v[150:153], v[182:185], v[126:129]
	v_mfma_f32_16x16x32_bf16 v[122:125], v[158:161], v[182:185], v[122:125]
	v_mfma_f32_16x16x32_bf16 v[108:111], v[150:153], v[202:205], v[108:111]
	v_mfma_f32_16x16x32_bf16 v[104:107], v[158:161], v[202:205], v[104:107]
	v_mfma_f32_16x16x32_bf16 v[92:95], v[150:153], v[210:213], v[92:95]
	v_mfma_f32_16x16x32_bf16 v[88:91], v[158:161], v[210:213], v[88:91]
	v_mfma_f32_16x16x32_bf16 v[76:79], v[150:153], v[218:221], v[76:79]
	v_mfma_f32_16x16x32_bf16 v[72:75], v[158:161], v[218:221], v[72:75]
	s_setprio 0
	s_setprio 1
	v_mfma_f32_16x16x32_bf16 v[118:121], v[162:165], v[178:181], v[118:121]
	v_mfma_f32_16x16x32_bf16 v[114:117], v[170:173], v[178:181], v[114:117]
	v_mfma_f32_16x16x32_bf16 v[100:103], v[162:165], v[198:201], v[100:103]
	v_mfma_f32_16x16x32_bf16 v[96:99], v[170:173], v[198:201], v[96:99]
	v_mfma_f32_16x16x32_bf16 v[84:87], v[162:165], v[206:209], v[84:87]
	v_mfma_f32_16x16x32_bf16 v[80:83], v[170:173], v[206:209], v[80:83]
	v_mfma_f32_16x16x32_bf16 v[68:71], v[162:165], v[214:217], v[68:71]
	v_mfma_f32_16x16x32_bf16 v[64:67], v[170:173], v[214:217], v[64:67]
	v_mfma_f32_16x16x32_bf16 v[118:121], v[166:169], v[182:185], v[118:121]
	v_mfma_f32_16x16x32_bf16 v[114:117], v[174:177], v[182:185], v[114:117]
	v_mfma_f32_16x16x32_bf16 v[100:103], v[166:169], v[202:205], v[100:103]
	v_mfma_f32_16x16x32_bf16 v[96:99], v[174:177], v[202:205], v[96:99]
	v_mfma_f32_16x16x32_bf16 v[84:87], v[166:169], v[210:213], v[84:87]
	v_mfma_f32_16x16x32_bf16 v[80:83], v[174:177], v[210:213], v[80:83]
	v_mfma_f32_16x16x32_bf16 v[68:71], v[166:169], v[218:221], v[68:71]
	v_mfma_f32_16x16x32_bf16 v[64:67], v[174:177], v[218:221], v[64:67]
	s_setprio 0
	s_barrier
	s_add_i32 s40, s56, s39
	v_lshl_add_u64 v[144:145], v[144:145], 0, s[60:61]
	s_mov_b32 m0, s40
	ds_read_b128 v[178:181], v149 offset:49152
	ds_read_b128 v[182:185], v149 offset:50176
	ds_read_b128 v[198:201], v149 offset:51200
	ds_read_b128 v[202:205], v149 offset:52224
	ds_read_b128 v[206:209], v149 offset:53248
	ds_read_b128 v[210:213], v149 offset:54272
	ds_read_b128 v[214:217], v149 offset:55296
	ds_read_b128 v[218:221], v149 offset:56320
	global_load_lds_dwordx4 v[144:145], off
	s_add_i32 m0, s40, 0x2000
	s_add_u32 s36, s36, 0x18080
	v_lshl_add_u64 v[144:145], v[194:195], 0, s[60:61]
	s_addc_u32 s37, s37, 0
	s_add_i32 s40, s57, s39
	global_load_lds_dwordx4 v[144:145], off
	v_lshl_add_u64 v[144:145], s[36:37], 0, v[112:113]
	s_mov_b32 m0, s40
	s_nop 0
	global_load_lds_dwordx4 v[144:145], off
	v_lshl_add_u64 v[144:145], s[36:37], 0, v[134:135]
	s_add_i32 m0, s40, 0x2000
	s_nop 0
	global_load_lds_dwordx4 v[144:145], off
	v_lshl_add_u64 v[144:145], v[196:197], 0, s[60:61]
	s_mov_b32 m0, s47
	s_nop 0
	global_load_lds_dwordx4 v[144:145], off
	v_lshl_add_u64 v[144:145], v[222:223], 0, s[60:61]
	s_mov_b32 m0, s50
	s_nop 0
	global_load_lds_dwordx4 v[144:145], off
	s_waitcnt vmcnt(8)
	s_waitcnt lgkmcnt(0)
	s_barrier
	s_setprio 1
	s_waitcnt lgkmcnt(0)
	v_mfma_f32_16x16x32_bf16 v[60:63], v[140:143], v[178:181], v[60:63]
	v_mfma_f32_16x16x32_bf16 v[56:59], v[154:157], v[178:181], v[56:59]
	v_mfma_f32_16x16x32_bf16 v[44:47], v[140:143], v[198:201], v[44:47]
	v_mfma_f32_16x16x32_bf16 v[40:43], v[154:157], v[198:201], v[40:43]
	v_mfma_f32_16x16x32_bf16 v[28:31], v[140:143], v[206:209], v[28:31]
	v_mfma_f32_16x16x32_bf16 v[24:27], v[154:157], v[206:209], v[24:27]
	v_mfma_f32_16x16x32_bf16 v[12:15], v[140:143], v[214:217], v[12:15]
	v_mfma_f32_16x16x32_bf16 v[8:11], v[154:157], v[214:217], v[8:11]
	v_mfma_f32_16x16x32_bf16 v[60:63], v[150:153], v[182:185], v[60:63]
	v_mfma_f32_16x16x32_bf16 v[56:59], v[158:161], v[182:185], v[56:59]
	v_mfma_f32_16x16x32_bf16 v[44:47], v[150:153], v[202:205], v[44:47]
	v_mfma_f32_16x16x32_bf16 v[40:43], v[158:161], v[202:205], v[40:43]
	v_mfma_f32_16x16x32_bf16 v[28:31], v[150:153], v[210:213], v[28:31]
	v_mfma_f32_16x16x32_bf16 v[24:27], v[158:161], v[210:213], v[24:27]
	v_mfma_f32_16x16x32_bf16 v[12:15], v[150:153], v[218:221], v[12:15]
	v_mfma_f32_16x16x32_bf16 v[8:11], v[158:161], v[218:221], v[8:11]
	s_setprio 0
	s_setprio 1
	v_mfma_f32_16x16x32_bf16 v[52:55], v[162:165], v[178:181], v[52:55]
	v_mfma_f32_16x16x32_bf16 v[48:51], v[170:173], v[178:181], v[48:51]
	v_mfma_f32_16x16x32_bf16 v[36:39], v[162:165], v[198:201], v[36:39]
	v_mfma_f32_16x16x32_bf16 v[32:35], v[170:173], v[198:201], v[32:35]
	v_mfma_f32_16x16x32_bf16 v[20:23], v[162:165], v[206:209], v[20:23]
	v_mfma_f32_16x16x32_bf16 v[16:19], v[170:173], v[206:209], v[16:19]
	v_mfma_f32_16x16x32_bf16 v[4:7], v[162:165], v[214:217], v[4:7]
	v_mfma_f32_16x16x32_bf16 v[0:3], v[170:173], v[214:217], v[0:3]
	v_mfma_f32_16x16x32_bf16 v[52:55], v[166:169], v[182:185], v[52:55]
	v_mfma_f32_16x16x32_bf16 v[48:51], v[174:177], v[182:185], v[48:51]
	v_mfma_f32_16x16x32_bf16 v[36:39], v[166:169], v[202:205], v[36:39]
	v_mfma_f32_16x16x32_bf16 v[32:35], v[174:177], v[202:205], v[32:35]
	v_mfma_f32_16x16x32_bf16 v[20:23], v[166:169], v[210:213], v[20:23]
	v_mfma_f32_16x16x32_bf16 v[16:19], v[174:177], v[210:213], v[16:19]
	v_mfma_f32_16x16x32_bf16 v[4:7], v[166:169], v[218:221], v[4:7]
	v_mfma_f32_16x16x32_bf16 v[0:3], v[174:177], v[218:221], v[0:3]
	s_setprio 0
	s_barrier
	s_add_i32 s69, s69, 2
	s_add_u32 s6, s6, 0x100
	s_addc_u32 s7, s7, 0
	s_add_u32 s62, s62, 0x100
	s_addc_u32 s63, s63, 0
	s_cmp_gt_u32 s69, 3
	s_cbranch_scc0 .LBB0_731
	s_branch .Lpeel_after_4
	.p2alignl 6, 3212836864

.LBB0_780:
	s_ashr_i32 s23, s22, 31
	s_lshl_b64 s[12:13], s[22:23], 19
	s_add_u32 s30, s39, s12
	s_addc_u32 s31, s47, s13
	s_and_b64 s[12:13], s[4:5], exec
	s_cselect_b32 s7, s31, s41
	s_cselect_b32 s9, s30, s40
	s_ashr_i32 s21, s20, 31
	s_lshl_b64 s[12:13], s[20:21], 17
	s_add_u32 s34, s55, s12
	s_addc_u32 s35, s58, s13
	s_and_b64 s[12:13], s[4:5], exec
	s_cselect_b32 s21, s35, s37
	s_cselect_b32 s23, s34, s36
	s_mov_b32 s24, 0
	s_mov_b64 s[42:43], -1
	s_mov_b64 s[44:45], 0
	s_add_u32 s25, s40, s24
	s_addc_u32 s50, s41, 0
	s_add_u32 s51, s25, 0x100
	s_addc_u32 s56, s50, 0
	s_and_b64 s[12:13], s[44:45], exec
	s_cselect_b32 s63, s7, s56
	s_cselect_b32 s62, s9, s51
	s_add_u32 s12, s36, s24
	s_addc_u32 s13, s37, 0
	s_add_u32 s24, s12, 0x100
	s_addc_u32 s51, s13, 0
	s_add_i32 s56, 0, 0x10000
	s_and_b64 s[12:13], s[44:45], exec
	s_cselect_b32 s73, s21, s51
	s_cselect_b32 s72, s23, s24
	s_add_i32 s57, 0, 0x14000
	s_add_u32 s96, s25, 0x40080
	s_addc_u32 s97, s50, 0
	s_add_i32 s75, s56, s59
	s_add_i32 m0, s69, 0xc000
	s_add_i32 s76, s69, 0xe000
	s_add_i32 s64, s75, 0x2000
	s_add_u32 vcc_lo, s72, 0x10000
	v_add_u32_e32 v140, s56, v143
	s_addc_u32 vcc_hi, s73, 0
	s_add_i32 s13, s57, s59
	ds_read_b128 v[136:139], v140
	ds_read_b128 v[146:149], v140 offset:1024
	ds_read_b128 v[150:153], v140 offset:2048
	ds_read_b128 v[154:157], v140 offset:3072
	v_add_u32_e32 v140, s57, v143
	s_add_i32 s12, s13, 0x2000
	s_add_i32 s94, 0, 0x18000
	s_add_i32 s95, 0, 0x1c000
	ds_read_b128 v[158:161], v140
	ds_read_b128 v[162:165], v140 offset:1024
	ds_read_b128 v[166:169], v140 offset:2048
	ds_read_b128 v[170:173], v140 offset:3072
	s_add_u32 s50, s62, 0x40000
	s_addc_u32 s51, s63, 0
	s_add_i32 s25, s94, s59
	s_add_i32 s87, s25, 0x2000
	s_add_u32 s44, s72, 0x10080
	s_addc_u32 s45, s73, 0
	s_add_i32 s90, s95, s59
	s_add_i32 s24, s90, 0x2000
	v_lshl_add_u64 v[140:141], s[96:97], 0, v[130:131]
	ds_read_b128 v[174:177], v145
	ds_read_b128 v[178:181], v145 offset:1024
	ds_read_b128 v[182:185], v145 offset:2048
	ds_read_b128 v[198:201], v145 offset:3072
	ds_read_b128 v[202:205], v145 offset:4096
	ds_read_b128 v[206:209], v145 offset:5120
	ds_read_b128 v[210:213], v145 offset:6144
	ds_read_b128 v[214:217], v145 offset:7168
	global_load_lds_dwordx4 v[140:141], off
	v_lshl_add_u64 v[140:141], s[96:97], 0, v[132:133]
	s_mov_b32 m0, s76
	s_nop 0
	global_load_lds_dwordx4 v[140:141], off
	s_waitcnt vmcnt(8)
	s_waitcnt lgkmcnt(0)
	s_barrier
	s_setprio 1
	s_waitcnt lgkmcnt(0)
	v_mfma_f32_16x16x32_bf16 v[126:129], v[136:139], v[174:177], 0
	v_mfma_f32_16x16x32_bf16 v[122:125], v[150:153], v[174:177], 0
	v_mfma_f32_16x16x32_bf16 v[108:111], v[136:139], v[182:185], 0
	v_mfma_f32_16x16x32_bf16 v[104:107], v[150:153], v[182:185], 0
	v_mfma_f32_16x16x32_bf16 v[92:95], v[136:139], v[202:205], 0
	v_mfma_f32_16x16x32_bf16 v[88:91], v[150:153], v[202:205], 0
	v_mfma_f32_16x16x32_bf16 v[76:79], v[136:139], v[210:213], 0
	v_mfma_f32_16x16x32_bf16 v[72:75], v[150:153], v[210:213], 0
	v_mfma_f32_16x16x32_bf16 v[126:129], v[146:149], v[178:181], v[126:129]
	v_mfma_f32_16x16x32_bf16 v[122:125], v[154:157], v[178:181], v[122:125]
	v_mfma_f32_16x16x32_bf16 v[108:111], v[146:149], v[198:201], v[108:111]
	v_mfma_f32_16x16x32_bf16 v[104:107], v[154:157], v[198:201], v[104:107]
	v_mfma_f32_16x16x32_bf16 v[92:95], v[146:149], v[206:209], v[92:95]
	v_mfma_f32_16x16x32_bf16 v[88:91], v[154:157], v[206:209], v[88:91]
	v_mfma_f32_16x16x32_bf16 v[76:79], v[146:149], v[214:217], v[76:79]
	v_mfma_f32_16x16x32_bf16 v[72:75], v[154:157], v[214:217], v[72:75]
	s_setprio 0
	s_setprio 1
	v_mfma_f32_16x16x32_bf16 v[118:121], v[158:161], v[174:177], 0
	v_mfma_f32_16x16x32_bf16 v[114:117], v[166:169], v[174:177], 0
	v_mfma_f32_16x16x32_bf16 v[100:103], v[158:161], v[182:185], 0
	v_mfma_f32_16x16x32_bf16 v[96:99], v[166:169], v[182:185], 0
	v_mfma_f32_16x16x32_bf16 v[84:87], v[158:161], v[202:205], 0
	v_mfma_f32_16x16x32_bf16 v[80:83], v[166:169], v[202:205], 0
	v_mfma_f32_16x16x32_bf16 v[68:71], v[158:161], v[210:213], 0
	v_mfma_f32_16x16x32_bf16 v[64:67], v[166:169], v[210:213], 0
	v_mfma_f32_16x16x32_bf16 v[118:121], v[162:165], v[178:181], v[118:121]
	v_mfma_f32_16x16x32_bf16 v[114:117], v[170:173], v[178:181], v[114:117]
	v_mfma_f32_16x16x32_bf16 v[100:103], v[162:165], v[198:201], v[100:103]
	v_mfma_f32_16x16x32_bf16 v[96:99], v[170:173], v[198:201], v[96:99]
	v_mfma_f32_16x16x32_bf16 v[84:87], v[162:165], v[206:209], v[84:87]
	v_mfma_f32_16x16x32_bf16 v[80:83], v[170:173], v[206:209], v[80:83]
	v_mfma_f32_16x16x32_bf16 v[68:71], v[162:165], v[214:217], v[68:71]
	v_mfma_f32_16x16x32_bf16 v[64:67], v[170:173], v[214:217], v[64:67]
	s_setprio 0
	s_barrier
	s_mov_b32 m0, s75
	v_lshl_add_u64 v[140:141], s[72:73], 0, v[112:113]
	ds_read_b128 v[174:177], v145 offset:16384
	ds_read_b128 v[178:181], v145 offset:17408
	ds_read_b128 v[182:185], v145 offset:18432
	ds_read_b128 v[198:201], v145 offset:19456
	ds_read_b128 v[202:205], v145 offset:20480
	ds_read_b128 v[206:209], v145 offset:21504
	ds_read_b128 v[210:213], v145 offset:22528
	ds_read_b128 v[214:217], v145 offset:23552
	global_load_lds_dwordx4 v[140:141], off
	v_lshl_add_u64 v[194:195], s[72:73], 0, v[134:135]
	s_mov_b32 m0, s64
	v_lshl_add_u64 v[196:197], vcc, 0, v[112:113]
	global_load_lds_dwordx4 v[194:195], off
	s_mov_b32 m0, s13
	v_lshl_add_u64 v[218:219], s[62:63], 0, v[132:133]
	global_load_lds_dwordx4 v[196:197], off
	v_lshl_add_u64 v[196:197], vcc, 0, v[134:135]
	s_mov_b32 m0, s12
	s_nop 0
	global_load_lds_dwordx4 v[196:197], off
	v_lshl_add_u64 v[196:197], s[62:63], 0, v[130:131]
	s_mov_b32 m0, s69
	s_nop 0
	global_load_lds_dwordx4 v[196:197], off
	s_mov_b32 m0, s70
	s_nop 0
	global_load_lds_dwordx4 v[218:219], off
	s_waitcnt vmcnt(8)
	s_waitcnt lgkmcnt(0)
	s_barrier
	s_setprio 1
	s_waitcnt lgkmcnt(0)
	v_mfma_f32_16x16x32_bf16 v[60:63], v[136:139], v[174:177], 0
	v_mfma_f32_16x16x32_bf16 v[56:59], v[150:153], v[174:177], 0
	v_mfma_f32_16x16x32_bf16 v[44:47], v[136:139], v[182:185], 0
	v_mfma_f32_16x16x32_bf16 v[40:43], v[150:153], v[182:185], 0
	v_mfma_f32_16x16x32_bf16 v[28:31], v[136:139], v[202:205], 0
	v_mfma_f32_16x16x32_bf16 v[24:27], v[150:153], v[202:205], 0
	v_mfma_f32_16x16x32_bf16 v[12:15], v[136:139], v[210:213], 0
	v_mfma_f32_16x16x32_bf16 v[8:11], v[150:153], v[210:213], 0
	v_mfma_f32_16x16x32_bf16 v[60:63], v[146:149], v[178:181], v[60:63]
	v_mfma_f32_16x16x32_bf16 v[56:59], v[154:157], v[178:181], v[56:59]
	v_mfma_f32_16x16x32_bf16 v[44:47], v[146:149], v[198:201], v[44:47]
	v_mfma_f32_16x16x32_bf16 v[40:43], v[154:157], v[198:201], v[40:43]
	v_mfma_f32_16x16x32_bf16 v[28:31], v[146:149], v[206:209], v[28:31]
	v_mfma_f32_16x16x32_bf16 v[24:27], v[154:157], v[206:209], v[24:27]
	v_mfma_f32_16x16x32_bf16 v[12:15], v[146:149], v[214:217], v[12:15]
	v_mfma_f32_16x16x32_bf16 v[8:11], v[154:157], v[214:217], v[8:11]
	s_setprio 0
	s_setprio 1
	v_mfma_f32_16x16x32_bf16 v[52:55], v[158:161], v[174:177], 0
	v_mfma_f32_16x16x32_bf16 v[48:51], v[166:169], v[174:177], 0
	v_mfma_f32_16x16x32_bf16 v[36:39], v[158:161], v[182:185], 0
	v_mfma_f32_16x16x32_bf16 v[32:35], v[166:169], v[182:185], 0
	v_mfma_f32_16x16x32_bf16 v[20:23], v[158:161], v[202:205], 0
	v_mfma_f32_16x16x32_bf16 v[16:19], v[166:169], v[202:205], 0
	v_mfma_f32_16x16x32_bf16 v[4:7], v[158:161], v[210:213], 0
	v_mfma_f32_16x16x32_bf16 v[0:3], v[166:169], v[210:213], 0
	v_mfma_f32_16x16x32_bf16 v[52:55], v[162:165], v[178:181], v[52:55]
	v_mfma_f32_16x16x32_bf16 v[48:51], v[170:173], v[178:181], v[48:51]
	v_mfma_f32_16x16x32_bf16 v[36:39], v[162:165], v[198:201], v[36:39]
	v_mfma_f32_16x16x32_bf16 v[32:35], v[170:173], v[198:201], v[32:35]
	v_mfma_f32_16x16x32_bf16 v[20:23], v[162:165], v[206:209], v[20:23]
	v_mfma_f32_16x16x32_bf16 v[16:19], v[170:173], v[206:209], v[16:19]
	v_mfma_f32_16x16x32_bf16 v[4:7], v[162:165], v[214:217], v[4:7]
	v_mfma_f32_16x16x32_bf16 v[0:3], v[170:173], v[214:217], v[0:3]
	s_setprio 0
	s_barrier
	v_add_u32_e32 v154, s94, v143
	v_add_u32_e32 v170, s95, v143
	ds_read_b128 v[136:139], v154
	ds_read_b128 v[146:149], v154 offset:1024
	ds_read_b128 v[150:153], v154 offset:2048
	ds_read_b128 v[154:157], v154 offset:3072
	ds_read_b128 v[158:161], v170
	ds_read_b128 v[162:165], v170 offset:1024
	ds_read_b128 v[166:169], v170 offset:2048
	ds_read_b128 v[170:173], v170 offset:3072
	s_mov_b32 m0, s71
	v_lshl_add_u64 v[220:221], s[50:51], 0, v[130:131]
	ds_read_b128 v[174:177], v145 offset:32768
	ds_read_b128 v[178:181], v145 offset:33792
	ds_read_b128 v[182:185], v145 offset:34816
	ds_read_b128 v[198:201], v145 offset:35840
	ds_read_b128 v[202:205], v145 offset:36864
	ds_read_b128 v[206:209], v145 offset:37888
	ds_read_b128 v[210:213], v145 offset:38912
	ds_read_b128 v[214:217], v145 offset:39936
	global_load_lds_dwordx4 v[220:221], off
	v_lshl_add_u64 v[220:221], s[50:51], 0, v[132:133]
	s_mov_b32 m0, s82
	s_nop 0
	global_load_lds_dwordx4 v[220:221], off
	s_waitcnt vmcnt(8)
	s_waitcnt lgkmcnt(0)
	s_barrier
	s_setprio 1
	s_waitcnt lgkmcnt(0)
	v_mfma_f32_16x16x32_bf16 v[126:129], v[136:139], v[174:177], v[126:129]
	v_mfma_f32_16x16x32_bf16 v[122:125], v[150:153], v[174:177], v[122:125]
	v_mfma_f32_16x16x32_bf16 v[108:111], v[136:139], v[182:185], v[108:111]
	v_mfma_f32_16x16x32_bf16 v[104:107], v[150:153], v[182:185], v[104:107]
	v_mfma_f32_16x16x32_bf16 v[92:95], v[136:139], v[202:205], v[92:95]
	v_mfma_f32_16x16x32_bf16 v[88:91], v[150:153], v[202:205], v[88:91]
	v_mfma_f32_16x16x32_bf16 v[76:79], v[136:139], v[210:213], v[76:79]
	v_mfma_f32_16x16x32_bf16 v[72:75], v[150:153], v[210:213], v[72:75]
	v_mfma_f32_16x16x32_bf16 v[126:129], v[146:149], v[178:181], v[126:129]
	v_mfma_f32_16x16x32_bf16 v[122:125], v[154:157], v[178:181], v[122:125]
	v_mfma_f32_16x16x32_bf16 v[108:111], v[146:149], v[198:201], v[108:111]
	v_mfma_f32_16x16x32_bf16 v[104:107], v[154:157], v[198:201], v[104:107]
	v_mfma_f32_16x16x32_bf16 v[92:95], v[146:149], v[206:209], v[92:95]
	v_mfma_f32_16x16x32_bf16 v[88:91], v[154:157], v[206:209], v[88:91]
	v_mfma_f32_16x16x32_bf16 v[76:79], v[146:149], v[214:217], v[76:79]
	v_mfma_f32_16x16x32_bf16 v[72:75], v[154:157], v[214:217], v[72:75]
	s_setprio 0
	s_setprio 1
	v_mfma_f32_16x16x32_bf16 v[118:121], v[158:161], v[174:177], v[118:121]
	v_mfma_f32_16x16x32_bf16 v[114:117], v[166:169], v[174:177], v[114:117]
	v_mfma_f32_16x16x32_bf16 v[100:103], v[158:161], v[182:185], v[100:103]
	v_mfma_f32_16x16x32_bf16 v[96:99], v[166:169], v[182:185], v[96:99]
	v_mfma_f32_16x16x32_bf16 v[84:87], v[158:161], v[202:205], v[84:87]
	v_mfma_f32_16x16x32_bf16 v[80:83], v[166:169], v[202:205], v[80:83]
	v_mfma_f32_16x16x32_bf16 v[68:71], v[158:161], v[210:213], v[68:71]
	v_mfma_f32_16x16x32_bf16 v[64:67], v[166:169], v[210:213], v[64:67]
	v_mfma_f32_16x16x32_bf16 v[118:121], v[162:165], v[178:181], v[118:121]
	v_mfma_f32_16x16x32_bf16 v[114:117], v[170:173], v[178:181], v[114:117]
	v_mfma_f32_16x16x32_bf16 v[100:103], v[162:165], v[198:201], v[100:103]
	v_mfma_f32_16x16x32_bf16 v[96:99], v[170:173], v[198:201], v[96:99]
	v_mfma_f32_16x16x32_bf16 v[84:87], v[162:165], v[206:209], v[84:87]
	v_mfma_f32_16x16x32_bf16 v[80:83], v[170:173], v[206:209], v[80:83]
	v_mfma_f32_16x16x32_bf16 v[68:71], v[162:165], v[214:217], v[68:71]
	v_mfma_f32_16x16x32_bf16 v[64:67], v[170:173], v[214:217], v[64:67]
	s_setprio 0
	s_barrier
	s_mov_b32 m0, s25
	v_lshl_add_u64 v[140:141], v[140:141], 0, s[60:61]
	ds_read_b128 v[174:177], v145 offset:49152
	ds_read_b128 v[178:181], v145 offset:50176
	ds_read_b128 v[182:185], v145 offset:51200
	ds_read_b128 v[198:201], v145 offset:52224
	ds_read_b128 v[202:205], v145 offset:53248
	ds_read_b128 v[206:209], v145 offset:54272
	ds_read_b128 v[210:213], v145 offset:55296
	ds_read_b128 v[214:217], v145 offset:56320
	global_load_lds_dwordx4 v[140:141], off
	v_lshl_add_u64 v[140:141], v[194:195], 0, s[60:61]
	s_mov_b32 m0, s87
	s_nop 0
	global_load_lds_dwordx4 v[140:141], off
	v_lshl_add_u64 v[140:141], s[44:45], 0, v[112:113]
	s_mov_b32 m0, s90
	s_nop 0
	global_load_lds_dwordx4 v[140:141], off
	v_lshl_add_u64 v[140:141], s[44:45], 0, v[134:135]
	s_mov_b32 m0, s24
	s_nop 0
	global_load_lds_dwordx4 v[140:141], off
	v_lshl_add_u64 v[140:141], v[196:197], 0, s[60:61]
	s_mov_b32 m0, s83
	s_nop 0
	global_load_lds_dwordx4 v[140:141], off
	v_lshl_add_u64 v[140:141], v[218:219], 0, s[60:61]
	s_mov_b32 m0, s84
	s_nop 0
	global_load_lds_dwordx4 v[140:141], off
	s_waitcnt vmcnt(8)
	s_waitcnt lgkmcnt(0)
	s_barrier
	s_setprio 1
	s_waitcnt lgkmcnt(0)
	v_mfma_f32_16x16x32_bf16 v[60:63], v[136:139], v[174:177], v[60:63]
	v_mfma_f32_16x16x32_bf16 v[56:59], v[150:153], v[174:177], v[56:59]
	v_mfma_f32_16x16x32_bf16 v[44:47], v[136:139], v[182:185], v[44:47]
	v_mfma_f32_16x16x32_bf16 v[40:43], v[150:153], v[182:185], v[40:43]
	v_mfma_f32_16x16x32_bf16 v[28:31], v[136:139], v[202:205], v[28:31]
	v_mfma_f32_16x16x32_bf16 v[24:27], v[150:153], v[202:205], v[24:27]
	v_mfma_f32_16x16x32_bf16 v[12:15], v[136:139], v[210:213], v[12:15]
	v_mfma_f32_16x16x32_bf16 v[8:11], v[150:153], v[210:213], v[8:11]
	v_mfma_f32_16x16x32_bf16 v[60:63], v[146:149], v[178:181], v[60:63]
	v_mfma_f32_16x16x32_bf16 v[56:59], v[154:157], v[178:181], v[56:59]
	v_mfma_f32_16x16x32_bf16 v[44:47], v[146:149], v[198:201], v[44:47]
	v_mfma_f32_16x16x32_bf16 v[40:43], v[154:157], v[198:201], v[40:43]
	v_mfma_f32_16x16x32_bf16 v[28:31], v[146:149], v[206:209], v[28:31]
	v_mfma_f32_16x16x32_bf16 v[24:27], v[154:157], v[206:209], v[24:27]
	v_mfma_f32_16x16x32_bf16 v[12:15], v[146:149], v[214:217], v[12:15]
	v_mfma_f32_16x16x32_bf16 v[8:11], v[154:157], v[214:217], v[8:11]
	s_setprio 0
	s_setprio 1
	v_mfma_f32_16x16x32_bf16 v[52:55], v[158:161], v[174:177], v[52:55]
	v_mfma_f32_16x16x32_bf16 v[48:51], v[166:169], v[174:177], v[48:51]
	v_mfma_f32_16x16x32_bf16 v[36:39], v[158:161], v[182:185], v[36:39]
	v_mfma_f32_16x16x32_bf16 v[32:35], v[166:169], v[182:185], v[32:35]
	v_mfma_f32_16x16x32_bf16 v[20:23], v[158:161], v[202:205], v[20:23]
	v_mfma_f32_16x16x32_bf16 v[16:19], v[166:169], v[202:205], v[16:19]
	v_mfma_f32_16x16x32_bf16 v[4:7], v[158:161], v[210:213], v[4:7]
	v_mfma_f32_16x16x32_bf16 v[0:3], v[166:169], v[210:213], v[0:3]
	v_mfma_f32_16x16x32_bf16 v[52:55], v[162:165], v[178:181], v[52:55]
	v_mfma_f32_16x16x32_bf16 v[48:51], v[170:173], v[178:181], v[48:51]
	v_mfma_f32_16x16x32_bf16 v[36:39], v[162:165], v[198:201], v[36:39]
	v_mfma_f32_16x16x32_bf16 v[32:35], v[170:173], v[198:201], v[32:35]
	v_mfma_f32_16x16x32_bf16 v[20:23], v[162:165], v[206:209], v[20:23]
	v_mfma_f32_16x16x32_bf16 v[16:19], v[170:173], v[206:209], v[16:19]
	v_mfma_f32_16x16x32_bf16 v[4:7], v[162:165], v[214:217], v[4:7]
	v_mfma_f32_16x16x32_bf16 v[0:3], v[170:173], v[214:217], v[0:3]
	s_setprio 0
	s_barrier
	s_movk_i32 s24, 0x100
	s_andn2_b64 vcc, exec, s[42:43]
	s_mov_b64 s[44:45], -1
	s_mov_b64 s[42:43], 0
	s_cbranch_vccz .LBB0_781
	s_branch .Lpeel_after_5
	.p2alignl 6, 3212836864

.LBB0_828:
	s_ashr_i32 s19, s18, 31
	s_lshl_b64 s[20:21], s[18:19], 17
	s_add_u32 s20, s25, s20
	s_addc_u32 s21, s38, s21
	s_and_b64 s[22:23], s[4:5], exec
	s_cselect_b32 s19, s21, s35
	s_cselect_b32 s90, s20, s34
	s_ashr_i32 s17, s16, 31
	s_lshl_b64 s[22:23], s[16:17], 19
	s_add_u32 s22, s39, s22
	s_addc_u32 s23, s47, s23
	s_and_b64 s[36:37], s[4:5], exec
	s_cselect_b32 s17, s23, s31
	s_cselect_b32 s94, s22, s30
	s_mov_b64 s[42:43], 0
	s_mov_b64 s[36:37], -1
	s_mov_b64 s[40:41], 0
	s_add_u32 s57, s34, s42
	s_addc_u32 s59, s35, s43
	s_add_u32 s50, s57, 0x100
	s_addc_u32 s51, s59, 0
	s_and_b64 s[44:45], s[40:41], exec
	s_cselect_b32 s45, s19, s51
	s_cselect_b32 s44, s90, s50
	s_add_u32 s42, s30, s42
	s_addc_u32 s43, s31, s43
	s_add_u32 s42, s42, 0x100
	s_addc_u32 s43, s43, 0
	s_add_i32 s64, 0, 0x10000
	s_and_b64 s[40:41], s[40:41], exec
	s_cselect_b32 s51, s17, s43
	s_cselect_b32 s50, s94, s42
	s_add_i32 s93, 0, 0x14000
	s_add_u32 s72, s57, 0x10080
	s_addc_u32 s73, s59, 0
	s_add_i32 s57, s64, s55
	s_add_i32 m0, s56, 0xc000
	s_add_i32 s59, s56, 0xe000
	s_add_i32 s76, s57, 0x2000
	v_add_u32_e32 v112, s64, v173
	s_add_u32 s62, s50, 0x40000
	ds_read_b128 v[130:133], v112
	ds_read_b128 v[134:137], v112 offset:1024
	ds_read_b128 v[138:141], v112 offset:2048
	ds_read_b128 v[142:145], v112 offset:3072
	v_add_u32_e32 v112, s93, v173
	s_addc_u32 s63, s51, 0
	s_add_i32 s75, s93, s55
	ds_read_b128 v[146:149], v112
	ds_read_b128 v[150:153], v112 offset:1024
	ds_read_b128 v[154:157], v112 offset:2048
	ds_read_b128 v[158:161], v112 offset:3072
	s_add_i32 s3, s75, 0x2000
	s_add_i32 s87, 0, 0x18000
	s_add_i32 vcc_hi, 0, 0x1c000
	s_add_u32 s42, s44, 0x10000
	s_addc_u32 s43, s45, 0
	s_add_i32 vcc_lo, s87, s55
	s_add_i32 s96, vcc_lo, 0x2000
	s_add_u32 s40, s50, 0x40080
	s_addc_u32 s41, s51, 0
	s_add_i32 s97, vcc_hi, s55
	s_add_i32 s95, s97, 0x2000
	v_lshl_add_u64 v[194:195], s[72:73], 0, v[168:169]
	ds_read_b128 v[178:181], v175
	ds_read_b128 v[182:185], v175 offset:1024
	ds_read_b128 v[198:201], v175 offset:2048
	ds_read_b128 v[202:205], v175 offset:3072
	ds_read_b128 v[206:209], v175 offset:4096
	ds_read_b128 v[210:213], v175 offset:5120
	ds_read_b128 v[214:217], v175 offset:6144
	ds_read_b128 v[218:221], v175 offset:7168
	global_load_lds_dwordx4 v[194:195], off
	v_lshl_add_u64 v[194:195], s[72:73], 0, v[164:165]
	s_mov_b32 m0, s59
	s_nop 0
	global_load_lds_dwordx4 v[194:195], off
	s_waitcnt vmcnt(8)
	s_waitcnt lgkmcnt(0)
	s_barrier
	s_setprio 1
	s_waitcnt lgkmcnt(0)
	v_mfma_f32_16x16x32_bf16 v[126:129], v[130:133], v[178:181], 0
	v_mfma_f32_16x16x32_bf16 v[122:125], v[138:141], v[178:181], 0
	v_mfma_f32_16x16x32_bf16 v[118:121], v[130:133], v[198:201], 0
	v_mfma_f32_16x16x32_bf16 v[114:117], v[138:141], v[198:201], 0
	v_mfma_f32_16x16x32_bf16 v[108:111], v[130:133], v[206:209], 0
	v_mfma_f32_16x16x32_bf16 v[104:107], v[138:141], v[206:209], 0
	v_mfma_f32_16x16x32_bf16 v[100:103], v[130:133], v[214:217], 0
	v_mfma_f32_16x16x32_bf16 v[96:99], v[138:141], v[214:217], 0
	v_mfma_f32_16x16x32_bf16 v[126:129], v[134:137], v[182:185], v[126:129]
	v_mfma_f32_16x16x32_bf16 v[122:125], v[142:145], v[182:185], v[122:125]
	v_mfma_f32_16x16x32_bf16 v[118:121], v[134:137], v[202:205], v[118:121]
	v_mfma_f32_16x16x32_bf16 v[114:117], v[142:145], v[202:205], v[114:117]
	v_mfma_f32_16x16x32_bf16 v[108:111], v[134:137], v[210:213], v[108:111]
	v_mfma_f32_16x16x32_bf16 v[104:107], v[142:145], v[210:213], v[104:107]
	v_mfma_f32_16x16x32_bf16 v[100:103], v[134:137], v[218:221], v[100:103]
	v_mfma_f32_16x16x32_bf16 v[96:99], v[142:145], v[218:221], v[96:99]
	s_setprio 0
	s_setprio 1
	v_mfma_f32_16x16x32_bf16 v[60:63], v[146:149], v[178:181], 0
	v_mfma_f32_16x16x32_bf16 v[56:59], v[154:157], v[178:181], 0
	v_mfma_f32_16x16x32_bf16 v[52:55], v[146:149], v[198:201], 0
	v_mfma_f32_16x16x32_bf16 v[48:51], v[154:157], v[198:201], 0
	v_mfma_f32_16x16x32_bf16 v[44:47], v[146:149], v[206:209], 0
	v_mfma_f32_16x16x32_bf16 v[40:43], v[154:157], v[206:209], 0
	v_mfma_f32_16x16x32_bf16 v[36:39], v[146:149], v[214:217], 0
	v_mfma_f32_16x16x32_bf16 v[32:35], v[154:157], v[214:217], 0
	v_mfma_f32_16x16x32_bf16 v[60:63], v[150:153], v[182:185], v[60:63]
	v_mfma_f32_16x16x32_bf16 v[56:59], v[158:161], v[182:185], v[56:59]
	v_mfma_f32_16x16x32_bf16 v[52:55], v[150:153], v[202:205], v[52:55]
	v_mfma_f32_16x16x32_bf16 v[48:51], v[158:161], v[202:205], v[48:51]
	v_mfma_f32_16x16x32_bf16 v[44:47], v[150:153], v[210:213], v[44:47]
	v_mfma_f32_16x16x32_bf16 v[40:43], v[158:161], v[210:213], v[40:43]
	v_mfma_f32_16x16x32_bf16 v[36:39], v[150:153], v[218:221], v[36:39]
	v_mfma_f32_16x16x32_bf16 v[32:35], v[158:161], v[218:221], v[32:35]
	s_setprio 0
	s_barrier
	s_mov_b32 m0, s57
	v_lshl_add_u64 v[194:195], s[50:51], 0, v[166:167]
	ds_read_b128 v[178:181], v175 offset:16384
	ds_read_b128 v[182:185], v175 offset:17408
	ds_read_b128 v[198:201], v175 offset:18432
	ds_read_b128 v[202:205], v175 offset:19456
	ds_read_b128 v[206:209], v175 offset:20480
	ds_read_b128 v[210:213], v175 offset:21504
	ds_read_b128 v[214:217], v175 offset:22528
	ds_read_b128 v[218:221], v175 offset:23552
	global_load_lds_dwordx4 v[194:195], off
	v_lshl_add_u64 v[196:197], s[50:51], 0, v[162:163]
	s_mov_b32 m0, s76
	v_lshl_add_u64 v[222:223], s[62:63], 0, v[166:167]
	global_load_lds_dwordx4 v[196:197], off
	s_mov_b32 m0, s75
	v_lshl_add_u64 v[234:235], s[44:45], 0, v[164:165]
	global_load_lds_dwordx4 v[222:223], off
	v_lshl_add_u64 v[222:223], s[62:63], 0, v[162:163]
	s_mov_b32 m0, s3
	s_nop 0
	global_load_lds_dwordx4 v[222:223], off
	v_lshl_add_u64 v[222:223], s[44:45], 0, v[168:169]
	s_mov_b32 m0, s56
	s_nop 0
	global_load_lds_dwordx4 v[222:223], off
	s_mov_b32 m0, s69
	s_nop 0
	global_load_lds_dwordx4 v[234:235], off
	s_waitcnt vmcnt(8)
	s_waitcnt lgkmcnt(0)
	s_barrier
	s_setprio 1
	s_waitcnt lgkmcnt(0)
	v_mfma_f32_16x16x32_bf16 v[92:95], v[130:133], v[178:181], 0
	v_mfma_f32_16x16x32_bf16 v[88:91], v[138:141], v[178:181], 0
	v_mfma_f32_16x16x32_bf16 v[84:87], v[130:133], v[198:201], 0
	v_mfma_f32_16x16x32_bf16 v[80:83], v[138:141], v[198:201], 0
	v_mfma_f32_16x16x32_bf16 v[76:79], v[130:133], v[206:209], 0
	v_mfma_f32_16x16x32_bf16 v[72:75], v[138:141], v[206:209], 0
	v_mfma_f32_16x16x32_bf16 v[68:71], v[130:133], v[214:217], 0
	v_mfma_f32_16x16x32_bf16 v[64:67], v[138:141], v[214:217], 0
	v_mfma_f32_16x16x32_bf16 v[92:95], v[134:137], v[182:185], v[92:95]
	v_mfma_f32_16x16x32_bf16 v[88:91], v[142:145], v[182:185], v[88:91]
	v_mfma_f32_16x16x32_bf16 v[84:87], v[134:137], v[202:205], v[84:87]
	v_mfma_f32_16x16x32_bf16 v[80:83], v[142:145], v[202:205], v[80:83]
	v_mfma_f32_16x16x32_bf16 v[76:79], v[134:137], v[210:213], v[76:79]
	v_mfma_f32_16x16x32_bf16 v[72:75], v[142:145], v[210:213], v[72:75]
	v_mfma_f32_16x16x32_bf16 v[68:71], v[134:137], v[218:221], v[68:71]
	v_mfma_f32_16x16x32_bf16 v[64:67], v[142:145], v[218:221], v[64:67]
	s_setprio 0
	s_setprio 1
	v_mfma_f32_16x16x32_bf16 v[28:31], v[146:149], v[178:181], 0
	v_mfma_f32_16x16x32_bf16 v[24:27], v[154:157], v[178:181], 0
	v_mfma_f32_16x16x32_bf16 v[20:23], v[146:149], v[198:201], 0
	v_mfma_f32_16x16x32_bf16 v[16:19], v[154:157], v[198:201], 0
	v_mfma_f32_16x16x32_bf16 v[12:15], v[146:149], v[206:209], 0
	v_mfma_f32_16x16x32_bf16 v[8:11], v[154:157], v[206:209], 0
	v_mfma_f32_16x16x32_bf16 v[4:7], v[146:149], v[214:217], 0
	v_mfma_f32_16x16x32_bf16 v[0:3], v[154:157], v[214:217], 0
	v_mfma_f32_16x16x32_bf16 v[28:31], v[150:153], v[182:185], v[28:31]
	v_mfma_f32_16x16x32_bf16 v[24:27], v[158:161], v[182:185], v[24:27]
	v_mfma_f32_16x16x32_bf16 v[20:23], v[150:153], v[202:205], v[20:23]
	v_mfma_f32_16x16x32_bf16 v[16:19], v[158:161], v[202:205], v[16:19]
	v_mfma_f32_16x16x32_bf16 v[12:15], v[150:153], v[210:213], v[12:15]
	v_mfma_f32_16x16x32_bf16 v[8:11], v[158:161], v[210:213], v[8:11]
	v_mfma_f32_16x16x32_bf16 v[4:7], v[150:153], v[218:221], v[4:7]
	v_mfma_f32_16x16x32_bf16 v[0:3], v[158:161], v[218:221], v[0:3]
	s_setprio 0
	s_barrier
	v_add_u32_e32 v112, s87, v173
	ds_read_b128 v[130:133], v112
	ds_read_b128 v[134:137], v112 offset:1024
	ds_read_b128 v[138:141], v112 offset:2048
	ds_read_b128 v[142:145], v112 offset:3072
	v_add_u32_e32 v112, vcc_hi, v173
	ds_read_b128 v[146:149], v112
	ds_read_b128 v[150:153], v112 offset:1024
	ds_read_b128 v[154:157], v112 offset:2048
	ds_read_b128 v[158:161], v112 offset:3072
	s_mov_b32 m0, s70
	v_lshl_add_u64 v[236:237], s[42:43], 0, v[168:169]
	ds_read_b128 v[178:181], v175 offset:32768
	ds_read_b128 v[182:185], v175 offset:33792
	ds_read_b128 v[198:201], v175 offset:34816
	ds_read_b128 v[202:205], v175 offset:35840
	ds_read_b128 v[206:209], v175 offset:36864
	ds_read_b128 v[210:213], v175 offset:37888
	ds_read_b128 v[214:217], v175 offset:38912
	ds_read_b128 v[218:221], v175 offset:39936
	global_load_lds_dwordx4 v[236:237], off
	v_lshl_add_u64 v[236:237], s[42:43], 0, v[164:165]
	s_mov_b32 m0, s71
	s_nop 0
	global_load_lds_dwordx4 v[236:237], off
	s_waitcnt vmcnt(8)
	s_waitcnt lgkmcnt(0)
	s_barrier
	s_setprio 1
	s_waitcnt lgkmcnt(0)
	v_mfma_f32_16x16x32_bf16 v[126:129], v[130:133], v[178:181], v[126:129]
	v_mfma_f32_16x16x32_bf16 v[122:125], v[138:141], v[178:181], v[122:125]
	v_mfma_f32_16x16x32_bf16 v[118:121], v[130:133], v[198:201], v[118:121]
	v_mfma_f32_16x16x32_bf16 v[114:117], v[138:141], v[198:201], v[114:117]
	v_mfma_f32_16x16x32_bf16 v[108:111], v[130:133], v[206:209], v[108:111]
	v_mfma_f32_16x16x32_bf16 v[104:107], v[138:141], v[206:209], v[104:107]
	v_mfma_f32_16x16x32_bf16 v[100:103], v[130:133], v[214:217], v[100:103]
	v_mfma_f32_16x16x32_bf16 v[96:99], v[138:141], v[214:217], v[96:99]
	v_mfma_f32_16x16x32_bf16 v[126:129], v[134:137], v[182:185], v[126:129]
	v_mfma_f32_16x16x32_bf16 v[122:125], v[142:145], v[182:185], v[122:125]
	v_mfma_f32_16x16x32_bf16 v[118:121], v[134:137], v[202:205], v[118:121]
	v_mfma_f32_16x16x32_bf16 v[114:117], v[142:145], v[202:205], v[114:117]
	v_mfma_f32_16x16x32_bf16 v[108:111], v[134:137], v[210:213], v[108:111]
	v_mfma_f32_16x16x32_bf16 v[104:107], v[142:145], v[210:213], v[104:107]
	v_mfma_f32_16x16x32_bf16 v[100:103], v[134:137], v[218:221], v[100:103]
	v_mfma_f32_16x16x32_bf16 v[96:99], v[142:145], v[218:221], v[96:99]
	s_setprio 0
	s_setprio 1
	v_mfma_f32_16x16x32_bf16 v[60:63], v[146:149], v[178:181], v[60:63]
	v_mfma_f32_16x16x32_bf16 v[56:59], v[154:157], v[178:181], v[56:59]
	v_mfma_f32_16x16x32_bf16 v[52:55], v[146:149], v[198:201], v[52:55]
	v_mfma_f32_16x16x32_bf16 v[48:51], v[154:157], v[198:201], v[48:51]
	v_mfma_f32_16x16x32_bf16 v[44:47], v[146:149], v[206:209], v[44:47]
	v_mfma_f32_16x16x32_bf16 v[40:43], v[154:157], v[206:209], v[40:43]
	v_mfma_f32_16x16x32_bf16 v[36:39], v[146:149], v[214:217], v[36:39]
	v_mfma_f32_16x16x32_bf16 v[32:35], v[154:157], v[214:217], v[32:35]
	v_mfma_f32_16x16x32_bf16 v[60:63], v[150:153], v[182:185], v[60:63]
	v_mfma_f32_16x16x32_bf16 v[56:59], v[158:161], v[182:185], v[56:59]
	v_mfma_f32_16x16x32_bf16 v[52:55], v[150:153], v[202:205], v[52:55]
	v_mfma_f32_16x16x32_bf16 v[48:51], v[158:161], v[202:205], v[48:51]
	v_mfma_f32_16x16x32_bf16 v[44:47], v[150:153], v[210:213], v[44:47]
	v_mfma_f32_16x16x32_bf16 v[40:43], v[158:161], v[210:213], v[40:43]
	v_mfma_f32_16x16x32_bf16 v[36:39], v[150:153], v[218:221], v[36:39]
	v_mfma_f32_16x16x32_bf16 v[32:35], v[158:161], v[218:221], v[32:35]
	s_setprio 0
	s_barrier
	s_mov_b32 m0, vcc_lo
	v_lshl_add_u64 v[194:195], v[194:195], 0, s[60:61]
	ds_read_b128 v[178:181], v175 offset:49152
	ds_read_b128 v[182:185], v175 offset:50176
	ds_read_b128 v[198:201], v175 offset:51200
	ds_read_b128 v[202:205], v175 offset:52224
	ds_read_b128 v[206:209], v175 offset:53248
	ds_read_b128 v[210:213], v175 offset:54272
	ds_read_b128 v[214:217], v175 offset:55296
	ds_read_b128 v[218:221], v175 offset:56320
	global_load_lds_dwordx4 v[194:195], off
	v_lshl_add_u64 v[194:195], v[196:197], 0, s[60:61]
	s_mov_b32 m0, s96
	s_nop 0
	global_load_lds_dwordx4 v[194:195], off
	v_lshl_add_u64 v[194:195], s[40:41], 0, v[166:167]
	s_mov_b32 m0, s97
	s_nop 0
	global_load_lds_dwordx4 v[194:195], off
	v_lshl_add_u64 v[194:195], s[40:41], 0, v[162:163]
	s_mov_b32 m0, s95
	s_nop 0
	global_load_lds_dwordx4 v[194:195], off
	v_lshl_add_u64 v[194:195], v[222:223], 0, s[60:61]
	s_mov_b32 m0, s84
	s_nop 0
	global_load_lds_dwordx4 v[194:195], off
	v_lshl_add_u64 v[194:195], v[234:235], 0, s[60:61]
	s_mov_b32 m0, s85
	s_nop 0
	global_load_lds_dwordx4 v[194:195], off
	s_waitcnt vmcnt(8)
	s_waitcnt lgkmcnt(0)
	s_barrier
	s_setprio 1
	s_waitcnt lgkmcnt(0)
	v_mfma_f32_16x16x32_bf16 v[92:95], v[130:133], v[178:181], v[92:95]
	v_mfma_f32_16x16x32_bf16 v[88:91], v[138:141], v[178:181], v[88:91]
	v_mfma_f32_16x16x32_bf16 v[84:87], v[130:133], v[198:201], v[84:87]
	v_mfma_f32_16x16x32_bf16 v[80:83], v[138:141], v[198:201], v[80:83]
	v_mfma_f32_16x16x32_bf16 v[76:79], v[130:133], v[206:209], v[76:79]
	v_mfma_f32_16x16x32_bf16 v[72:75], v[138:141], v[206:209], v[72:75]
	v_mfma_f32_16x16x32_bf16 v[68:71], v[130:133], v[214:217], v[68:71]
	v_mfma_f32_16x16x32_bf16 v[64:67], v[138:141], v[214:217], v[64:67]
	v_mfma_f32_16x16x32_bf16 v[92:95], v[134:137], v[182:185], v[92:95]
	v_mfma_f32_16x16x32_bf16 v[88:91], v[142:145], v[182:185], v[88:91]
	v_mfma_f32_16x16x32_bf16 v[84:87], v[134:137], v[202:205], v[84:87]
	v_mfma_f32_16x16x32_bf16 v[80:83], v[142:145], v[202:205], v[80:83]
	v_mfma_f32_16x16x32_bf16 v[76:79], v[134:137], v[210:213], v[76:79]
	v_mfma_f32_16x16x32_bf16 v[72:75], v[142:145], v[210:213], v[72:75]
	v_mfma_f32_16x16x32_bf16 v[68:71], v[134:137], v[218:221], v[68:71]
	v_mfma_f32_16x16x32_bf16 v[64:67], v[142:145], v[218:221], v[64:67]
	s_setprio 0
	s_setprio 1
	v_mfma_f32_16x16x32_bf16 v[28:31], v[146:149], v[178:181], v[28:31]
	v_mfma_f32_16x16x32_bf16 v[24:27], v[154:157], v[178:181], v[24:27]
	v_mfma_f32_16x16x32_bf16 v[20:23], v[146:149], v[198:201], v[20:23]
	v_mfma_f32_16x16x32_bf16 v[16:19], v[154:157], v[198:201], v[16:19]
	v_mfma_f32_16x16x32_bf16 v[12:15], v[146:149], v[206:209], v[12:15]
	v_mfma_f32_16x16x32_bf16 v[8:11], v[154:157], v[206:209], v[8:11]
	v_mfma_f32_16x16x32_bf16 v[4:7], v[146:149], v[214:217], v[4:7]
	v_mfma_f32_16x16x32_bf16 v[0:3], v[154:157], v[214:217], v[0:3]
	v_mfma_f32_16x16x32_bf16 v[28:31], v[150:153], v[182:185], v[28:31]
	v_mfma_f32_16x16x32_bf16 v[24:27], v[158:161], v[182:185], v[24:27]
	v_mfma_f32_16x16x32_bf16 v[20:23], v[150:153], v[202:205], v[20:23]
	v_mfma_f32_16x16x32_bf16 v[16:19], v[158:161], v[202:205], v[16:19]
	v_mfma_f32_16x16x32_bf16 v[12:15], v[150:153], v[210:213], v[12:15]
	v_mfma_f32_16x16x32_bf16 v[8:11], v[158:161], v[210:213], v[8:11]
	v_mfma_f32_16x16x32_bf16 v[4:7], v[150:153], v[218:221], v[4:7]
	v_mfma_f32_16x16x32_bf16 v[0:3], v[158:161], v[218:221], v[0:3]
	s_setprio 0
	s_barrier
	s_andn2_b64 vcc, exec, s[36:37]
	s_mov_b64 s[40:41], -1
	s_mov_b64 s[36:37], 0
	s_mov_b64 s[42:43], 0x100
	s_cbranch_vccz .LBB0_829
	s_branch .Lpeel_after_6
	.p2alignl 6, 3212836864

.LBB0_1047:
	s_or_b64 exec, exec, s[6:7]
	v_cndmask_b32_e64 v16, 0, v232, s[20:21]
	v_fmac_f32_e32 v16, 0xbf549a78, v140
	v_exp_f32_e32 v16, v16
	s_waitcnt vmcnt(13)
	v_cvt_f32_i32_e32 v65, v141
	v_cndmask_b32_e64 v17, 0, v231, s[20:21]
	v_mul_u32_u24_e32 v174, 0xd0, v154
	v_ldexp_f32 v16, v16, v17
	v_mul_f32_e32 v16, v16, v65
	v_cvt_f64_f32_e32 v[16:17], v16
	v_mul_f64 v[18:19], v[16:17], s[48:49]
	v_rndne_f64_e32 v[18:19], v[18:19]
	v_fma_f64 v[16:17], v[16:17], s[48:49], -v[18:19]
	v_cvt_f32_f64_e32 v17, v[16:17]
	v_sin_f32_e32 v16, v17
	v_cos_f32_e32 v18, v17
	v_cndmask_b32_e64 v17, 0, v232, s[18:19]
	v_fmac_f32_e32 v17, 0xbf549a78, v136
	v_exp_f32_e32 v17, v17
	v_cndmask_b32_e64 v19, 0, v231, s[18:19]
	v_mov_b32_e32 v179, 0
	s_mov_b32 s6, 0
	v_ldexp_f32 v17, v17, v19
	v_mul_f32_e32 v17, v17, v65
	v_cvt_f64_f32_e32 v[20:21], v17
	v_mul_f64 v[22:23], v[20:21], s[48:49]
	v_rndne_f64_e32 v[22:23], v[22:23]
	v_fma_f64 v[20:21], v[20:21], s[48:49], -v[22:23]
	v_cvt_f32_f64_e32 v19, v[20:21]
	v_cndmask_b32_e64 v20, 0, v232, s[16:17]
	v_fmac_f32_e32 v20, 0xbf549a78, v135
	v_exp_f32_e32 v20, v20
	v_cndmask_b32_e64 v21, 0, v231, s[16:17]
	v_sin_f32_e32 v17, v19
	v_cos_f32_e32 v19, v19
	v_ldexp_f32 v20, v20, v21
	v_mul_f32_e32 v20, v20, v65
	v_cvt_f64_f32_e32 v[20:21], v20
	v_mul_f64 v[22:23], v[20:21], s[48:49]
	v_rndne_f64_e32 v[22:23], v[22:23]
	v_fma_f64 v[20:21], v[20:21], s[48:49], -v[22:23]
	v_cvt_f32_f64_e32 v21, v[20:21]
	v_sin_f32_e32 v20, v21
	v_cos_f32_e32 v22, v21
	v_cndmask_b32_e64 v21, 0, v232, s[14:15]
	v_fmac_f32_e32 v21, 0xbf549a78, v134
	v_exp_f32_e32 v21, v21
	v_cndmask_b32_e64 v23, 0, v231, s[14:15]
	v_ldexp_f32 v21, v21, v23
	v_mul_f32_e32 v21, v21, v65
	v_cvt_f64_f32_e32 v[24:25], v21
	v_mul_f64 v[26:27], v[24:25], s[48:49]
	v_rndne_f64_e32 v[26:27], v[26:27]
	v_fma_f64 v[24:25], v[24:25], s[48:49], -v[26:27]
	v_cvt_f32_f64_e32 v23, v[24:25]
	v_cndmask_b32_e64 v24, 0, v232, s[12:13]
	v_fmac_f32_e32 v24, 0xbf549a78, v133
	v_exp_f32_e32 v24, v24
	v_cndmask_b32_e64 v25, 0, v231, s[12:13]
	v_sin_f32_e32 v21, v23
	v_cos_f32_e32 v23, v23
	v_ldexp_f32 v24, v24, v25
	v_mul_f32_e32 v24, v24, v65
	v_cvt_f64_f32_e32 v[24:25], v24
	v_mul_f64 v[26:27], v[24:25], s[48:49]
	v_rndne_f64_e32 v[26:27], v[26:27]
	v_fma_f64 v[24:25], v[24:25], s[48:49], -v[26:27]
	v_cvt_f32_f64_e32 v25, v[24:25]
	v_sin_f32_e32 v24, v25
	v_cos_f32_e32 v26, v25
	v_cndmask_b32_e64 v25, 0, v232, s[10:11]
	v_fmac_f32_e32 v25, 0xbf549a78, v132
	v_exp_f32_e32 v25, v25
	v_cndmask_b32_e64 v27, 0, v231, s[10:11]
	s_mov_b32 s11, 0xb000
	s_movk_i32 s10, 0x5800
	v_ldexp_f32 v25, v25, v27
	v_mul_f32_e32 v25, v25, v65
	v_cvt_f64_f32_e32 v[28:29], v25
	v_mul_f64 v[30:31], v[28:29], s[48:49]
	v_rndne_f64_e32 v[30:31], v[30:31]
	v_fma_f64 v[28:29], v[28:29], s[48:49], -v[30:31]
	v_cvt_f32_f64_e32 v27, v[28:29]
	v_cndmask_b32_e64 v28, 0, v232, s[8:9]
	v_fmac_f32_e32 v28, 0xbf549a78, v131
	v_exp_f32_e32 v28, v28
	v_cndmask_b32_e64 v29, 0, v231, s[8:9]
	v_sin_f32_e32 v25, v27
	v_cos_f32_e32 v27, v27
	v_ldexp_f32 v28, v28, v29
	v_mul_f32_e32 v28, v28, v65
	v_cvt_f64_f32_e32 v[28:29], v28
	v_mul_f64 v[30:31], v[28:29], s[48:49]
	v_rndne_f64_e32 v[30:31], v[30:31]
	v_fma_f64 v[28:29], v[28:29], s[48:49], -v[30:31]
	v_cvt_f32_f64_e32 v29, v[28:29]
	v_sin_f32_e32 v28, v29
	v_cos_f32_e32 v30, v29
	v_cndmask_b32_e32 v29, 0, v232, vcc
	v_fmac_f32_e32 v29, 0xbf549a78, v130
	v_exp_f32_e32 v29, v29
	v_cndmask_b32_e32 v31, 0, v231, vcc
	s_mov_b32 s12, -2
	v_ldexp_f32 v29, v29, v31
	v_mul_f32_e32 v29, v29, v65
	v_mul_f32_e32 v65, 0x4b800000, v64
	v_cndmask_b32_e64 v64, v64, v65, s[22:23]
	v_rsq_f32_e32 v64, v64
	v_cvt_f64_f32_e32 v[72:73], v29
	v_mul_f64 v[130:131], v[72:73], s[48:49]
	v_rndne_f64_e32 v[130:131], v[130:131]
	v_mul_f32_e32 v65, 0x45800000, v64
	v_fma_f64 v[72:73], v[72:73], s[48:49], -v[130:131]
	v_cndmask_b32_e64 v64, v64, v65, s[22:23]
	v_cvt_f32_f64_e32 v31, v[72:73]
	s_waitcnt vmcnt(10)
	v_pk_mul_f32 v[0:1], v[0:1], v[64:65] op_sel_hi:[1,0]
	v_sin_f32_e32 v29, v31
	v_pk_mul_f32 v[8:9], v[8:9], v[64:65] op_sel_hi:[1,0]
	v_pk_mul_f32 v[0:1], v[0:1], v[76:77]
	v_pk_mul_f32 v[2:3], v[2:3], v[64:65] op_sel_hi:[1,0]
	v_cos_f32_e32 v31, v31
	v_pk_mul_f32 v[8:9], v[8:9], v[74:75]
	v_pk_mul_f32 v[2:3], v[2:3], v[68:69]
	v_pk_mul_f32 v[68:69], v[0:1], v[26:27]
	v_pk_mul_f32 v[0:1], v[0:1], v[24:25]
	v_pk_mul_f32 v[10:11], v[10:11], v[64:65] op_sel_hi:[1,0]
	v_pk_fma_f32 v[0:1], v[8:9], v[26:27], v[0:1] neg_lo:[0,0,1] neg_hi:[0,0,1]
	s_waitcnt vmcnt(9)
	v_pk_mul_f32 v[4:5], v[4:5], v[64:65] op_sel_hi:[1,0]
	v_pk_mul_f32 v[0:1], v[0:1], s[80:81] op_sel_hi:[1,0]
	v_pk_mul_f32 v[12:13], v[12:13], v[64:65] op_sel_hi:[1,0]
	v_pk_mul_f32 v[10:11], v[10:11], v[70:71]
	v_pk_mul_f32 v[4:5], v[4:5], v[82:83]
	v_pk_mul_f32 v[6:7], v[6:7], v[64:65] op_sel_hi:[1,0]
	v_cvt_pk_bf16_f32 v144, v0, v1
	v_pk_mul_f32 v[0:1], v[2:3], v[28:29]
	s_waitcnt vmcnt(1)
	v_pk_mul_f32 v[60:61], v[60:61], v[64:65] op_sel_hi:[1,0]
	v_pk_mul_f32 v[62:63], v[62:63], v[64:65] op_sel_hi:[1,0]
	v_pk_mul_f32 v[56:57], v[56:57], v[64:65] op_sel_hi:[1,0]
	v_pk_mul_f32 v[58:59], v[58:59], v[64:65] op_sel_hi:[1,0]
	v_pk_mul_f32 v[52:53], v[52:53], v[64:65] op_sel_hi:[1,0]
	v_pk_mul_f32 v[54:55], v[54:55], v[64:65] op_sel_hi:[1,0]
	v_pk_mul_f32 v[48:49], v[48:49], v[64:65] op_sel_hi:[1,0]
	v_pk_mul_f32 v[50:51], v[50:51], v[64:65] op_sel_hi:[1,0]
	v_pk_mul_f32 v[44:45], v[44:45], v[64:65] op_sel_hi:[1,0]
	v_pk_mul_f32 v[46:47], v[46:47], v[64:65] op_sel_hi:[1,0]
	v_pk_mul_f32 v[40:41], v[40:41], v[64:65] op_sel_hi:[1,0]
	v_pk_mul_f32 v[42:43], v[42:43], v[64:65] op_sel_hi:[1,0]
	v_pk_mul_f32 v[36:37], v[36:37], v[64:65] op_sel_hi:[1,0]
	v_pk_mul_f32 v[38:39], v[38:39], v[64:65] op_sel_hi:[1,0]
	v_pk_mul_f32 v[32:33], v[32:33], v[64:65] op_sel_hi:[1,0]
	v_pk_mul_f32 v[34:35], v[34:35], v[64:65] op_sel_hi:[1,0]
	v_pk_mul_f32 v[12:13], v[12:13], v[84:85]
	v_pk_mul_f32 v[14:15], v[14:15], v[64:65] op_sel_hi:[1,0]
	v_pk_mul_f32 v[6:7], v[6:7], v[78:79]
	v_pk_mul_f32 v[64:65], v[4:5], v[18:19]
	v_pk_fma_f32 v[0:1], v[10:11], v[30:31], v[0:1] neg_lo:[0,0,1] neg_hi:[0,0,1]
	v_pk_mul_f32 v[62:63], v[62:63], v[66:67]
	v_pk_mul_f32 v[14:15], v[14:15], v[80:81]
	v_pk_fma_f32 v[64:65], v[12:13], v[16:17], v[64:65]
	v_pk_mul_f32 v[66:67], v[6:7], v[22:23]
	v_pk_mul_f32 v[0:1], v[0:1], s[80:81] op_sel_hi:[1,0]
	v_pk_fma_f32 v[66:67], v[14:15], v[20:21], v[66:67]
	v_cvt_pk_bf16_f32 v145, v0, v1
	v_pk_mul_f32 v[0:1], v[64:65], s[80:81] op_sel_hi:[1,0]
	v_pk_fma_f32 v[68:69], v[8:9], v[24:25], v[68:69]
	v_pk_mul_f32 v[70:71], v[2:3], v[30:31]
	v_cvt_pk_bf16_f32 v146, v0, v1
	v_pk_mul_f32 v[0:1], v[66:67], s[80:81] op_sel_hi:[1,0]
	v_pk_fma_f32 v[70:71], v[10:11], v[28:29], v[70:71]
	v_cvt_pk_bf16_f32 v147, v0, v1
	v_pk_mul_f32 v[0:1], v[68:69], s[80:81] op_sel_hi:[1,0]
	v_pk_mul_f32 v[4:5], v[4:5], v[16:17]
	v_cvt_pk_bf16_f32 v148, v0, v1
	v_pk_mul_f32 v[0:1], v[70:71], s[80:81] op_sel_hi:[1,0]
	v_pk_fma_f32 v[4:5], v[12:13], v[18:19], v[4:5] neg_lo:[0,0,1] neg_hi:[0,0,1]
	v_cvt_pk_bf16_f32 v149, v0, v1
	v_add_co_u32_e32 v0, vcc, s53, v164
	v_pk_mul_f32 v[4:5], v[4:5], s[80:81] op_sel_hi:[1,0]
	s_nop 0
	v_addc_co_u32_e32 v1, vcc, 0, v165, vcc
	global_load_dwordx4 v[150:153], v[0:1], off
	v_cvt_pk_bf16_f32 v142, v4, v5
	v_pk_mul_f32 v[4:5], v[6:7], v[20:21]
	v_pk_mul_f32 v[32:33], v[32:33], v[88:89]
	v_pk_fma_f32 v[4:5], v[14:15], v[22:23], v[4:5] neg_lo:[0,0,1] neg_hi:[0,0,1]
	v_pk_mul_f32 v[60:61], v[60:61], v[128:129]
	v_pk_mul_f32 v[56:57], v[56:57], v[126:127]
	v_pk_mul_f32 v[44:45], v[44:45], v[100:101]
	v_pk_mul_f32 v[40:41], v[40:41], v[96:97]
	v_pk_mul_f32 v[36:37], v[36:37], v[92:93]
	v_pk_mul_f32 v[34:35], v[34:35], v[86:87]
	v_pk_mul_f32 v[32:33], v[32:33], s[80:81] op_sel_hi:[1,0]
	v_pk_mul_f32 v[4:5], v[4:5], s[80:81] op_sel_hi:[1,0]
	v_add3_u32 v12, 0, v174, v112
	v_pk_mul_f32 v[58:59], v[58:59], v[110:111]
	v_pk_mul_f32 v[52:53], v[52:53], v[108:109]
	v_pk_mul_f32 v[48:49], v[48:49], v[104:105]
	v_pk_mul_f32 v[46:47], v[46:47], v[98:99]
	v_pk_mul_f32 v[42:43], v[42:43], v[94:95]
	v_pk_mul_f32 v[38:39], v[38:39], v[90:91]
	v_pk_mul_f32 v[60:61], v[60:61], s[80:81] op_sel_hi:[1,0]
	v_pk_mul_f32 v[56:57], v[56:57], s[80:81] op_sel_hi:[1,0]
	v_pk_mul_f32 v[44:45], v[44:45], s[80:81] op_sel_hi:[1,0]
	v_pk_mul_f32 v[40:41], v[40:41], s[80:81] op_sel_hi:[1,0]
	v_pk_mul_f32 v[36:37], v[36:37], s[80:81] op_sel_hi:[1,0]
	v_cvt_pk_bf16_f32 v140, v32, v33
	v_pk_mul_f32 v[32:33], v[34:35], s[80:81] op_sel_hi:[1,0]
	v_cvt_pk_bf16_f32 v143, v4, v5
	s_waitcnt lgkmcnt(0)
	s_barrier
	ds_read_b128 v[0:3], v12 offset:6656
	ds_read_b128 v[4:7], v12
	ds_read_b128 v[8:11], v12 offset:32
	v_pk_mul_f32 v[54:55], v[54:55], v[106:107]
	v_pk_mul_f32 v[50:51], v[50:51], v[102:103]
	v_cvt_pk_bf16_f32 v126, v60, v61
	v_pk_mul_f32 v[60:61], v[62:63], s[80:81] op_sel_hi:[1,0]
	v_cvt_pk_bf16_f32 v128, v56, v57
	v_pk_mul_f32 v[56:57], v[58:59], s[80:81] op_sel_hi:[1,0]
	v_pk_mul_f32 v[52:53], v[52:53], s[80:81] op_sel_hi:[1,0]
	v_pk_mul_f32 v[48:49], v[48:49], s[80:81] op_sel_hi:[1,0]
	v_cvt_pk_bf16_f32 v134, v44, v45
	v_pk_mul_f32 v[44:45], v[46:47], s[80:81] op_sel_hi:[1,0]
	v_cvt_pk_bf16_f32 v136, v40, v41
	v_pk_mul_f32 v[40:41], v[42:43], s[80:81] op_sel_hi:[1,0]
	v_cvt_pk_bf16_f32 v138, v36, v37
	v_pk_mul_f32 v[36:37], v[38:39], s[80:81] op_sel_hi:[1,0]
	v_cvt_pk_bf16_f32 v141, v32, v33
	v_xor_b32_e32 v32, 0x80000000, v176
	v_cvt_pk_bf16_f32 v127, v60, v61
	v_cvt_pk_bf16_f32 v129, v56, v57
	v_cvt_pk_bf16_f32 v130, v52, v53
	v_pk_mul_f32 v[52:53], v[54:55], s[80:81] op_sel_hi:[1,0]
	v_cvt_pk_bf16_f32 v132, v48, v49
	v_pk_mul_f32 v[48:49], v[50:51], s[80:81] op_sel_hi:[1,0]
	v_cvt_pk_bf16_f32 v135, v44, v45
	v_cvt_pk_bf16_f32 v137, v40, v41
	v_cvt_pk_bf16_f32 v139, v36, v37
	v_mov_b32_e32 v33, v32
	v_mov_b32_e32 v34, v32
	v_mov_b32_e32 v35, v32
	v_mov_b32_e32 v36, v32
	v_mov_b32_e32 v37, v32
	v_mov_b32_e32 v38, v32
	v_mov_b32_e32 v39, v32
	v_mov_b32_e32 v40, v32
	v_mov_b32_e32 v41, v32
	v_mov_b32_e32 v42, v32
	v_mov_b32_e32 v43, v32
	v_mov_b32_e32 v44, v32
	v_mov_b32_e32 v45, v32
	v_mov_b32_e32 v46, v32
	v_mov_b32_e32 v47, v32
	v_cvt_pk_bf16_f32 v131, v52, v53
	v_cvt_pk_bf16_f32 v133, v48, v49
	s_waitcnt lgkmcnt(2)
	v_mfma_f32_32x32x16_bf16 v[48:63], v[0:3], v[126:129], v[32:47]
	ds_read_b128 v[0:3], v12 offset:6688
	v_mul_u32_u24_e32 v176, 0x90, v154
	v_mov_b32_e32 v16, 0
	v_mov_b32_e32 v17, v179
	v_mov_b32_e32 v18, v179
	v_mov_b32_e32 v19, v179
	v_mov_b32_e32 v20, v179
	s_waitcnt lgkmcnt(2)
	v_mfma_f32_32x32x16_bf16 v[64:79], v[4:7], v[126:129], v[32:47]
	v_mov_b32_e32 v21, v179
	v_mov_b32_e32 v22, v179
	v_mov_b32_e32 v23, v179
	v_mov_b32_e32 v24, v179
	v_mov_b32_e32 v25, v179
	v_mov_b32_e32 v26, v179
	v_mov_b32_e32 v27, v179
	s_waitcnt lgkmcnt(1)
	v_mfma_f32_32x32x16_bf16 v[64:79], v[8:11], v[130:133], v[64:79]
	v_mov_b32_e32 v28, v179
	v_mov_b32_e32 v29, v179
	v_mov_b32_e32 v30, v179
	v_mov_b32_e32 v31, v179
	v_mov_b32_e32 v8, v179
	v_mov_b32_e32 v9, v179
	v_mov_b32_e32 v10, v179
	s_waitcnt lgkmcnt(0)
	v_mfma_f32_32x32x16_bf16 v[48:63], v[0:3], v[130:133], v[48:63]
	ds_read_b128 v[0:3], v12 offset:64
	ds_read_b128 v[4:7], v12 offset:6720
	v_mov_b32_e32 v11, v179
	v_mov_b32_e32 v13, v179
	v_mov_b32_e32 v14, v179
	v_mov_b32_e32 v15, v179
	s_waitcnt lgkmcnt(1)
	v_mfma_f32_32x32x16_bf16 v[64:79], v[0:3], v[134:137], v[64:79]
	s_waitcnt lgkmcnt(0)
	v_mfma_f32_32x32x16_bf16 v[48:63], v[4:7], v[134:137], v[48:63]
	ds_read_b128 v[0:3], v12 offset:96
	ds_read_b128 v[4:7], v12 offset:6752
	s_waitcnt lgkmcnt(1)
	v_mfma_f32_32x32x16_bf16 v[64:79], v[0:3], v[138:141], v[64:79]
	s_waitcnt lgkmcnt(0)
	v_mfma_f32_32x32x16_bf16 v[48:63], v[4:7], v[138:141], v[48:63]
	ds_read_b128 v[0:3], v12 offset:128
	ds_read_b128 v[4:7], v12 offset:6784
	s_waitcnt lgkmcnt(1)
	v_mfma_f32_32x32x16_bf16 v[64:79], v[0:3], v[142:145], v[64:79]
	s_waitcnt lgkmcnt(0)
	v_mfma_f32_32x32x16_bf16 v[48:63], v[4:7], v[142:145], v[48:63]
	ds_read_b128 v[0:3], v12 offset:160
	ds_read_b128 v[4:7], v12 offset:6816
	v_mov_b32_e32 v12, v179
	s_waitcnt lgkmcnt(1)
	v_mfma_f32_32x32x16_bf16 v[64:79], v[0:3], v[146:149], v[64:79]
	v_mov_b32_e32 v0, 0
	v_mov_b32_e32 v1, v179
	v_mov_b32_e32 v2, v179
	v_mov_b32_e32 v3, v179
	s_waitcnt lgkmcnt(0)
	v_mfma_f32_32x32x16_bf16 v[48:63], v[4:7], v[146:149], v[48:63]
	v_mov_b32_e32 v4, v179
	v_mov_b32_e32 v5, v179
	v_mov_b32_e32 v6, v179
	v_mov_b32_e32 v7, v179
	v_mov_b32_e32 v214, 0
	v_mov_b32_e32 v215, 0
	v_mov_b32_e32 v216, 0
	v_mov_b32_e32 v217, 0
	v_mov_b32_e32 v218, 0
	v_mov_b32_e32 v194, 0
	v_mov_b32_e32 v195, 0
	v_mov_b32_e32 v196, 0
	v_mov_b32_e32 v197, 0
	v_mov_b32_e32 v198, 0
	v_mov_b32_e32 v199, 0
	v_mov_b32_e32 v200, 0
	v_mov_b32_e32 v201, 0
	.p2alignl 6, 3212836864

.LBB0_1385:
	s_ashr_i32 s31, s30, 31
	s_lshl_b64 s[24:25], s[30:31], 19
	s_add_u32 s34, s38, s24
	s_addc_u32 s35, s39, s25
	s_and_b64 s[24:25], s[6:7], exec
	s_cselect_b32 s24, s35, s45
	s_cselect_b32 s25, s34, s44
	s_ashr_i32 s23, s22, 31
	s_lshl_b64 s[36:37], s[22:23], 19
	s_add_u32 s36, s47, s36
	s_addc_u32 s37, s55, s37
	s_and_b64 s[56:57], s[6:7], exec
	s_cselect_b32 s23, s37, s51
	s_cselect_b32 s31, s36, s50
	s_add_u32 s44, s44, 0x40080
	s_addc_u32 s45, s45, 0
	s_add_u32 s41, s50, 0x100
	s_addc_u32 s84, s51, 0
	s_mov_b32 s85, -2
	s_waitcnt lgkmcnt(0)
	s_add_u32 s3, s44, 0xfffc0080
	s_addc_u32 s50, s45, -1
	s_add_i32 s56, 0, 0x10000
	s_cmp_eq_u32 s85, 12
	s_cselect_b32 s63, s24, s50
	s_cselect_b32 s62, s25, s3
	s_cselect_b32 s51, s23, s84
	s_cselect_b32 s50, s31, s41
	s_add_i32 s3, 0, 0x14000
	v_add_u32_e32 v142, s56, v213
	v_add_u32_e32 v158, s3, v213
	ds_read_b128 v[130:133], v142
	ds_read_b128 v[134:137], v142 offset:1024
	ds_read_b128 v[138:141], v142 offset:2048
	ds_read_b128 v[142:145], v142 offset:3072
	ds_read_b128 v[146:149], v158
	ds_read_b128 v[150:153], v158 offset:1024
	ds_read_b128 v[154:157], v158 offset:2048
	ds_read_b128 v[158:161], v158 offset:3072
	v_lshl_add_u64 v[216:217], s[44:45], 0, v[184:185]
	s_add_i32 m0, s43, 0xc000
	ds_read_b128 v[162:165], v215
	ds_read_b128 v[166:169], v215 offset:1024
	ds_read_b128 v[170:173], v215 offset:2048
	ds_read_b128 v[174:177], v215 offset:3072
	ds_read_b128 v[194:197], v215 offset:4096
	ds_read_b128 v[200:203], v215 offset:5120
	ds_read_b128 v[204:207], v215 offset:6144
	ds_read_b128 v[208:211], v215 offset:7168
	global_load_lds_dwordx4 v[216:217], off
	v_lshl_add_u64 v[216:217], s[44:45], 0, v[198:199]
	s_add_i32 m0, s43, 0xe000
	s_nop 0
	global_load_lds_dwordx4 v[216:217], off
	s_waitcnt vmcnt(8)
	s_waitcnt lgkmcnt(0)
	s_barrier
	s_setprio 1
	s_waitcnt lgkmcnt(0)
	v_mfma_f32_16x16x32_bf16 v[126:129], v[130:133], v[162:165], 0
	v_mfma_f32_16x16x32_bf16 v[122:125], v[138:141], v[162:165], 0
	v_mfma_f32_16x16x32_bf16 v[108:111], v[130:133], v[170:173], 0
	v_mfma_f32_16x16x32_bf16 v[104:107], v[138:141], v[170:173], 0
	v_mfma_f32_16x16x32_bf16 v[92:95], v[130:133], v[194:197], 0
	v_mfma_f32_16x16x32_bf16 v[88:91], v[138:141], v[194:197], 0
	v_mfma_f32_16x16x32_bf16 v[76:79], v[130:133], v[204:207], 0
	v_mfma_f32_16x16x32_bf16 v[72:75], v[138:141], v[204:207], 0
	v_mfma_f32_16x16x32_bf16 v[126:129], v[134:137], v[166:169], v[126:129]
	v_mfma_f32_16x16x32_bf16 v[122:125], v[142:145], v[166:169], v[122:125]
	v_mfma_f32_16x16x32_bf16 v[108:111], v[134:137], v[174:177], v[108:111]
	v_mfma_f32_16x16x32_bf16 v[104:107], v[142:145], v[174:177], v[104:107]
	v_mfma_f32_16x16x32_bf16 v[92:95], v[134:137], v[200:203], v[92:95]
	v_mfma_f32_16x16x32_bf16 v[88:91], v[142:145], v[200:203], v[88:91]
	v_mfma_f32_16x16x32_bf16 v[76:79], v[134:137], v[208:211], v[76:79]
	v_mfma_f32_16x16x32_bf16 v[72:75], v[142:145], v[208:211], v[72:75]
	s_setprio 0
	s_setprio 1
	v_mfma_f32_16x16x32_bf16 v[118:121], v[146:149], v[162:165], 0
	v_mfma_f32_16x16x32_bf16 v[114:117], v[154:157], v[162:165], 0
	v_mfma_f32_16x16x32_bf16 v[100:103], v[146:149], v[170:173], 0
	v_mfma_f32_16x16x32_bf16 v[96:99], v[154:157], v[170:173], 0
	v_mfma_f32_16x16x32_bf16 v[84:87], v[146:149], v[194:197], 0
	v_mfma_f32_16x16x32_bf16 v[80:83], v[154:157], v[194:197], 0
	v_mfma_f32_16x16x32_bf16 v[68:71], v[146:149], v[204:207], 0
	v_mfma_f32_16x16x32_bf16 v[64:67], v[154:157], v[204:207], 0
	v_mfma_f32_16x16x32_bf16 v[118:121], v[150:153], v[166:169], v[118:121]
	v_mfma_f32_16x16x32_bf16 v[114:117], v[158:161], v[166:169], v[114:117]
	v_mfma_f32_16x16x32_bf16 v[100:103], v[150:153], v[174:177], v[100:103]
	v_mfma_f32_16x16x32_bf16 v[96:99], v[158:161], v[174:177], v[96:99]
	v_mfma_f32_16x16x32_bf16 v[84:87], v[150:153], v[200:203], v[84:87]
	v_mfma_f32_16x16x32_bf16 v[80:83], v[158:161], v[200:203], v[80:83]
	v_mfma_f32_16x16x32_bf16 v[68:71], v[150:153], v[208:211], v[68:71]
	v_mfma_f32_16x16x32_bf16 v[64:67], v[158:161], v[208:211], v[64:67]
	s_setprio 0
	s_barrier
	s_add_i32 s56, s56, s58
	v_lshl_add_u64 v[216:217], s[50:51], 0, v[112:113]
	s_mov_b32 m0, s56
	ds_read_b128 v[162:165], v215 offset:16384
	ds_read_b128 v[166:169], v215 offset:17408
	ds_read_b128 v[170:173], v215 offset:18432
	ds_read_b128 v[174:177], v215 offset:19456
	ds_read_b128 v[194:197], v215 offset:20480
	ds_read_b128 v[200:203], v215 offset:21504
	ds_read_b128 v[204:207], v215 offset:22528
	ds_read_b128 v[208:211], v215 offset:23552
	global_load_lds_dwordx4 v[216:217], off
	s_add_i32 m0, s56, 0x2000
	s_add_u32 s56, s50, 0x40000
	v_lshl_add_u64 v[218:219], s[50:51], 0, v[182:183]
	s_addc_u32 s57, s51, 0
	s_add_i32 s3, s3, s58
	global_load_lds_dwordx4 v[218:219], off
	v_lshl_add_u64 v[220:221], s[56:57], 0, v[112:113]
	s_mov_b32 m0, s3
	v_lshl_add_u64 v[222:223], s[62:63], 0, v[180:181]
	global_load_lds_dwordx4 v[220:221], off
	v_lshl_add_u64 v[220:221], s[56:57], 0, v[182:183]
	s_add_i32 m0, s3, 0x2000
	s_nop 0
	global_load_lds_dwordx4 v[220:221], off
	v_lshl_add_u64 v[220:221], s[62:63], 0, v[178:179]
	s_mov_b32 m0, s43
	s_nop 0
	global_load_lds_dwordx4 v[220:221], off
	s_mov_b32 m0, s59
	s_nop 0
	global_load_lds_dwordx4 v[222:223], off
	s_waitcnt vmcnt(8)
	s_waitcnt lgkmcnt(0)
	s_barrier
	s_setprio 1
	s_waitcnt lgkmcnt(0)
	v_mfma_f32_16x16x32_bf16 v[60:63], v[130:133], v[162:165], 0
	v_mfma_f32_16x16x32_bf16 v[56:59], v[138:141], v[162:165], 0
	v_mfma_f32_16x16x32_bf16 v[44:47], v[130:133], v[170:173], 0
	v_mfma_f32_16x16x32_bf16 v[40:43], v[138:141], v[170:173], 0
	v_mfma_f32_16x16x32_bf16 v[28:31], v[130:133], v[194:197], 0
	v_mfma_f32_16x16x32_bf16 v[24:27], v[138:141], v[194:197], 0
	v_mfma_f32_16x16x32_bf16 v[12:15], v[130:133], v[204:207], 0
	v_mfma_f32_16x16x32_bf16 v[8:11], v[138:141], v[204:207], 0
	v_mfma_f32_16x16x32_bf16 v[60:63], v[134:137], v[166:169], v[60:63]
	v_mfma_f32_16x16x32_bf16 v[56:59], v[142:145], v[166:169], v[56:59]
	v_mfma_f32_16x16x32_bf16 v[44:47], v[134:137], v[174:177], v[44:47]
	v_mfma_f32_16x16x32_bf16 v[40:43], v[142:145], v[174:177], v[40:43]
	v_mfma_f32_16x16x32_bf16 v[28:31], v[134:137], v[200:203], v[28:31]
	v_mfma_f32_16x16x32_bf16 v[24:27], v[142:145], v[200:203], v[24:27]
	v_mfma_f32_16x16x32_bf16 v[12:15], v[134:137], v[208:211], v[12:15]
	v_mfma_f32_16x16x32_bf16 v[8:11], v[142:145], v[208:211], v[8:11]
	s_setprio 0
	s_setprio 1
	v_mfma_f32_16x16x32_bf16 v[52:55], v[146:149], v[162:165], 0
	v_mfma_f32_16x16x32_bf16 v[48:51], v[154:157], v[162:165], 0
	v_mfma_f32_16x16x32_bf16 v[36:39], v[146:149], v[170:173], 0
	v_mfma_f32_16x16x32_bf16 v[32:35], v[154:157], v[170:173], 0
	v_mfma_f32_16x16x32_bf16 v[20:23], v[146:149], v[194:197], 0
	v_mfma_f32_16x16x32_bf16 v[16:19], v[154:157], v[194:197], 0
	v_mfma_f32_16x16x32_bf16 v[4:7], v[146:149], v[204:207], 0
	v_mfma_f32_16x16x32_bf16 v[0:3], v[154:157], v[204:207], 0
	v_mfma_f32_16x16x32_bf16 v[52:55], v[150:153], v[166:169], v[52:55]
	v_mfma_f32_16x16x32_bf16 v[48:51], v[158:161], v[166:169], v[48:51]
	v_mfma_f32_16x16x32_bf16 v[36:39], v[150:153], v[174:177], v[36:39]
	v_mfma_f32_16x16x32_bf16 v[32:35], v[158:161], v[174:177], v[32:35]
	v_mfma_f32_16x16x32_bf16 v[20:23], v[150:153], v[200:203], v[20:23]
	v_mfma_f32_16x16x32_bf16 v[16:19], v[158:161], v[200:203], v[16:19]
	v_mfma_f32_16x16x32_bf16 v[4:7], v[150:153], v[208:211], v[4:7]
	v_mfma_f32_16x16x32_bf16 v[0:3], v[158:161], v[208:211], v[0:3]
	s_setprio 0
	s_barrier
	s_add_i32 s3, 0, 0x18000
	s_add_i32 s64, 0, 0x1c000
	v_add_u32_e32 v142, s3, v213
	v_add_u32_e32 v158, s64, v213
	ds_read_b128 v[130:133], v142
	ds_read_b128 v[134:137], v142 offset:1024
	ds_read_b128 v[138:141], v142 offset:2048
	ds_read_b128 v[142:145], v142 offset:3072
	ds_read_b128 v[146:149], v158
	ds_read_b128 v[150:153], v158 offset:1024
	ds_read_b128 v[154:157], v158 offset:2048
	ds_read_b128 v[158:161], v158 offset:3072
	s_add_u32 s56, s62, 0x40000
	s_addc_u32 s57, s63, 0
	s_mov_b32 m0, s69
	v_lshl_add_u64 v[234:235], s[56:57], 0, v[178:179]
	ds_read_b128 v[162:165], v215 offset:32768
	ds_read_b128 v[166:169], v215 offset:33792
	ds_read_b128 v[170:173], v215 offset:34816
	ds_read_b128 v[174:177], v215 offset:35840
	ds_read_b128 v[194:197], v215 offset:36864
	ds_read_b128 v[200:203], v215 offset:37888
	ds_read_b128 v[204:207], v215 offset:38912
	ds_read_b128 v[208:211], v215 offset:39936
	global_load_lds_dwordx4 v[234:235], off
	v_lshl_add_u64 v[234:235], s[56:57], 0, v[180:181]
	s_mov_b32 m0, s70
	s_nop 0
	global_load_lds_dwordx4 v[234:235], off
	s_waitcnt vmcnt(8)
	s_waitcnt lgkmcnt(0)
	s_barrier
	s_setprio 1
	s_waitcnt lgkmcnt(0)
	v_mfma_f32_16x16x32_bf16 v[126:129], v[130:133], v[162:165], v[126:129]
	v_mfma_f32_16x16x32_bf16 v[122:125], v[138:141], v[162:165], v[122:125]
	v_mfma_f32_16x16x32_bf16 v[108:111], v[130:133], v[170:173], v[108:111]
	v_mfma_f32_16x16x32_bf16 v[104:107], v[138:141], v[170:173], v[104:107]
	v_mfma_f32_16x16x32_bf16 v[92:95], v[130:133], v[194:197], v[92:95]
	v_mfma_f32_16x16x32_bf16 v[88:91], v[138:141], v[194:197], v[88:91]
	v_mfma_f32_16x16x32_bf16 v[76:79], v[130:133], v[204:207], v[76:79]
	v_mfma_f32_16x16x32_bf16 v[72:75], v[138:141], v[204:207], v[72:75]
	v_mfma_f32_16x16x32_bf16 v[126:129], v[134:137], v[166:169], v[126:129]
	v_mfma_f32_16x16x32_bf16 v[122:125], v[142:145], v[166:169], v[122:125]
	v_mfma_f32_16x16x32_bf16 v[108:111], v[134:137], v[174:177], v[108:111]
	v_mfma_f32_16x16x32_bf16 v[104:107], v[142:145], v[174:177], v[104:107]
	v_mfma_f32_16x16x32_bf16 v[92:95], v[134:137], v[200:203], v[92:95]
	v_mfma_f32_16x16x32_bf16 v[88:91], v[142:145], v[200:203], v[88:91]
	v_mfma_f32_16x16x32_bf16 v[76:79], v[134:137], v[208:211], v[76:79]
	v_mfma_f32_16x16x32_bf16 v[72:75], v[142:145], v[208:211], v[72:75]
	s_setprio 0
	s_setprio 1
	v_mfma_f32_16x16x32_bf16 v[118:121], v[146:149], v[162:165], v[118:121]
	v_mfma_f32_16x16x32_bf16 v[114:117], v[154:157], v[162:165], v[114:117]
	v_mfma_f32_16x16x32_bf16 v[100:103], v[146:149], v[170:173], v[100:103]
	v_mfma_f32_16x16x32_bf16 v[96:99], v[154:157], v[170:173], v[96:99]
	v_mfma_f32_16x16x32_bf16 v[84:87], v[146:149], v[194:197], v[84:87]
	v_mfma_f32_16x16x32_bf16 v[80:83], v[154:157], v[194:197], v[80:83]
	v_mfma_f32_16x16x32_bf16 v[68:71], v[146:149], v[204:207], v[68:71]
	v_mfma_f32_16x16x32_bf16 v[64:67], v[154:157], v[204:207], v[64:67]
	v_mfma_f32_16x16x32_bf16 v[118:121], v[150:153], v[166:169], v[118:121]
	v_mfma_f32_16x16x32_bf16 v[114:117], v[158:161], v[166:169], v[114:117]
	v_mfma_f32_16x16x32_bf16 v[100:103], v[150:153], v[174:177], v[100:103]
	v_mfma_f32_16x16x32_bf16 v[96:99], v[158:161], v[174:177], v[96:99]
	v_mfma_f32_16x16x32_bf16 v[84:87], v[150:153], v[200:203], v[84:87]
	v_mfma_f32_16x16x32_bf16 v[80:83], v[158:161], v[200:203], v[80:83]
	v_mfma_f32_16x16x32_bf16 v[68:71], v[150:153], v[208:211], v[68:71]
	v_mfma_f32_16x16x32_bf16 v[64:67], v[158:161], v[208:211], v[64:67]
	s_setprio 0
	s_barrier
	s_add_i32 s3, s3, s58
	v_lshl_add_u64 v[216:217], v[216:217], 0, s[60:61]
	s_mov_b32 m0, s3
	ds_read_b128 v[162:165], v215 offset:49152
	ds_read_b128 v[166:169], v215 offset:50176
	ds_read_b128 v[170:173], v215 offset:51200
	ds_read_b128 v[174:177], v215 offset:52224
	ds_read_b128 v[194:197], v215 offset:53248
	ds_read_b128 v[200:203], v215 offset:54272
	ds_read_b128 v[204:207], v215 offset:55296
	ds_read_b128 v[208:211], v215 offset:56320
	global_load_lds_dwordx4 v[216:217], off
	s_add_i32 m0, s3, 0x2000
	s_add_u32 s50, s50, 0x40080
	v_lshl_add_u64 v[216:217], v[218:219], 0, s[60:61]
	s_addc_u32 s51, s51, 0
	s_add_i32 s3, s64, s58
	global_load_lds_dwordx4 v[216:217], off
	v_lshl_add_u64 v[216:217], s[50:51], 0, v[112:113]
	s_mov_b32 m0, s3
	s_nop 0
	global_load_lds_dwordx4 v[216:217], off
	v_lshl_add_u64 v[216:217], s[50:51], 0, v[182:183]
	s_add_i32 m0, s3, 0x2000
	s_nop 0
	global_load_lds_dwordx4 v[216:217], off
	v_lshl_add_u64 v[216:217], v[220:221], 0, s[60:61]
	s_mov_b32 m0, s72
	s_nop 0
	global_load_lds_dwordx4 v[216:217], off
	v_lshl_add_u64 v[216:217], v[222:223], 0, s[60:61]
	s_mov_b32 m0, s73
	s_nop 0
	global_load_lds_dwordx4 v[216:217], off
	s_waitcnt vmcnt(8)
	s_waitcnt lgkmcnt(0)
	s_barrier
	s_setprio 1
	s_waitcnt lgkmcnt(0)
	v_mfma_f32_16x16x32_bf16 v[60:63], v[130:133], v[162:165], v[60:63]
	v_mfma_f32_16x16x32_bf16 v[56:59], v[138:141], v[162:165], v[56:59]
	v_mfma_f32_16x16x32_bf16 v[44:47], v[130:133], v[170:173], v[44:47]
	v_mfma_f32_16x16x32_bf16 v[40:43], v[138:141], v[170:173], v[40:43]
	v_mfma_f32_16x16x32_bf16 v[28:31], v[130:133], v[194:197], v[28:31]
	v_mfma_f32_16x16x32_bf16 v[24:27], v[138:141], v[194:197], v[24:27]
	v_mfma_f32_16x16x32_bf16 v[12:15], v[130:133], v[204:207], v[12:15]
	v_mfma_f32_16x16x32_bf16 v[8:11], v[138:141], v[204:207], v[8:11]
	v_mfma_f32_16x16x32_bf16 v[60:63], v[134:137], v[166:169], v[60:63]
	v_mfma_f32_16x16x32_bf16 v[56:59], v[142:145], v[166:169], v[56:59]
	v_mfma_f32_16x16x32_bf16 v[44:47], v[134:137], v[174:177], v[44:47]
	v_mfma_f32_16x16x32_bf16 v[40:43], v[142:145], v[174:177], v[40:43]
	v_mfma_f32_16x16x32_bf16 v[28:31], v[134:137], v[200:203], v[28:31]
	v_mfma_f32_16x16x32_bf16 v[24:27], v[142:145], v[200:203], v[24:27]
	v_mfma_f32_16x16x32_bf16 v[12:15], v[134:137], v[208:211], v[12:15]
	v_mfma_f32_16x16x32_bf16 v[8:11], v[142:145], v[208:211], v[8:11]
	s_setprio 0
	s_setprio 1
	v_mfma_f32_16x16x32_bf16 v[52:55], v[146:149], v[162:165], v[52:55]
	v_mfma_f32_16x16x32_bf16 v[48:51], v[154:157], v[162:165], v[48:51]
	v_mfma_f32_16x16x32_bf16 v[36:39], v[146:149], v[170:173], v[36:39]
	v_mfma_f32_16x16x32_bf16 v[32:35], v[154:157], v[170:173], v[32:35]
	v_mfma_f32_16x16x32_bf16 v[20:23], v[146:149], v[194:197], v[20:23]
	v_mfma_f32_16x16x32_bf16 v[16:19], v[154:157], v[194:197], v[16:19]
	v_mfma_f32_16x16x32_bf16 v[4:7], v[146:149], v[204:207], v[4:7]
	v_mfma_f32_16x16x32_bf16 v[0:3], v[154:157], v[204:207], v[0:3]
	v_mfma_f32_16x16x32_bf16 v[52:55], v[150:153], v[166:169], v[52:55]
	v_mfma_f32_16x16x32_bf16 v[48:51], v[158:161], v[166:169], v[48:51]
	v_mfma_f32_16x16x32_bf16 v[36:39], v[150:153], v[174:177], v[36:39]
	v_mfma_f32_16x16x32_bf16 v[32:35], v[158:161], v[174:177], v[32:35]
	v_mfma_f32_16x16x32_bf16 v[20:23], v[150:153], v[200:203], v[20:23]
	v_mfma_f32_16x16x32_bf16 v[16:19], v[158:161], v[200:203], v[16:19]
	v_mfma_f32_16x16x32_bf16 v[4:7], v[150:153], v[208:211], v[4:7]
	v_mfma_f32_16x16x32_bf16 v[0:3], v[158:161], v[208:211], v[0:3]
	s_setprio 0
	s_barrier
	s_add_i32 s85, s85, 2
	s_add_u32 s44, s44, 0x100
	s_addc_u32 s45, s45, 0
	s_add_u32 s41, s41, 0x100
	s_addc_u32 s84, s84, 0
	s_cmp_gt_u32 s85, 13
	s_cbranch_scc0 .LBB0_1386
	s_branch .Lpeel_after_7
	.p2alignl 6, 3212836864

.LBB0_1470:
	s_ashr_i32 s17, s16, 31
	s_lshl_b64 s[18:19], s[16:17], 19
	s_add_u32 s18, s25, s18
	s_addc_u32 s19, s29, s19
	s_and_b64 s[20:21], s[4:5], exec
	s_cselect_b32 s17, s19, s23
	s_cselect_b32 s50, s18, s22
	s_ashr_i32 s15, s14, 31
	s_lshl_b64 s[20:21], s[14:15], 19
	s_add_u32 s20, s36, s20
	s_addc_u32 s21, s37, s21
	s_and_b64 s[34:35], s[4:5], exec
	s_cselect_b32 s15, s21, s31
	s_cselect_b32 s51, s20, s30
	s_add_u32 s22, s22, 0x40080
	s_addc_u32 s23, s23, 0
	s_add_u32 s55, s30, 0x100
	s_addc_u32 s58, s31, 0
	s_mov_b32 s59, -2
	s_add_u32 s3, s22, 0xfffc0080
	s_addc_u32 s30, s23, -1
	s_add_i32 s56, 0, 0x10000
	s_cmp_eq_u32 s59, 12
	s_cselect_b32 s35, s17, s30
	s_cselect_b32 s34, s50, s3
	s_cselect_b32 s31, s15, s58
	s_cselect_b32 s30, s51, s55
	s_add_i32 s3, 0, 0x14000
	v_add_u32_e32 v122, s56, v204
	v_add_u32_e32 v170, s3, v204
	ds_read_b128 v[76:79], v122
	ds_read_b128 v[80:83], v122 offset:1024
	ds_read_b128 v[118:121], v122 offset:2048
	ds_read_b128 v[122:125], v122 offset:3072
	ds_read_b128 v[146:149], v170
	ds_read_b128 v[150:153], v170 offset:1024
	ds_read_b128 v[166:169], v170 offset:2048
	ds_read_b128 v[170:173], v170 offset:3072
	v_lshl_add_u64 v[220:221], s[22:23], 0, v[162:163]
	s_add_i32 m0, s40, 0xc000
	ds_read_b128 v[174:177], v206
	ds_read_b128 v[178:181], v206 offset:1024
	ds_read_b128 v[182:185], v206 offset:2048
	ds_read_b128 v[194:197], v206 offset:3072
	ds_read_b128 v[198:201], v206 offset:4096
	ds_read_b128 v[208:211], v206 offset:5120
	ds_read_b128 v[212:215], v206 offset:6144
	ds_read_b128 v[216:219], v206 offset:7168
	global_load_lds_dwordx4 v[220:221], off
	v_lshl_add_u64 v[220:221], s[22:23], 0, v[164:165]
	s_add_i32 m0, s40, 0xe000
	s_nop 0
	global_load_lds_dwordx4 v[220:221], off
	s_waitcnt vmcnt(8)
	s_waitcnt lgkmcnt(0)
	s_barrier
	s_setprio 1
	s_waitcnt lgkmcnt(0)
	v_mfma_f32_16x16x32_bf16 v[142:145], v[76:79], v[174:177], 0
	v_mfma_f32_16x16x32_bf16 v[134:137], v[118:121], v[174:177], 0
	v_mfma_f32_16x16x32_bf16 v[126:129], v[76:79], v[182:185], 0
	v_mfma_f32_16x16x32_bf16 v[108:111], v[118:121], v[182:185], 0
	v_mfma_f32_16x16x32_bf16 v[100:103], v[76:79], v[198:201], 0
	v_mfma_f32_16x16x32_bf16 v[92:95], v[118:121], v[198:201], 0
	v_mfma_f32_16x16x32_bf16 v[84:87], v[76:79], v[212:215], 0
	v_mfma_f32_16x16x32_bf16 v[68:71], v[118:121], v[212:215], 0
	v_mfma_f32_16x16x32_bf16 v[142:145], v[80:83], v[178:181], v[142:145]
	v_mfma_f32_16x16x32_bf16 v[134:137], v[122:125], v[178:181], v[134:137]
	v_mfma_f32_16x16x32_bf16 v[126:129], v[80:83], v[194:197], v[126:129]
	v_mfma_f32_16x16x32_bf16 v[108:111], v[122:125], v[194:197], v[108:111]
	v_mfma_f32_16x16x32_bf16 v[100:103], v[80:83], v[208:211], v[100:103]
	v_mfma_f32_16x16x32_bf16 v[92:95], v[122:125], v[208:211], v[92:95]
	v_mfma_f32_16x16x32_bf16 v[84:87], v[80:83], v[216:219], v[84:87]
	v_mfma_f32_16x16x32_bf16 v[68:71], v[122:125], v[216:219], v[68:71]
	s_setprio 0
	s_setprio 1
	v_mfma_f32_16x16x32_bf16 v[138:141], v[146:149], v[174:177], 0
	v_mfma_f32_16x16x32_bf16 v[130:133], v[166:169], v[174:177], 0
	v_mfma_f32_16x16x32_bf16 v[114:117], v[146:149], v[182:185], 0
	v_mfma_f32_16x16x32_bf16 v[104:107], v[166:169], v[182:185], 0
	v_mfma_f32_16x16x32_bf16 v[96:99], v[146:149], v[198:201], 0
	v_mfma_f32_16x16x32_bf16 v[88:91], v[166:169], v[198:201], 0
	v_mfma_f32_16x16x32_bf16 v[72:75], v[146:149], v[212:215], 0
	v_mfma_f32_16x16x32_bf16 v[64:67], v[166:169], v[212:215], 0
	v_mfma_f32_16x16x32_bf16 v[138:141], v[150:153], v[178:181], v[138:141]
	v_mfma_f32_16x16x32_bf16 v[130:133], v[170:173], v[178:181], v[130:133]
	v_mfma_f32_16x16x32_bf16 v[114:117], v[150:153], v[194:197], v[114:117]
	v_mfma_f32_16x16x32_bf16 v[104:107], v[170:173], v[194:197], v[104:107]
	v_mfma_f32_16x16x32_bf16 v[96:99], v[150:153], v[208:211], v[96:99]
	v_mfma_f32_16x16x32_bf16 v[88:91], v[170:173], v[208:211], v[88:91]
	v_mfma_f32_16x16x32_bf16 v[72:75], v[150:153], v[216:219], v[72:75]
	v_mfma_f32_16x16x32_bf16 v[64:67], v[170:173], v[216:219], v[64:67]
	s_setprio 0
	s_barrier
	s_add_i32 s56, s56, s39
	v_lshl_add_u64 v[220:221], s[30:31], 0, v[112:113]
	s_mov_b32 m0, s56
	ds_read_b128 v[174:177], v206 offset:16384
	ds_read_b128 v[178:181], v206 offset:17408
	ds_read_b128 v[182:185], v206 offset:18432
	ds_read_b128 v[194:197], v206 offset:19456
	ds_read_b128 v[198:201], v206 offset:20480
	ds_read_b128 v[208:211], v206 offset:21504
	ds_read_b128 v[212:215], v206 offset:22528
	ds_read_b128 v[216:219], v206 offset:23552
	global_load_lds_dwordx4 v[220:221], off
	s_add_i32 m0, s56, 0x2000
	s_add_u32 s56, s30, 0x40000
	v_lshl_add_u64 v[222:223], s[30:31], 0, v[154:155]
	s_addc_u32 s57, s31, 0
	s_add_i32 s3, s3, s39
	global_load_lds_dwordx4 v[222:223], off
	v_lshl_add_u64 v[234:235], s[56:57], 0, v[112:113]
	s_mov_b32 m0, s3
	v_lshl_add_u64 v[236:237], s[34:35], 0, v[156:157]
	global_load_lds_dwordx4 v[234:235], off
	v_lshl_add_u64 v[234:235], s[56:57], 0, v[154:155]
	s_add_i32 m0, s3, 0x2000
	s_nop 0
	global_load_lds_dwordx4 v[234:235], off
	v_lshl_add_u64 v[234:235], s[34:35], 0, v[158:159]
	s_mov_b32 m0, s40
	s_nop 0
	global_load_lds_dwordx4 v[234:235], off
	s_mov_b32 m0, s41
	s_nop 0
	global_load_lds_dwordx4 v[236:237], off
	s_waitcnt vmcnt(8)
	s_waitcnt lgkmcnt(0)
	s_barrier
	s_setprio 1
	s_waitcnt lgkmcnt(0)
	v_mfma_f32_16x16x32_bf16 v[60:63], v[76:79], v[174:177], 0
	v_mfma_f32_16x16x32_bf16 v[52:55], v[118:121], v[174:177], 0
	v_mfma_f32_16x16x32_bf16 v[44:47], v[76:79], v[182:185], 0
	v_mfma_f32_16x16x32_bf16 v[36:39], v[118:121], v[182:185], 0
	v_mfma_f32_16x16x32_bf16 v[28:31], v[76:79], v[198:201], 0
	v_mfma_f32_16x16x32_bf16 v[20:23], v[118:121], v[198:201], 0
	v_mfma_f32_16x16x32_bf16 v[12:15], v[76:79], v[212:215], 0
	v_mfma_f32_16x16x32_bf16 v[4:7], v[118:121], v[212:215], 0
	v_mfma_f32_16x16x32_bf16 v[60:63], v[80:83], v[178:181], v[60:63]
	v_mfma_f32_16x16x32_bf16 v[52:55], v[122:125], v[178:181], v[52:55]
	v_mfma_f32_16x16x32_bf16 v[44:47], v[80:83], v[194:197], v[44:47]
	v_mfma_f32_16x16x32_bf16 v[36:39], v[122:125], v[194:197], v[36:39]
	v_mfma_f32_16x16x32_bf16 v[28:31], v[80:83], v[208:211], v[28:31]
	v_mfma_f32_16x16x32_bf16 v[20:23], v[122:125], v[208:211], v[20:23]
	v_mfma_f32_16x16x32_bf16 v[12:15], v[80:83], v[216:219], v[12:15]
	v_mfma_f32_16x16x32_bf16 v[4:7], v[122:125], v[216:219], v[4:7]
	s_setprio 0
	s_setprio 1
	v_mfma_f32_16x16x32_bf16 v[56:59], v[146:149], v[174:177], 0
	v_mfma_f32_16x16x32_bf16 v[48:51], v[166:169], v[174:177], 0
	v_mfma_f32_16x16x32_bf16 v[40:43], v[146:149], v[182:185], 0
	v_mfma_f32_16x16x32_bf16 v[32:35], v[166:169], v[182:185], 0
	v_mfma_f32_16x16x32_bf16 v[24:27], v[146:149], v[198:201], 0
	v_mfma_f32_16x16x32_bf16 v[16:19], v[166:169], v[198:201], 0
	v_mfma_f32_16x16x32_bf16 v[8:11], v[146:149], v[212:215], 0
	v_mfma_f32_16x16x32_bf16 v[0:3], v[166:169], v[212:215], 0
	v_mfma_f32_16x16x32_bf16 v[56:59], v[150:153], v[178:181], v[56:59]
	v_mfma_f32_16x16x32_bf16 v[48:51], v[170:173], v[178:181], v[48:51]
	v_mfma_f32_16x16x32_bf16 v[40:43], v[150:153], v[194:197], v[40:43]
	v_mfma_f32_16x16x32_bf16 v[32:35], v[170:173], v[194:197], v[32:35]
	v_mfma_f32_16x16x32_bf16 v[24:27], v[150:153], v[208:211], v[24:27]
	v_mfma_f32_16x16x32_bf16 v[16:19], v[170:173], v[208:211], v[16:19]
	v_mfma_f32_16x16x32_bf16 v[8:11], v[150:153], v[216:219], v[8:11]
	v_mfma_f32_16x16x32_bf16 v[0:3], v[170:173], v[216:219], v[0:3]
	s_setprio 0
	s_barrier
	s_add_i32 s3, 0, 0x18000
	s_add_i32 s56, 0, 0x1c000
	v_add_u32_e32 v122, s3, v204
	v_add_u32_e32 v170, s56, v204
	ds_read_b128 v[76:79], v122
	ds_read_b128 v[80:83], v122 offset:1024
	ds_read_b128 v[118:121], v122 offset:2048
	ds_read_b128 v[122:125], v122 offset:3072
	ds_read_b128 v[146:149], v170
	ds_read_b128 v[150:153], v170 offset:1024
	ds_read_b128 v[166:169], v170 offset:2048
	ds_read_b128 v[170:173], v170 offset:3072
	s_add_u32 s34, s34, 0x40000
	s_addc_u32 s35, s35, 0
	s_mov_b32 m0, s42
	v_lshl_add_u64 v[238:239], s[34:35], 0, v[158:159]
	ds_read_b128 v[174:177], v206 offset:32768
	ds_read_b128 v[178:181], v206 offset:33792
	ds_read_b128 v[182:185], v206 offset:34816
	ds_read_b128 v[194:197], v206 offset:35840
	ds_read_b128 v[198:201], v206 offset:36864
	ds_read_b128 v[208:211], v206 offset:37888
	ds_read_b128 v[212:215], v206 offset:38912
	ds_read_b128 v[216:219], v206 offset:39936
	global_load_lds_dwordx4 v[238:239], off
	v_lshl_add_u64 v[238:239], s[34:35], 0, v[156:157]
	s_mov_b32 m0, s43
	s_nop 0
	global_load_lds_dwordx4 v[238:239], off
	s_waitcnt vmcnt(8)
	s_waitcnt lgkmcnt(0)
	s_barrier
	s_setprio 1
	s_waitcnt lgkmcnt(0)
	v_mfma_f32_16x16x32_bf16 v[142:145], v[76:79], v[174:177], v[142:145]
	v_mfma_f32_16x16x32_bf16 v[134:137], v[118:121], v[174:177], v[134:137]
	v_mfma_f32_16x16x32_bf16 v[126:129], v[76:79], v[182:185], v[126:129]
	v_mfma_f32_16x16x32_bf16 v[108:111], v[118:121], v[182:185], v[108:111]
	v_mfma_f32_16x16x32_bf16 v[100:103], v[76:79], v[198:201], v[100:103]
	v_mfma_f32_16x16x32_bf16 v[92:95], v[118:121], v[198:201], v[92:95]
	v_mfma_f32_16x16x32_bf16 v[84:87], v[76:79], v[212:215], v[84:87]
	v_mfma_f32_16x16x32_bf16 v[68:71], v[118:121], v[212:215], v[68:71]
	v_mfma_f32_16x16x32_bf16 v[142:145], v[80:83], v[178:181], v[142:145]
	v_mfma_f32_16x16x32_bf16 v[134:137], v[122:125], v[178:181], v[134:137]
	v_mfma_f32_16x16x32_bf16 v[126:129], v[80:83], v[194:197], v[126:129]
	v_mfma_f32_16x16x32_bf16 v[108:111], v[122:125], v[194:197], v[108:111]
	v_mfma_f32_16x16x32_bf16 v[100:103], v[80:83], v[208:211], v[100:103]
	v_mfma_f32_16x16x32_bf16 v[92:95], v[122:125], v[208:211], v[92:95]
	v_mfma_f32_16x16x32_bf16 v[84:87], v[80:83], v[216:219], v[84:87]
	v_mfma_f32_16x16x32_bf16 v[68:71], v[122:125], v[216:219], v[68:71]
	s_setprio 0
	s_setprio 1
	v_mfma_f32_16x16x32_bf16 v[138:141], v[146:149], v[174:177], v[138:141]
	v_mfma_f32_16x16x32_bf16 v[130:133], v[166:169], v[174:177], v[130:133]
	v_mfma_f32_16x16x32_bf16 v[114:117], v[146:149], v[182:185], v[114:117]
	v_mfma_f32_16x16x32_bf16 v[104:107], v[166:169], v[182:185], v[104:107]
	v_mfma_f32_16x16x32_bf16 v[96:99], v[146:149], v[198:201], v[96:99]
	v_mfma_f32_16x16x32_bf16 v[88:91], v[166:169], v[198:201], v[88:91]
	v_mfma_f32_16x16x32_bf16 v[72:75], v[146:149], v[212:215], v[72:75]
	v_mfma_f32_16x16x32_bf16 v[64:67], v[166:169], v[212:215], v[64:67]
	v_mfma_f32_16x16x32_bf16 v[138:141], v[150:153], v[178:181], v[138:141]
	v_mfma_f32_16x16x32_bf16 v[130:133], v[170:173], v[178:181], v[130:133]
	v_mfma_f32_16x16x32_bf16 v[114:117], v[150:153], v[194:197], v[114:117]
	v_mfma_f32_16x16x32_bf16 v[104:107], v[170:173], v[194:197], v[104:107]
	v_mfma_f32_16x16x32_bf16 v[96:99], v[150:153], v[208:211], v[96:99]
	v_mfma_f32_16x16x32_bf16 v[88:91], v[170:173], v[208:211], v[88:91]
	v_mfma_f32_16x16x32_bf16 v[72:75], v[150:153], v[216:219], v[72:75]
	v_mfma_f32_16x16x32_bf16 v[64:67], v[170:173], v[216:219], v[64:67]
	s_setprio 0
	s_barrier
	s_add_i32 s3, s3, s39
	v_lshl_add_u64 v[220:221], v[220:221], 0, s[60:61]
	s_mov_b32 m0, s3
	ds_read_b128 v[174:177], v206 offset:49152
	ds_read_b128 v[178:181], v206 offset:50176
	ds_read_b128 v[182:185], v206 offset:51200
	ds_read_b128 v[194:197], v206 offset:52224
	ds_read_b128 v[198:201], v206 offset:53248
	ds_read_b128 v[208:211], v206 offset:54272
	ds_read_b128 v[212:215], v206 offset:55296
	ds_read_b128 v[216:219], v206 offset:56320
	global_load_lds_dwordx4 v[220:221], off
	s_add_i32 m0, s3, 0x2000
	s_add_u32 s30, s30, 0x40080
	v_lshl_add_u64 v[220:221], v[222:223], 0, s[60:61]
	s_addc_u32 s31, s31, 0
	s_add_i32 s3, s56, s39
	global_load_lds_dwordx4 v[220:221], off
	v_lshl_add_u64 v[220:221], s[30:31], 0, v[112:113]
	s_mov_b32 m0, s3
	s_nop 0
	global_load_lds_dwordx4 v[220:221], off
	v_lshl_add_u64 v[220:221], s[30:31], 0, v[154:155]
	s_add_i32 m0, s3, 0x2000
	s_nop 0
	global_load_lds_dwordx4 v[220:221], off
	v_lshl_add_u64 v[220:221], v[234:235], 0, s[60:61]
	s_mov_b32 m0, s44
	s_nop 0
	global_load_lds_dwordx4 v[220:221], off
	v_lshl_add_u64 v[220:221], v[236:237], 0, s[60:61]
	s_mov_b32 m0, s45
	s_nop 0
	global_load_lds_dwordx4 v[220:221], off
	s_waitcnt vmcnt(8)
	s_waitcnt lgkmcnt(0)
	s_barrier
	s_setprio 1
	s_waitcnt lgkmcnt(0)
	v_mfma_f32_16x16x32_bf16 v[60:63], v[76:79], v[174:177], v[60:63]
	v_mfma_f32_16x16x32_bf16 v[52:55], v[118:121], v[174:177], v[52:55]
	v_mfma_f32_16x16x32_bf16 v[44:47], v[76:79], v[182:185], v[44:47]
	v_mfma_f32_16x16x32_bf16 v[36:39], v[118:121], v[182:185], v[36:39]
	v_mfma_f32_16x16x32_bf16 v[28:31], v[76:79], v[198:201], v[28:31]
	v_mfma_f32_16x16x32_bf16 v[20:23], v[118:121], v[198:201], v[20:23]
	v_mfma_f32_16x16x32_bf16 v[12:15], v[76:79], v[212:215], v[12:15]
	v_mfma_f32_16x16x32_bf16 v[4:7], v[118:121], v[212:215], v[4:7]
	v_mfma_f32_16x16x32_bf16 v[60:63], v[80:83], v[178:181], v[60:63]
	v_mfma_f32_16x16x32_bf16 v[52:55], v[122:125], v[178:181], v[52:55]
	v_mfma_f32_16x16x32_bf16 v[44:47], v[80:83], v[194:197], v[44:47]
	v_mfma_f32_16x16x32_bf16 v[36:39], v[122:125], v[194:197], v[36:39]
	v_mfma_f32_16x16x32_bf16 v[28:31], v[80:83], v[208:211], v[28:31]
	v_mfma_f32_16x16x32_bf16 v[20:23], v[122:125], v[208:211], v[20:23]
	v_mfma_f32_16x16x32_bf16 v[12:15], v[80:83], v[216:219], v[12:15]
	v_mfma_f32_16x16x32_bf16 v[4:7], v[122:125], v[216:219], v[4:7]
	s_setprio 0
	s_setprio 1
	v_mfma_f32_16x16x32_bf16 v[56:59], v[146:149], v[174:177], v[56:59]
	v_mfma_f32_16x16x32_bf16 v[48:51], v[166:169], v[174:177], v[48:51]
	v_mfma_f32_16x16x32_bf16 v[40:43], v[146:149], v[182:185], v[40:43]
	v_mfma_f32_16x16x32_bf16 v[32:35], v[166:169], v[182:185], v[32:35]
	v_mfma_f32_16x16x32_bf16 v[24:27], v[146:149], v[198:201], v[24:27]
	v_mfma_f32_16x16x32_bf16 v[16:19], v[166:169], v[198:201], v[16:19]
	v_mfma_f32_16x16x32_bf16 v[8:11], v[146:149], v[212:215], v[8:11]
	v_mfma_f32_16x16x32_bf16 v[0:3], v[166:169], v[212:215], v[0:3]
	v_mfma_f32_16x16x32_bf16 v[56:59], v[150:153], v[178:181], v[56:59]
	v_mfma_f32_16x16x32_bf16 v[48:51], v[170:173], v[178:181], v[48:51]
	v_mfma_f32_16x16x32_bf16 v[40:43], v[150:153], v[194:197], v[40:43]
	v_mfma_f32_16x16x32_bf16 v[32:35], v[170:173], v[194:197], v[32:35]
	v_mfma_f32_16x16x32_bf16 v[24:27], v[150:153], v[208:211], v[24:27]
	v_mfma_f32_16x16x32_bf16 v[16:19], v[170:173], v[208:211], v[16:19]
	v_mfma_f32_16x16x32_bf16 v[8:11], v[150:153], v[216:219], v[8:11]
	v_mfma_f32_16x16x32_bf16 v[0:3], v[170:173], v[216:219], v[0:3]
	s_setprio 0
	s_barrier
	s_add_i32 s59, s59, 2
	s_add_u32 s22, s22, 0x100
	s_addc_u32 s23, s23, 0
	s_add_u32 s55, s55, 0x100
	s_addc_u32 s58, s58, 0
	s_cmp_gt_u32 s59, 13
	s_cbranch_scc0 .LBB0_1471
	s_branch .Lpeel_after_8
	.p2alignl 6, 3212836864

.LBB0_1556:
	s_add_u32 s73, s40, 0x100
	s_addc_u32 s82, s41, 0
	s_mov_b32 s83, -2
	s_waitcnt lgkmcnt(0)
	s_add_u32 s6, s36, 0x100
	s_addc_u32 s7, s37, 0
	s_add_i32 s3, 0, 0x10000
	s_cmp_eq_u32 s83, 40
	s_cselect_b32 s41, s31, s7
	s_cselect_b32 s40, s30, s6
	s_cselect_b32 s39, s35, s82
	s_cselect_b32 s38, s34, s73
	s_add_i32 s56, 0, 0x14000
	v_add_u32_e32 v142, s3, v248
	v_add_u32_e32 v158, s56, v248
	ds_read_b128 v[130:133], v142
	ds_read_b128 v[134:137], v142 offset:1024
	ds_read_b128 v[138:141], v142 offset:2048
	ds_read_b128 v[142:145], v142 offset:3072
	ds_read_b128 v[146:149], v158
	ds_read_b128 v[150:153], v158 offset:1024
	ds_read_b128 v[154:157], v158 offset:2048
	ds_read_b128 v[158:161], v158 offset:3072
	v_lshl_add_u64 v[212:213], s[36:37], 0, v[204:205]
	s_add_i32 m0, s50, 0xc000
	ds_read_b128 v[162:165], v250
	ds_read_b128 v[166:169], v250 offset:1024
	ds_read_b128 v[170:173], v250 offset:2048
	ds_read_b128 v[174:177], v250 offset:3072
	ds_read_b128 v[178:181], v250 offset:4096
	ds_read_b128 v[182:185], v250 offset:5120
	ds_read_b128 v[194:197], v250 offset:6144
	ds_read_b128 v[208:211], v250 offset:7168
	global_load_lds_dwordx4 v[212:213], off
	v_lshl_add_u64 v[212:213], s[36:37], 0, v[206:207]
	s_add_i32 m0, s50, 0xe000
	s_nop 0
	global_load_lds_dwordx4 v[212:213], off
	s_waitcnt vmcnt(8)
	s_waitcnt lgkmcnt(0)
	s_barrier
	s_setprio 1
	s_waitcnt lgkmcnt(0)
	v_mfma_f32_16x16x32_bf16 v[126:129], v[130:133], v[162:165], 0
	v_mfma_f32_16x16x32_bf16 v[122:125], v[138:141], v[162:165], 0
	v_mfma_f32_16x16x32_bf16 v[108:111], v[130:133], v[170:173], 0
	v_mfma_f32_16x16x32_bf16 v[104:107], v[138:141], v[170:173], 0
	v_mfma_f32_16x16x32_bf16 v[92:95], v[130:133], v[178:181], 0
	v_mfma_f32_16x16x32_bf16 v[88:91], v[138:141], v[178:181], 0
	v_mfma_f32_16x16x32_bf16 v[76:79], v[130:133], v[194:197], 0
	v_mfma_f32_16x16x32_bf16 v[72:75], v[138:141], v[194:197], 0
	v_mfma_f32_16x16x32_bf16 v[126:129], v[134:137], v[166:169], v[126:129]
	v_mfma_f32_16x16x32_bf16 v[122:125], v[142:145], v[166:169], v[122:125]
	v_mfma_f32_16x16x32_bf16 v[108:111], v[134:137], v[174:177], v[108:111]
	v_mfma_f32_16x16x32_bf16 v[104:107], v[142:145], v[174:177], v[104:107]
	v_mfma_f32_16x16x32_bf16 v[92:95], v[134:137], v[182:185], v[92:95]
	v_mfma_f32_16x16x32_bf16 v[88:91], v[142:145], v[182:185], v[88:91]
	v_mfma_f32_16x16x32_bf16 v[76:79], v[134:137], v[208:211], v[76:79]
	v_mfma_f32_16x16x32_bf16 v[72:75], v[142:145], v[208:211], v[72:75]
	s_setprio 0
	s_setprio 1
	v_mfma_f32_16x16x32_bf16 v[118:121], v[146:149], v[162:165], 0
	v_mfma_f32_16x16x32_bf16 v[114:117], v[154:157], v[162:165], 0
	v_mfma_f32_16x16x32_bf16 v[100:103], v[146:149], v[170:173], 0
	v_mfma_f32_16x16x32_bf16 v[96:99], v[154:157], v[170:173], 0
	v_mfma_f32_16x16x32_bf16 v[84:87], v[146:149], v[178:181], 0
	v_mfma_f32_16x16x32_bf16 v[80:83], v[154:157], v[178:181], 0
	v_mfma_f32_16x16x32_bf16 v[68:71], v[146:149], v[194:197], 0
	v_mfma_f32_16x16x32_bf16 v[64:67], v[154:157], v[194:197], 0
	v_mfma_f32_16x16x32_bf16 v[118:121], v[150:153], v[166:169], v[118:121]
	v_mfma_f32_16x16x32_bf16 v[114:117], v[158:161], v[166:169], v[114:117]
	v_mfma_f32_16x16x32_bf16 v[100:103], v[150:153], v[174:177], v[100:103]
	v_mfma_f32_16x16x32_bf16 v[96:99], v[158:161], v[174:177], v[96:99]
	v_mfma_f32_16x16x32_bf16 v[84:87], v[150:153], v[182:185], v[84:87]
	v_mfma_f32_16x16x32_bf16 v[80:83], v[158:161], v[182:185], v[80:83]
	v_mfma_f32_16x16x32_bf16 v[68:71], v[150:153], v[208:211], v[68:71]
	v_mfma_f32_16x16x32_bf16 v[64:67], v[158:161], v[208:211], v[64:67]
	s_setprio 0
	s_barrier
	s_add_i32 s3, s3, s42
	v_lshl_add_u64 v[212:213], s[38:39], 0, v[112:113]
	s_mov_b32 m0, s3
	ds_read_b128 v[162:165], v250 offset:16384
	ds_read_b128 v[166:169], v250 offset:17408
	ds_read_b128 v[170:173], v250 offset:18432
	ds_read_b128 v[174:177], v250 offset:19456
	ds_read_b128 v[178:181], v250 offset:20480
	ds_read_b128 v[182:185], v250 offset:21504
	ds_read_b128 v[194:197], v250 offset:22528
	ds_read_b128 v[208:211], v250 offset:23552
	global_load_lds_dwordx4 v[212:213], off
	s_add_i32 m0, s3, 0x2000
	s_add_u32 s36, s38, 0xb0000
	v_lshl_add_u64 v[214:215], s[38:39], 0, v[202:203]
	s_addc_u32 s37, s39, 0
	s_add_i32 s3, s56, s42
	global_load_lds_dwordx4 v[214:215], off
	v_lshl_add_u64 v[216:217], s[36:37], 0, v[112:113]
	s_mov_b32 m0, s3
	v_lshl_add_u64 v[218:219], s[40:41], 0, v[200:201]
	global_load_lds_dwordx4 v[216:217], off
	v_lshl_add_u64 v[216:217], s[36:37], 0, v[202:203]
	s_add_i32 m0, s3, 0x2000
	s_nop 0
	global_load_lds_dwordx4 v[216:217], off
	v_lshl_add_u64 v[216:217], s[40:41], 0, v[198:199]
	s_mov_b32 m0, s50
	s_nop 0
	global_load_lds_dwordx4 v[216:217], off
	s_mov_b32 m0, s51
	s_nop 0
	global_load_lds_dwordx4 v[218:219], off
	s_waitcnt vmcnt(8)
	s_waitcnt lgkmcnt(0)
	s_barrier
	s_setprio 1
	s_waitcnt lgkmcnt(0)
	v_mfma_f32_16x16x32_bf16 v[60:63], v[130:133], v[162:165], 0
	v_mfma_f32_16x16x32_bf16 v[56:59], v[138:141], v[162:165], 0
	v_mfma_f32_16x16x32_bf16 v[44:47], v[130:133], v[170:173], 0
	v_mfma_f32_16x16x32_bf16 v[40:43], v[138:141], v[170:173], 0
	v_mfma_f32_16x16x32_bf16 v[28:31], v[130:133], v[178:181], 0
	v_mfma_f32_16x16x32_bf16 v[24:27], v[138:141], v[178:181], 0
	v_mfma_f32_16x16x32_bf16 v[12:15], v[130:133], v[194:197], 0
	v_mfma_f32_16x16x32_bf16 v[8:11], v[138:141], v[194:197], 0
	v_mfma_f32_16x16x32_bf16 v[60:63], v[134:137], v[166:169], v[60:63]
	v_mfma_f32_16x16x32_bf16 v[56:59], v[142:145], v[166:169], v[56:59]
	v_mfma_f32_16x16x32_bf16 v[44:47], v[134:137], v[174:177], v[44:47]
	v_mfma_f32_16x16x32_bf16 v[40:43], v[142:145], v[174:177], v[40:43]
	v_mfma_f32_16x16x32_bf16 v[28:31], v[134:137], v[182:185], v[28:31]
	v_mfma_f32_16x16x32_bf16 v[24:27], v[142:145], v[182:185], v[24:27]
	v_mfma_f32_16x16x32_bf16 v[12:15], v[134:137], v[208:211], v[12:15]
	v_mfma_f32_16x16x32_bf16 v[8:11], v[142:145], v[208:211], v[8:11]
	s_setprio 0
	s_setprio 1
	v_mfma_f32_16x16x32_bf16 v[52:55], v[146:149], v[162:165], 0
	v_mfma_f32_16x16x32_bf16 v[48:51], v[154:157], v[162:165], 0
	v_mfma_f32_16x16x32_bf16 v[36:39], v[146:149], v[170:173], 0
	v_mfma_f32_16x16x32_bf16 v[32:35], v[154:157], v[170:173], 0
	v_mfma_f32_16x16x32_bf16 v[20:23], v[146:149], v[178:181], 0
	v_mfma_f32_16x16x32_bf16 v[16:19], v[154:157], v[178:181], 0
	v_mfma_f32_16x16x32_bf16 v[4:7], v[146:149], v[194:197], 0
	v_mfma_f32_16x16x32_bf16 v[0:3], v[154:157], v[194:197], 0
	v_mfma_f32_16x16x32_bf16 v[52:55], v[150:153], v[166:169], v[52:55]
	v_mfma_f32_16x16x32_bf16 v[48:51], v[158:161], v[166:169], v[48:51]
	v_mfma_f32_16x16x32_bf16 v[36:39], v[150:153], v[174:177], v[36:39]
	v_mfma_f32_16x16x32_bf16 v[32:35], v[158:161], v[174:177], v[32:35]
	v_mfma_f32_16x16x32_bf16 v[20:23], v[150:153], v[182:185], v[20:23]
	v_mfma_f32_16x16x32_bf16 v[16:19], v[158:161], v[182:185], v[16:19]
	v_mfma_f32_16x16x32_bf16 v[4:7], v[150:153], v[208:211], v[4:7]
	v_mfma_f32_16x16x32_bf16 v[0:3], v[158:161], v[208:211], v[0:3]
	s_setprio 0
	s_barrier
	s_add_i32 s3, 0, 0x18000
	s_add_i32 s56, 0, 0x1c000
	v_add_u32_e32 v142, s3, v248
	v_add_u32_e32 v158, s56, v248
	ds_read_b128 v[130:133], v142
	ds_read_b128 v[134:137], v142 offset:1024
	ds_read_b128 v[138:141], v142 offset:2048
	ds_read_b128 v[142:145], v142 offset:3072
	ds_read_b128 v[146:149], v158
	ds_read_b128 v[150:153], v158 offset:1024
	ds_read_b128 v[154:157], v158 offset:2048
	ds_read_b128 v[158:161], v158 offset:3072
	s_add_u32 s36, s40, 0xb0000
	s_addc_u32 s37, s41, 0
	s_mov_b32 m0, s55
	v_lshl_add_u64 v[220:221], s[36:37], 0, v[198:199]
	ds_read_b128 v[162:165], v250 offset:32768
	ds_read_b128 v[166:169], v250 offset:33792
	ds_read_b128 v[170:173], v250 offset:34816
	ds_read_b128 v[174:177], v250 offset:35840
	ds_read_b128 v[178:181], v250 offset:36864
	ds_read_b128 v[182:185], v250 offset:37888
	ds_read_b128 v[194:197], v250 offset:38912
	ds_read_b128 v[208:211], v250 offset:39936
	global_load_lds_dwordx4 v[220:221], off
	v_lshl_add_u64 v[220:221], s[36:37], 0, v[200:201]
	s_mov_b32 m0, s58
	s_nop 0
	global_load_lds_dwordx4 v[220:221], off
	s_waitcnt vmcnt(8)
	s_waitcnt lgkmcnt(0)
	s_barrier
	s_setprio 1
	s_waitcnt lgkmcnt(0)
	v_mfma_f32_16x16x32_bf16 v[126:129], v[130:133], v[162:165], v[126:129]
	v_mfma_f32_16x16x32_bf16 v[122:125], v[138:141], v[162:165], v[122:125]
	v_mfma_f32_16x16x32_bf16 v[108:111], v[130:133], v[170:173], v[108:111]
	v_mfma_f32_16x16x32_bf16 v[104:107], v[138:141], v[170:173], v[104:107]
	v_mfma_f32_16x16x32_bf16 v[92:95], v[130:133], v[178:181], v[92:95]
	v_mfma_f32_16x16x32_bf16 v[88:91], v[138:141], v[178:181], v[88:91]
	v_mfma_f32_16x16x32_bf16 v[76:79], v[130:133], v[194:197], v[76:79]
	v_mfma_f32_16x16x32_bf16 v[72:75], v[138:141], v[194:197], v[72:75]
	v_mfma_f32_16x16x32_bf16 v[126:129], v[134:137], v[166:169], v[126:129]
	v_mfma_f32_16x16x32_bf16 v[122:125], v[142:145], v[166:169], v[122:125]
	v_mfma_f32_16x16x32_bf16 v[108:111], v[134:137], v[174:177], v[108:111]
	v_mfma_f32_16x16x32_bf16 v[104:107], v[142:145], v[174:177], v[104:107]
	v_mfma_f32_16x16x32_bf16 v[92:95], v[134:137], v[182:185], v[92:95]
	v_mfma_f32_16x16x32_bf16 v[88:91], v[142:145], v[182:185], v[88:91]
	v_mfma_f32_16x16x32_bf16 v[76:79], v[134:137], v[208:211], v[76:79]
	v_mfma_f32_16x16x32_bf16 v[72:75], v[142:145], v[208:211], v[72:75]
	s_setprio 0
	s_setprio 1
	v_mfma_f32_16x16x32_bf16 v[118:121], v[146:149], v[162:165], v[118:121]
	v_mfma_f32_16x16x32_bf16 v[114:117], v[154:157], v[162:165], v[114:117]
	v_mfma_f32_16x16x32_bf16 v[100:103], v[146:149], v[170:173], v[100:103]
	v_mfma_f32_16x16x32_bf16 v[96:99], v[154:157], v[170:173], v[96:99]
	v_mfma_f32_16x16x32_bf16 v[84:87], v[146:149], v[178:181], v[84:87]
	v_mfma_f32_16x16x32_bf16 v[80:83], v[154:157], v[178:181], v[80:83]
	v_mfma_f32_16x16x32_bf16 v[68:71], v[146:149], v[194:197], v[68:71]
	v_mfma_f32_16x16x32_bf16 v[64:67], v[154:157], v[194:197], v[64:67]
	v_mfma_f32_16x16x32_bf16 v[118:121], v[150:153], v[166:169], v[118:121]
	v_mfma_f32_16x16x32_bf16 v[114:117], v[158:161], v[166:169], v[114:117]
	v_mfma_f32_16x16x32_bf16 v[100:103], v[150:153], v[174:177], v[100:103]
	v_mfma_f32_16x16x32_bf16 v[96:99], v[158:161], v[174:177], v[96:99]
	v_mfma_f32_16x16x32_bf16 v[84:87], v[150:153], v[182:185], v[84:87]
	v_mfma_f32_16x16x32_bf16 v[80:83], v[158:161], v[182:185], v[80:83]
	v_mfma_f32_16x16x32_bf16 v[68:71], v[150:153], v[208:211], v[68:71]
	v_mfma_f32_16x16x32_bf16 v[64:67], v[158:161], v[208:211], v[64:67]
	s_setprio 0
	s_barrier
	s_add_i32 s3, s3, s42
	v_lshl_add_u64 v[212:213], v[212:213], 0, s[60:61]
	s_mov_b32 m0, s3
	ds_read_b128 v[162:165], v250 offset:49152
	ds_read_b128 v[166:169], v250 offset:50176
	ds_read_b128 v[170:173], v250 offset:51200
	ds_read_b128 v[174:177], v250 offset:52224
	ds_read_b128 v[178:181], v250 offset:53248
	ds_read_b128 v[182:185], v250 offset:54272
	ds_read_b128 v[194:197], v250 offset:55296
	ds_read_b128 v[208:211], v250 offset:56320
	global_load_lds_dwordx4 v[212:213], off
	s_add_i32 m0, s3, 0x2000
	s_add_u32 s36, s38, 0xb0080
	v_lshl_add_u64 v[212:213], v[214:215], 0, s[60:61]
	s_addc_u32 s37, s39, 0
	s_add_i32 s3, s56, s42
	global_load_lds_dwordx4 v[212:213], off
	v_lshl_add_u64 v[212:213], s[36:37], 0, v[112:113]
	s_mov_b32 m0, s3
	s_nop 0
	global_load_lds_dwordx4 v[212:213], off
	v_lshl_add_u64 v[212:213], s[36:37], 0, v[202:203]
	s_add_i32 m0, s3, 0x2000
	s_nop 0
	global_load_lds_dwordx4 v[212:213], off
	v_lshl_add_u64 v[212:213], v[216:217], 0, s[60:61]
	s_mov_b32 m0, s62
	s_nop 0
	global_load_lds_dwordx4 v[212:213], off
	v_lshl_add_u64 v[212:213], v[218:219], 0, s[60:61]
	s_mov_b32 m0, s63
	s_nop 0
	global_load_lds_dwordx4 v[212:213], off
	s_waitcnt vmcnt(8)
	s_waitcnt lgkmcnt(0)
	s_barrier
	s_setprio 1
	s_waitcnt lgkmcnt(0)
	v_mfma_f32_16x16x32_bf16 v[60:63], v[130:133], v[162:165], v[60:63]
	v_mfma_f32_16x16x32_bf16 v[56:59], v[138:141], v[162:165], v[56:59]
	v_mfma_f32_16x16x32_bf16 v[44:47], v[130:133], v[170:173], v[44:47]
	v_mfma_f32_16x16x32_bf16 v[40:43], v[138:141], v[170:173], v[40:43]
	v_mfma_f32_16x16x32_bf16 v[28:31], v[130:133], v[178:181], v[28:31]
	v_mfma_f32_16x16x32_bf16 v[24:27], v[138:141], v[178:181], v[24:27]
	v_mfma_f32_16x16x32_bf16 v[12:15], v[130:133], v[194:197], v[12:15]
	v_mfma_f32_16x16x32_bf16 v[8:11], v[138:141], v[194:197], v[8:11]
	v_mfma_f32_16x16x32_bf16 v[60:63], v[134:137], v[166:169], v[60:63]
	v_mfma_f32_16x16x32_bf16 v[56:59], v[142:145], v[166:169], v[56:59]
	v_mfma_f32_16x16x32_bf16 v[44:47], v[134:137], v[174:177], v[44:47]
	v_mfma_f32_16x16x32_bf16 v[40:43], v[142:145], v[174:177], v[40:43]
	v_mfma_f32_16x16x32_bf16 v[28:31], v[134:137], v[182:185], v[28:31]
	v_mfma_f32_16x16x32_bf16 v[24:27], v[142:145], v[182:185], v[24:27]
	v_mfma_f32_16x16x32_bf16 v[12:15], v[134:137], v[208:211], v[12:15]
	v_mfma_f32_16x16x32_bf16 v[8:11], v[142:145], v[208:211], v[8:11]
	s_setprio 0
	s_setprio 1
	v_mfma_f32_16x16x32_bf16 v[52:55], v[146:149], v[162:165], v[52:55]
	v_mfma_f32_16x16x32_bf16 v[48:51], v[154:157], v[162:165], v[48:51]
	v_mfma_f32_16x16x32_bf16 v[36:39], v[146:149], v[170:173], v[36:39]
	v_mfma_f32_16x16x32_bf16 v[32:35], v[154:157], v[170:173], v[32:35]
	v_mfma_f32_16x16x32_bf16 v[20:23], v[146:149], v[178:181], v[20:23]
	v_mfma_f32_16x16x32_bf16 v[16:19], v[154:157], v[178:181], v[16:19]
	v_mfma_f32_16x16x32_bf16 v[4:7], v[146:149], v[194:197], v[4:7]
	v_mfma_f32_16x16x32_bf16 v[0:3], v[154:157], v[194:197], v[0:3]
	v_mfma_f32_16x16x32_bf16 v[52:55], v[150:153], v[166:169], v[52:55]
	v_mfma_f32_16x16x32_bf16 v[48:51], v[158:161], v[166:169], v[48:51]
	v_mfma_f32_16x16x32_bf16 v[36:39], v[150:153], v[174:177], v[36:39]
	v_mfma_f32_16x16x32_bf16 v[32:35], v[158:161], v[174:177], v[32:35]
	v_mfma_f32_16x16x32_bf16 v[20:23], v[150:153], v[182:185], v[20:23]
	v_mfma_f32_16x16x32_bf16 v[16:19], v[158:161], v[182:185], v[16:19]
	v_mfma_f32_16x16x32_bf16 v[4:7], v[150:153], v[208:211], v[4:7]
	v_mfma_f32_16x16x32_bf16 v[0:3], v[158:161], v[208:211], v[0:3]
	s_setprio 0
	s_barrier
	s_add_i32 s83, s83, 2
	s_add_u32 s73, s73, 0x100
	s_addc_u32 s82, s82, 0
	s_cmp_gt_u32 s83, 41
	s_mov_b64 s[36:37], s[6:7]
	s_cbranch_scc0 .LBB0_1557
	s_branch .Lpeel_after_9
	.p2alignl 6, 3212836864
